# expert lists sorted again with an in-register bitonic sort (16 keys per lane, DPP cross-lane steps) + per-unit barrier
# baseline (speedup 1.0000x reference)
; DEV int tid_l() { int t = threadIdx.x; asm volatile("" : "+v"(t)); return t; }
; DEV void sort_lists(int lane, int& myi0, int& myi1, float& myg0, float& myg1) {
; #pragma unroll
;     for (int k = 2; k <= 128; k <<= 1) {
; #pragma unroll
;       for (int j = k >> 1; j >= 1; j >>= 1) {
;         if (j == 64) {
;           const bool sw_ = myi1 < myi0;
;           const int ti = sw_ ? myi1 : myi0, tj = sw_ ? myi0 : myi1; const float tg = sw_ ? myg1 : myg0, th = sw_ ? myg0 : myg1;
;           myi0 = ti; myi1 = tj; myg0 = tg; myg1 = th;
;         } else {
;           const bool lower = (lane & j) == 0;
;           {
;             const bool up = (k == 128) ? true : ((k == 64) ? true : ((lane & k) == 0));
;             const int oi = __shfl_xor(myi0, j); const float og = __shfl_xor(myg0, j);
;             const bool take = (lower == up) ? (oi < myi0) : (oi > myi0);
;             myi0 = take ? oi : myi0; myg0 = take ? og : myg0;
;           }
;           {
;             const bool up = (k == 128) ? true : ((k == 64) ? false : ((lane & k) == 0));
;             const int oi = __shfl_xor(myi1, j); const float og = __shfl_xor(myg1, j);
;             const bool take = (lower == up) ? (oi < myi1) : (oi > myi1);
;             myi1 = take ? oi : myi1; myg1 = take ? og : myg1;
;           }
;         }
;       }
;     }
; }
; DEV void peer_gather(const Params& P, int l, int m0, const int* idxs, const float* gs) {
;   const int tid = tid_l(), lane = tid & 63, wid = tid >> 6;
;   const unsigned char* U = P.ws + WS_TAB + (size_t)l * 32 * MB;
;   const unsigned char* V = U + 16 * MB;
;   bf16_t* hn = (bf16_t*)(P.ws + WS_HN);
;   const float* gp = P.norm_ple + l * DM;
;   const int row = lane >> 4, rmap = ((row & 1) << 1) | (row >> 1);
;   u32x4 nxa = *(const u32x4*)(hn + (size_t)(m0 + wid * 16) * DM + lane * 16), nxb = *(const u32x4*)(hn + (size_t)(m0 + wid * 16) * DM + lane * 16 + 8);
;   int ni0 = idxs[(wid * 16) * 128 + lane], ni1 = idxs[(wid * 16) * 128 + 64 + lane];
;   float ng0 = gs[(wid * 16) * 128 + lane], ng1 = gs[(wid * 16) * 128 + 64 + lane];
;   sort_lists(lane, ni0, ni1, ng0, ng1);
.LBB0_313:
	s_waitcnt vmcnt(0) lgkmcnt(0)
	v_and_b32_e32 v233, 63, v176
	v_lshlrev_b32_e32 v234, 2, v233
	v_and_b32_e32 v116, 7, v233
	v_lshlrev_b32_e32 v235, 4, v116
	v_lshlrev_b32_e32 v236, 5, v116
	v_lshrrev_b32_e32 v117, 3, v233
	v_lshlrev_b32_e32 v237, 2, v117
	v_lshl_add_u32 v239, v116, 3, v117
	v_lshlrev_b32_e32 v239, 2, v239
	v_lshlrev_b32_e32 v238, 4, v116
	v_and_b32_e32 v117, 1, v117
	v_lshl_add_u32 v238, v117, 2, v238
	v_bfe_u32 v117, v233, 4, 1
	v_lshl_add_u32 v238, v117, 1, v238
	v_lshrrev_b32_e32 v117, 5, v233
	v_add_u32_e32 v238, v117, v238
	v_lshlrev_b32_e32 v238, 2, v238
	v_add_u32_e32 v249, 0, v237
	v_add_u32_e32 v250, 32, v237
	v_add_u32_e32 v251, 64, v237
	v_add_u32_e32 v252, 96, v237
	v_add_u32_e32 v253, 128, v237
	v_add_u32_e32 v254, 160, v237
	v_add_u32_e32 v255, 192, v237
	v_add_u32_e32 v153, 224, v237
	v_readfirstlane_b32 s33, v176
	s_lshr_b32 s33, s33, 6
	s_lshl_b32 s101, s33, 13
	s_lshl_b32 s33, s33, 4
	v_readlane_b32 s3, v231, 30
	s_add_u32 s3, s3, s33
	v_readlane_b32 s82, v231, 26
	v_readlane_b32 s83, v231, 27
	s_nop 4
	s_lshl_b32 vcc_lo, s33, 9
	s_add_u32 s82, s82, vcc_lo
	s_addc_u32 s83, s83, 0
	v_lshlrev_b32_e32 v40, 7, v237
	v_lshrrev_b32_e32 v41, 1, v235
	v_add3_u32 v41, v41, v40, s101
	v_lshl_add_u32 v40, v235, 2, v40
	v_mov_b32_e32 v24, 0
	v_add_u32_e32 v42, s101, v234
	v_add_u32_e32 v42, 0x10000, v42
	ds_write_b32 v42, v24 offset:0
	ds_write_b32 v42, v24 offset:256
	ds_write_b32 v42, v24 offset:512
	ds_write_b32 v42, v24 offset:768
	ds_write_b32 v42, v24 offset:1024
	ds_write_b32 v42, v24 offset:1280
	ds_write_b32 v42, v24 offset:1536
	ds_write_b32 v42, v24 offset:1792
	ds_write_b32 v42, v24 offset:2048
	ds_write_b32 v42, v24 offset:2304
	ds_write_b32 v42, v24 offset:2560
	ds_write_b32 v42, v24 offset:2816
	ds_write_b32 v42, v24 offset:3072
	ds_write_b32 v42, v24 offset:3328
	ds_write_b32 v42, v24 offset:3584
	ds_write_b32 v42, v24 offset:3840
	ds_write_b32 v42, v24 offset:4096
	ds_write_b32 v42, v24 offset:4352
	ds_write_b32 v42, v24 offset:4608
	ds_write_b32 v42, v24 offset:4864
	ds_write_b32 v42, v24 offset:5120
	ds_write_b32 v42, v24 offset:5376
	ds_write_b32 v42, v24 offset:5632
	ds_write_b32 v42, v24 offset:5888
	ds_write_b32 v42, v24 offset:6144
	ds_write_b32 v42, v24 offset:6400
	ds_write_b32 v42, v24 offset:6656
	ds_write_b32 v42, v24 offset:6912
	ds_write_b32 v42, v24 offset:7168
	ds_write_b32 v42, v24 offset:7424
	ds_write_b32 v42, v24 offset:7680
	ds_write_b32 v42, v24 offset:7936
	global_load_dwordx4 v[0:3], v40, s[82:83] offset:0
	global_load_dwordx4 v[4:7], v40, s[82:83] offset:16
	global_load_dwordx4 v[8:11], v40, s[82:83] offset:32
	global_load_dwordx4 v[12:15], v40, s[82:83] offset:48
	s_waitcnt vmcnt(0)
	s_add_u32 s82, s82, 0x1000
	s_addc_u32 s83, s83, 0
	v_lshl_or_b32 v0, v0, 7, v235
	v_lshl_or_b32 v1, v1, 7, v235
	v_lshl_or_b32 v2, v2, 7, v235
	v_lshl_or_b32 v3, v3, 7, v235
	v_lshl_or_b32 v4, v4, 7, v235
	v_lshl_or_b32 v5, v5, 7, v235
	v_lshl_or_b32 v6, v6, 7, v235
	v_lshl_or_b32 v7, v7, 7, v235
	v_lshl_or_b32 v8, v8, 7, v235
	v_lshl_or_b32 v9, v9, 7, v235
	v_lshl_or_b32 v10, v10, 7, v235
	v_lshl_or_b32 v11, v11, 7, v235
	v_lshl_or_b32 v12, v12, 7, v235
	v_lshl_or_b32 v13, v13, 7, v235
	v_lshl_or_b32 v14, v14, 7, v235
	v_lshl_or_b32 v15, v15, 7, v235
	v_or_b32_e32 v1, 1, v1
	v_or_b32_e32 v2, 2, v2
	v_or_b32_e32 v3, 3, v3
	v_or_b32_e32 v4, 4, v4
	v_or_b32_e32 v5, 5, v5
	v_or_b32_e32 v6, 6, v6
	v_or_b32_e32 v7, 7, v7
	v_or_b32_e32 v8, 8, v8
	v_or_b32_e32 v9, 9, v9
	v_or_b32_e32 v10, 10, v10
	v_or_b32_e32 v11, 11, v11
	v_or_b32_e32 v12, 12, v12
	v_or_b32_e32 v13, 13, v13
	v_or_b32_e32 v14, 14, v14
	v_or_b32_e32 v15, 15, v15
	v_min_u32_e32 v16, v0, v1
	v_min_u32_e32 v17, v2, v3
	v_min_u32_e32 v18, v4, v5
	v_min_u32_e32 v19, v6, v7
	v_min_u32_e32 v20, v8, v9
	v_min_u32_e32 v21, v10, v11
	v_min_u32_e32 v22, v12, v13
	v_min_u32_e32 v23, v14, v15
	v_max_u32_e32 v1, v0, v1
	v_max_u32_e32 v3, v2, v3
	v_max_u32_e32 v5, v4, v5
	v_max_u32_e32 v7, v6, v7
	v_max_u32_e32 v9, v8, v9
	v_max_u32_e32 v11, v10, v11
	v_max_u32_e32 v13, v12, v13
	v_max_u32_e32 v15, v14, v15
	v_min_u32_e32 v0, v16, v3
	v_min_u32_e32 v2, v1, v17
	v_min_u32_e32 v4, v18, v7
	v_min_u32_e32 v6, v5, v19
	v_min_u32_e32 v8, v20, v11
	v_min_u32_e32 v10, v9, v21
	v_min_u32_e32 v12, v22, v15
	v_min_u32_e32 v14, v13, v23
	v_max_u32_e32 v3, v16, v3
	v_max_u32_e32 v17, v1, v17
	v_max_u32_e32 v7, v18, v7
	v_max_u32_e32 v19, v5, v19
	v_max_u32_e32 v11, v20, v11
	v_max_u32_e32 v21, v9, v21
	v_max_u32_e32 v15, v22, v15
	v_max_u32_e32 v23, v13, v23
	v_min_u32_e32 v16, v0, v2
	v_min_u32_e32 v1, v17, v3
	v_min_u32_e32 v18, v4, v6
	v_min_u32_e32 v5, v19, v7
	v_min_u32_e32 v20, v8, v10
	v_min_u32_e32 v9, v21, v11
	v_min_u32_e32 v22, v12, v14
	v_min_u32_e32 v13, v23, v15
	v_max_u32_e32 v2, v0, v2
	v_max_u32_e32 v3, v17, v3
	v_max_u32_e32 v6, v4, v6
	v_max_u32_e32 v7, v19, v7
	v_max_u32_e32 v10, v8, v10
	v_max_u32_e32 v11, v21, v11
	v_max_u32_e32 v14, v12, v14
	v_max_u32_e32 v15, v23, v15
	v_min_u32_e32 v0, v16, v7
	v_min_u32_e32 v17, v2, v5
	v_min_u32_e32 v4, v1, v6
	v_min_u32_e32 v19, v3, v18
	v_min_u32_e32 v8, v20, v15
	v_min_u32_e32 v21, v10, v13
	v_min_u32_e32 v12, v9, v14
	v_min_u32_e32 v23, v11, v22
	v_max_u32_e32 v7, v16, v7
	v_max_u32_e32 v5, v2, v5
	v_max_u32_e32 v6, v1, v6
	v_max_u32_e32 v18, v3, v18
	v_max_u32_e32 v15, v20, v15
	v_max_u32_e32 v13, v10, v13
	v_max_u32_e32 v14, v9, v14
	v_max_u32_e32 v22, v11, v22
	v_min_u32_e32 v16, v0, v4
	v_min_u32_e32 v2, v17, v19
	v_min_u32_e32 v1, v18, v5
	v_min_u32_e32 v3, v6, v7
	v_min_u32_e32 v20, v8, v12
	v_min_u32_e32 v10, v21, v23
	v_min_u32_e32 v9, v22, v13
	v_min_u32_e32 v11, v14, v15
; DEV void sort_lists(int lane, int& myi0, int& myi1, float& myg0, float& myg1) {
; #pragma unroll
;     for (int k = 2; k <= 128; k <<= 1) {
; #pragma unroll
;       for (int j = k >> 1; j >= 1; j >>= 1) {
;         if (j == 64) {
;           const bool sw_ = myi1 < myi0;
;           const int ti = sw_ ? myi1 : myi0, tj = sw_ ? myi0 : myi1; const float tg = sw_ ? myg1 : myg0, th = sw_ ? myg0 : myg1;
;           myi0 = ti; myi1 = tj; myg0 = tg; myg1 = th;
;         } else {
;           const bool lower = (lane & j) == 0;
;           {
;             const bool up = (k == 128) ? true : ((k == 64) ? true : ((lane & k) == 0));
;             const int oi = __shfl_xor(myi0, j); const float og = __shfl_xor(myg0, j);
;             const bool take = (lower == up) ? (oi < myi0) : (oi > myi0);
;             myi0 = take ? oi : myi0; myg0 = take ? og : myg0;
;           }
;           {
;             const bool up = (k == 128) ? true : ((k == 64) ? false : ((lane & k) == 0));
;             const int oi = __shfl_xor(myi1, j); const float og = __shfl_xor(myg1, j);
;             const bool take = (lower == up) ? (oi < myi1) : (oi > myi1);
;             myi1 = take ? oi : myi1; myg1 = take ? og : myg1;
;           }
;         }
;       }
;     }
; }
	v_max_u32_e32 v4, v0, v4
	v_max_u32_e32 v19, v17, v19
	v_max_u32_e32 v5, v18, v5
	v_max_u32_e32 v7, v6, v7
	v_max_u32_e32 v12, v8, v12
	v_max_u32_e32 v23, v21, v23
	v_max_u32_e32 v13, v22, v13
	v_max_u32_e32 v15, v14, v15
	v_min_u32_e32 v0, v16, v2
	v_min_u32_e32 v17, v4, v19
	v_min_u32_e32 v18, v1, v3
	v_min_u32_e32 v6, v5, v7
	v_min_u32_e32 v8, v20, v10
	v_min_u32_e32 v21, v12, v23
	v_min_u32_e32 v22, v9, v11
	v_min_u32_e32 v14, v13, v15
	v_max_u32_e32 v2, v16, v2
	v_max_u32_e32 v19, v4, v19
	v_max_u32_e32 v3, v1, v3
	v_max_u32_e32 v7, v5, v7
	v_max_u32_e32 v10, v20, v10
	v_max_u32_e32 v23, v12, v23
	v_max_u32_e32 v11, v9, v11
	v_max_u32_e32 v15, v13, v15
	v_min_u32_e32 v16, v0, v15
	v_min_u32_e32 v4, v2, v14
	v_min_u32_e32 v1, v17, v11
	v_min_u32_e32 v5, v19, v22
	v_min_u32_e32 v20, v18, v23
	v_min_u32_e32 v12, v3, v21
	v_min_u32_e32 v9, v6, v10
	v_min_u32_e32 v13, v7, v8
	v_max_u32_e32 v15, v0, v15
	v_max_u32_e32 v14, v2, v14
	v_max_u32_e32 v11, v17, v11
	v_max_u32_e32 v22, v19, v22
	v_max_u32_e32 v23, v18, v23
	v_max_u32_e32 v21, v3, v21
	v_max_u32_e32 v10, v6, v10
	v_max_u32_e32 v8, v7, v8
	v_min_u32_e32 v0, v16, v20
	v_min_u32_e32 v2, v4, v12
	v_min_u32_e32 v17, v1, v9
	v_min_u32_e32 v19, v5, v13
	v_min_u32_e32 v18, v8, v22
	v_min_u32_e32 v3, v10, v11
	v_min_u32_e32 v6, v21, v14
	v_min_u32_e32 v7, v23, v15
	v_max_u32_e32 v20, v16, v20
	v_max_u32_e32 v12, v4, v12
	v_max_u32_e32 v9, v1, v9
	v_max_u32_e32 v13, v5, v13
	v_max_u32_e32 v22, v8, v22
	v_max_u32_e32 v11, v10, v11
	v_max_u32_e32 v14, v21, v14
	v_max_u32_e32 v15, v23, v15
	v_min_u32_e32 v16, v0, v17
	v_min_u32_e32 v4, v2, v19
	v_min_u32_e32 v1, v20, v9
	v_min_u32_e32 v5, v12, v13
	v_min_u32_e32 v8, v18, v6
	v_min_u32_e32 v10, v3, v7
	v_min_u32_e32 v21, v22, v14
	v_min_u32_e32 v23, v11, v15
	v_max_u32_e32 v17, v0, v17
	v_max_u32_e32 v19, v2, v19
	v_max_u32_e32 v9, v20, v9
	v_max_u32_e32 v13, v12, v13
	v_max_u32_e32 v6, v18, v6
	v_max_u32_e32 v7, v3, v7
	v_max_u32_e32 v14, v22, v14
	v_max_u32_e32 v15, v11, v15
	v_min_u32_e32 v0, v16, v4
	v_min_u32_e32 v2, v17, v19
	v_min_u32_e32 v20, v1, v5
	v_min_u32_e32 v12, v9, v13
	v_min_u32_e32 v18, v8, v10
	v_min_u32_e32 v3, v6, v7
	v_min_u32_e32 v22, v21, v23
	v_min_u32_e32 v11, v14, v15
	v_max_u32_e32 v4, v16, v4
	v_max_u32_e32 v19, v17, v19
	v_max_u32_e32 v5, v1, v5
	v_max_u32_e32 v13, v9, v13
	v_max_u32_e32 v10, v8, v10
	v_max_u32_e32 v7, v6, v7
	v_max_u32_e32 v23, v21, v23
	v_max_u32_e32 v15, v14, v15
	s_mov_b32 s88, 0x55555555
	s_mov_b32 s89, 0x55555555
	s_nop 1
	v_min_u32_dpp v24, v15, v0 quad_perm:[1,0,3,2] row_mask:0xf bank_mask:0xf
	v_max_u32_dpp v25, v15, v0 quad_perm:[1,0,3,2] row_mask:0xf bank_mask:0xf
	v_min_u32_dpp v26, v0, v15 quad_perm:[1,0,3,2] row_mask:0xf bank_mask:0xf
	v_max_u32_dpp v27, v0, v15 quad_perm:[1,0,3,2] row_mask:0xf bank_mask:0xf
	v_min_u32_dpp v28, v11, v4 quad_perm:[1,0,3,2] row_mask:0xf bank_mask:0xf
	v_max_u32_dpp v29, v11, v4 quad_perm:[1,0,3,2] row_mask:0xf bank_mask:0xf
	v_min_u32_dpp v30, v4, v11 quad_perm:[1,0,3,2] row_mask:0xf bank_mask:0xf
	v_max_u32_dpp v31, v4, v11 quad_perm:[1,0,3,2] row_mask:0xf bank_mask:0xf
	v_min_u32_dpp v32, v23, v2 quad_perm:[1,0,3,2] row_mask:0xf bank_mask:0xf
	v_max_u32_dpp v33, v23, v2 quad_perm:[1,0,3,2] row_mask:0xf bank_mask:0xf
	v_min_u32_dpp v34, v2, v23 quad_perm:[1,0,3,2] row_mask:0xf bank_mask:0xf
	v_max_u32_dpp v35, v2, v23 quad_perm:[1,0,3,2] row_mask:0xf bank_mask:0xf
	v_min_u32_dpp v36, v22, v19 quad_perm:[1,0,3,2] row_mask:0xf bank_mask:0xf
	v_max_u32_dpp v37, v22, v19 quad_perm:[1,0,3,2] row_mask:0xf bank_mask:0xf
	v_min_u32_dpp v38, v19, v22 quad_perm:[1,0,3,2] row_mask:0xf bank_mask:0xf
	v_max_u32_dpp v39, v19, v22 quad_perm:[1,0,3,2] row_mask:0xf bank_mask:0xf
	v_cndmask_b32_e64 v0, v25, v24, s[88:89]
	v_cndmask_b32_e64 v15, v27, v26, s[88:89]
	v_cndmask_b32_e64 v4, v29, v28, s[88:89]
	v_cndmask_b32_e64 v11, v31, v30, s[88:89]
	v_cndmask_b32_e64 v2, v33, v32, s[88:89]
	v_cndmask_b32_e64 v23, v35, v34, s[88:89]
	v_cndmask_b32_e64 v19, v37, v36, s[88:89]
	v_cndmask_b32_e64 v22, v39, v38, s[88:89]
	s_nop 1
	v_min_u32_dpp v24, v7, v20 quad_perm:[1,0,3,2] row_mask:0xf bank_mask:0xf
	v_max_u32_dpp v25, v7, v20 quad_perm:[1,0,3,2] row_mask:0xf bank_mask:0xf
	v_min_u32_dpp v26, v20, v7 quad_perm:[1,0,3,2] row_mask:0xf bank_mask:0xf
	v_max_u32_dpp v27, v20, v7 quad_perm:[1,0,3,2] row_mask:0xf bank_mask:0xf
	v_min_u32_dpp v28, v3, v5 quad_perm:[1,0,3,2] row_mask:0xf bank_mask:0xf
	v_max_u32_dpp v29, v3, v5 quad_perm:[1,0,3,2] row_mask:0xf bank_mask:0xf
	v_min_u32_dpp v30, v5, v3 quad_perm:[1,0,3,2] row_mask:0xf bank_mask:0xf
	v_max_u32_dpp v31, v5, v3 quad_perm:[1,0,3,2] row_mask:0xf bank_mask:0xf
	v_min_u32_dpp v32, v10, v12 quad_perm:[1,0,3,2] row_mask:0xf bank_mask:0xf
	v_max_u32_dpp v33, v10, v12 quad_perm:[1,0,3,2] row_mask:0xf bank_mask:0xf
	v_min_u32_dpp v34, v12, v10 quad_perm:[1,0,3,2] row_mask:0xf bank_mask:0xf
	v_max_u32_dpp v35, v12, v10 quad_perm:[1,0,3,2] row_mask:0xf bank_mask:0xf
	v_min_u32_dpp v36, v18, v13 quad_perm:[1,0,3,2] row_mask:0xf bank_mask:0xf
	v_max_u32_dpp v37, v18, v13 quad_perm:[1,0,3,2] row_mask:0xf bank_mask:0xf
	v_min_u32_dpp v38, v13, v18 quad_perm:[1,0,3,2] row_mask:0xf bank_mask:0xf
	v_max_u32_dpp v39, v13, v18 quad_perm:[1,0,3,2] row_mask:0xf bank_mask:0xf
	v_cndmask_b32_e64 v20, v25, v24, s[88:89]
	v_cndmask_b32_e64 v7, v27, v26, s[88:89]
	v_cndmask_b32_e64 v5, v29, v28, s[88:89]
	v_cndmask_b32_e64 v3, v31, v30, s[88:89]
	v_cndmask_b32_e64 v12, v33, v32, s[88:89]
	v_cndmask_b32_e64 v10, v35, v34, s[88:89]
	v_cndmask_b32_e64 v13, v37, v36, s[88:89]
	v_cndmask_b32_e64 v18, v39, v38, s[88:89]
	s_nop 1
	v_min_u32_e32 v16, v0, v18
; DEV void sort_lists(int lane, int& myi0, int& myi1, float& myg0, float& myg1) {
; #pragma unroll
;     for (int k = 2; k <= 128; k <<= 1) {
; #pragma unroll
;       for (int j = k >> 1; j >= 1; j >>= 1) {
;         if (j == 64) {
;           const bool sw_ = myi1 < myi0;
;           const int ti = sw_ ? myi1 : myi0, tj = sw_ ? myi0 : myi1; const float tg = sw_ ? myg1 : myg0, th = sw_ ? myg0 : myg1;
;           myi0 = ti; myi1 = tj; myg0 = tg; myg1 = th;
;         } else {
;           const bool lower = (lane & j) == 0;
;           {
;             const bool up = (k == 128) ? true : ((k == 64) ? true : ((lane & k) == 0));
;             const int oi = __shfl_xor(myi0, j); const float og = __shfl_xor(myg0, j);
;             const bool take = (lower == up) ? (oi < myi0) : (oi > myi0);
;             myi0 = take ? oi : myi0; myg0 = take ? og : myg0;
;           }
;           {
;             const bool up = (k == 128) ? true : ((k == 64) ? false : ((lane & k) == 0));
;             const int oi = __shfl_xor(myi1, j); const float og = __shfl_xor(myg1, j);
;             const bool take = (lower == up) ? (oi < myi1) : (oi > myi1);
;             myi1 = take ? oi : myi1; myg1 = take ? og : myg1;
;           }
;         }
;       }
;     }
; }
	v_min_u32_e32 v17, v4, v10
	v_min_u32_e32 v1, v2, v3
	v_min_u32_e32 v9, v19, v7
	v_min_u32_e32 v8, v20, v22
	v_min_u32_e32 v6, v5, v23
	v_min_u32_e32 v21, v12, v11
	v_min_u32_e32 v14, v13, v15
	v_max_u32_e32 v18, v0, v18
	v_max_u32_e32 v10, v4, v10
	v_max_u32_e32 v3, v2, v3
	v_max_u32_e32 v7, v19, v7
	v_max_u32_e32 v22, v20, v22
	v_max_u32_e32 v23, v5, v23
	v_max_u32_e32 v11, v12, v11
	v_max_u32_e32 v15, v13, v15
	v_min_u32_e32 v0, v16, v8
	v_min_u32_e32 v4, v17, v6
	v_min_u32_e32 v2, v1, v21
	v_min_u32_e32 v19, v9, v14
	v_min_u32_e32 v20, v18, v22
	v_min_u32_e32 v5, v10, v23
	v_min_u32_e32 v12, v3, v11
	v_min_u32_e32 v13, v7, v15
	v_max_u32_e32 v8, v16, v8
	v_max_u32_e32 v6, v17, v6
	v_max_u32_e32 v21, v1, v21
	v_max_u32_e32 v14, v9, v14
	v_max_u32_e32 v22, v18, v22
	v_max_u32_e32 v23, v10, v23
	v_max_u32_e32 v11, v3, v11
	v_max_u32_e32 v15, v7, v15
	v_min_u32_e32 v16, v0, v2
	v_min_u32_e32 v17, v4, v19
	v_min_u32_e32 v1, v8, v21
	v_min_u32_e32 v9, v6, v14
	v_min_u32_e32 v18, v20, v12
	v_min_u32_e32 v10, v5, v13
	v_min_u32_e32 v3, v22, v11
	v_min_u32_e32 v7, v23, v15
	v_max_u32_e32 v2, v0, v2
	v_max_u32_e32 v19, v4, v19
	v_max_u32_e32 v21, v8, v21
	v_max_u32_e32 v14, v6, v14
	v_max_u32_e32 v12, v20, v12
	v_max_u32_e32 v13, v5, v13
	v_max_u32_e32 v11, v22, v11
	v_max_u32_e32 v15, v23, v15
	v_min_u32_e32 v0, v16, v17
	v_min_u32_e32 v4, v2, v19
	v_min_u32_e32 v8, v1, v9
	v_min_u32_e32 v6, v21, v14
	v_min_u32_e32 v20, v18, v10
	v_min_u32_e32 v5, v12, v13
	v_min_u32_e32 v22, v3, v7
	v_min_u32_e32 v23, v11, v15
	v_max_u32_e32 v17, v16, v17
	v_max_u32_e32 v19, v2, v19
	v_max_u32_e32 v9, v1, v9
	v_max_u32_e32 v14, v21, v14
	v_max_u32_e32 v10, v18, v10
	v_max_u32_e32 v13, v12, v13
	v_max_u32_e32 v7, v3, v7
	v_max_u32_e32 v15, v11, v15
	s_mov_b32 s88, 0x33333333
	s_mov_b32 s89, 0x33333333
	s_nop 1
	v_min_u32_dpp v24, v15, v0 quad_perm:[3,2,1,0] row_mask:0xf bank_mask:0xf
	v_max_u32_dpp v25, v15, v0 quad_perm:[3,2,1,0] row_mask:0xf bank_mask:0xf
	v_min_u32_dpp v26, v0, v15 quad_perm:[3,2,1,0] row_mask:0xf bank_mask:0xf
	v_max_u32_dpp v27, v0, v15 quad_perm:[3,2,1,0] row_mask:0xf bank_mask:0xf
	v_min_u32_dpp v28, v23, v17 quad_perm:[3,2,1,0] row_mask:0xf bank_mask:0xf
	v_max_u32_dpp v29, v23, v17 quad_perm:[3,2,1,0] row_mask:0xf bank_mask:0xf
	v_min_u32_dpp v30, v17, v23 quad_perm:[3,2,1,0] row_mask:0xf bank_mask:0xf
	v_max_u32_dpp v31, v17, v23 quad_perm:[3,2,1,0] row_mask:0xf bank_mask:0xf
	v_min_u32_dpp v32, v7, v4 quad_perm:[3,2,1,0] row_mask:0xf bank_mask:0xf
	v_max_u32_dpp v33, v7, v4 quad_perm:[3,2,1,0] row_mask:0xf bank_mask:0xf
	v_min_u32_dpp v34, v4, v7 quad_perm:[3,2,1,0] row_mask:0xf bank_mask:0xf
	v_max_u32_dpp v35, v4, v7 quad_perm:[3,2,1,0] row_mask:0xf bank_mask:0xf
	v_min_u32_dpp v36, v22, v19 quad_perm:[3,2,1,0] row_mask:0xf bank_mask:0xf
	v_max_u32_dpp v37, v22, v19 quad_perm:[3,2,1,0] row_mask:0xf bank_mask:0xf
	v_min_u32_dpp v38, v19, v22 quad_perm:[3,2,1,0] row_mask:0xf bank_mask:0xf
	v_max_u32_dpp v39, v19, v22 quad_perm:[3,2,1,0] row_mask:0xf bank_mask:0xf
	v_cndmask_b32_e64 v0, v25, v24, s[88:89]
	v_cndmask_b32_e64 v15, v27, v26, s[88:89]
	v_cndmask_b32_e64 v17, v29, v28, s[88:89]
	v_cndmask_b32_e64 v23, v31, v30, s[88:89]
	v_cndmask_b32_e64 v4, v33, v32, s[88:89]
	v_cndmask_b32_e64 v7, v35, v34, s[88:89]
	v_cndmask_b32_e64 v19, v37, v36, s[88:89]
	v_cndmask_b32_e64 v22, v39, v38, s[88:89]
	s_nop 1
	v_min_u32_dpp v24, v13, v8 quad_perm:[3,2,1,0] row_mask:0xf bank_mask:0xf
	v_max_u32_dpp v25, v13, v8 quad_perm:[3,2,1,0] row_mask:0xf bank_mask:0xf
	v_min_u32_dpp v26, v8, v13 quad_perm:[3,2,1,0] row_mask:0xf bank_mask:0xf
	v_max_u32_dpp v27, v8, v13 quad_perm:[3,2,1,0] row_mask:0xf bank_mask:0xf
	v_min_u32_dpp v28, v5, v9 quad_perm:[3,2,1,0] row_mask:0xf bank_mask:0xf
	v_max_u32_dpp v29, v5, v9 quad_perm:[3,2,1,0] row_mask:0xf bank_mask:0xf
	v_min_u32_dpp v30, v9, v5 quad_perm:[3,2,1,0] row_mask:0xf bank_mask:0xf
	v_max_u32_dpp v31, v9, v5 quad_perm:[3,2,1,0] row_mask:0xf bank_mask:0xf
	v_min_u32_dpp v32, v10, v6 quad_perm:[3,2,1,0] row_mask:0xf bank_mask:0xf
	v_max_u32_dpp v33, v10, v6 quad_perm:[3,2,1,0] row_mask:0xf bank_mask:0xf
	v_min_u32_dpp v34, v6, v10 quad_perm:[3,2,1,0] row_mask:0xf bank_mask:0xf
	v_max_u32_dpp v35, v6, v10 quad_perm:[3,2,1,0] row_mask:0xf bank_mask:0xf
	v_min_u32_dpp v36, v20, v14 quad_perm:[3,2,1,0] row_mask:0xf bank_mask:0xf
	v_max_u32_dpp v37, v20, v14 quad_perm:[3,2,1,0] row_mask:0xf bank_mask:0xf
	v_min_u32_dpp v38, v14, v20 quad_perm:[3,2,1,0] row_mask:0xf bank_mask:0xf
	v_max_u32_dpp v39, v14, v20 quad_perm:[3,2,1,0] row_mask:0xf bank_mask:0xf
	v_cndmask_b32_e64 v8, v25, v24, s[88:89]
	v_cndmask_b32_e64 v13, v27, v26, s[88:89]
	v_cndmask_b32_e64 v9, v29, v28, s[88:89]
	v_cndmask_b32_e64 v5, v31, v30, s[88:89]
	v_cndmask_b32_e64 v6, v33, v32, s[88:89]
	v_cndmask_b32_e64 v10, v35, v34, s[88:89]
	v_cndmask_b32_e64 v14, v37, v36, s[88:89]
	v_cndmask_b32_e64 v20, v39, v38, s[88:89]
	s_nop 1
	s_mov_b32 s88, 0x55555555
	s_mov_b32 s89, 0x55555555
	s_nop 1
	v_min_u32_dpp v24, v0, v0 quad_perm:[1,0,3,2] row_mask:0xf bank_mask:0xf
	v_max_u32_dpp v25, v0, v0 quad_perm:[1,0,3,2] row_mask:0xf bank_mask:0xf
	v_min_u32_dpp v26, v17, v17 quad_perm:[1,0,3,2] row_mask:0xf bank_mask:0xf
	v_max_u32_dpp v27, v17, v17 quad_perm:[1,0,3,2] row_mask:0xf bank_mask:0xf
	v_min_u32_dpp v28, v4, v4 quad_perm:[1,0,3,2] row_mask:0xf bank_mask:0xf
	v_max_u32_dpp v29, v4, v4 quad_perm:[1,0,3,2] row_mask:0xf bank_mask:0xf
	v_min_u32_dpp v30, v19, v19 quad_perm:[1,0,3,2] row_mask:0xf bank_mask:0xf
	v_max_u32_dpp v31, v19, v19 quad_perm:[1,0,3,2] row_mask:0xf bank_mask:0xf
	v_min_u32_dpp v32, v8, v8 quad_perm:[1,0,3,2] row_mask:0xf bank_mask:0xf
; DEV void sort_lists(int lane, int& myi0, int& myi1, float& myg0, float& myg1) {
; #pragma unroll
;     for (int k = 2; k <= 128; k <<= 1) {
; #pragma unroll
;       for (int j = k >> 1; j >= 1; j >>= 1) {
;         if (j == 64) {
;           const bool sw_ = myi1 < myi0;
;           const int ti = sw_ ? myi1 : myi0, tj = sw_ ? myi0 : myi1; const float tg = sw_ ? myg1 : myg0, th = sw_ ? myg0 : myg1;
;           myi0 = ti; myi1 = tj; myg0 = tg; myg1 = th;
;         } else {
;           const bool lower = (lane & j) == 0;
;           {
;             const bool up = (k == 128) ? true : ((k == 64) ? true : ((lane & k) == 0));
;             const int oi = __shfl_xor(myi0, j); const float og = __shfl_xor(myg0, j);
;             const bool take = (lower == up) ? (oi < myi0) : (oi > myi0);
;             myi0 = take ? oi : myi0; myg0 = take ? og : myg0;
;           }
;           {
;             const bool up = (k == 128) ? true : ((k == 64) ? false : ((lane & k) == 0));
;             const int oi = __shfl_xor(myi1, j); const float og = __shfl_xor(myg1, j);
;             const bool take = (lower == up) ? (oi < myi1) : (oi > myi1);
;             myi1 = take ? oi : myi1; myg1 = take ? og : myg1;
;           }
;         }
;       }
;     }
; }
	v_max_u32_dpp v33, v8, v8 quad_perm:[1,0,3,2] row_mask:0xf bank_mask:0xf
	v_min_u32_dpp v34, v9, v9 quad_perm:[1,0,3,2] row_mask:0xf bank_mask:0xf
	v_max_u32_dpp v35, v9, v9 quad_perm:[1,0,3,2] row_mask:0xf bank_mask:0xf
	v_min_u32_dpp v36, v6, v6 quad_perm:[1,0,3,2] row_mask:0xf bank_mask:0xf
	v_max_u32_dpp v37, v6, v6 quad_perm:[1,0,3,2] row_mask:0xf bank_mask:0xf
	v_min_u32_dpp v38, v14, v14 quad_perm:[1,0,3,2] row_mask:0xf bank_mask:0xf
	v_max_u32_dpp v39, v14, v14 quad_perm:[1,0,3,2] row_mask:0xf bank_mask:0xf
	v_cndmask_b32_e64 v0, v25, v24, s[88:89]
	v_cndmask_b32_e64 v17, v27, v26, s[88:89]
	v_cndmask_b32_e64 v4, v29, v28, s[88:89]
	v_cndmask_b32_e64 v19, v31, v30, s[88:89]
	v_cndmask_b32_e64 v8, v33, v32, s[88:89]
	v_cndmask_b32_e64 v9, v35, v34, s[88:89]
	v_cndmask_b32_e64 v6, v37, v36, s[88:89]
	v_cndmask_b32_e64 v14, v39, v38, s[88:89]
	s_nop 1
	v_min_u32_dpp v24, v20, v20 quad_perm:[1,0,3,2] row_mask:0xf bank_mask:0xf
	v_max_u32_dpp v25, v20, v20 quad_perm:[1,0,3,2] row_mask:0xf bank_mask:0xf
	v_min_u32_dpp v26, v10, v10 quad_perm:[1,0,3,2] row_mask:0xf bank_mask:0xf
	v_max_u32_dpp v27, v10, v10 quad_perm:[1,0,3,2] row_mask:0xf bank_mask:0xf
	v_min_u32_dpp v28, v5, v5 quad_perm:[1,0,3,2] row_mask:0xf bank_mask:0xf
	v_max_u32_dpp v29, v5, v5 quad_perm:[1,0,3,2] row_mask:0xf bank_mask:0xf
	v_min_u32_dpp v30, v13, v13 quad_perm:[1,0,3,2] row_mask:0xf bank_mask:0xf
	v_max_u32_dpp v31, v13, v13 quad_perm:[1,0,3,2] row_mask:0xf bank_mask:0xf
	v_min_u32_dpp v32, v22, v22 quad_perm:[1,0,3,2] row_mask:0xf bank_mask:0xf
	v_max_u32_dpp v33, v22, v22 quad_perm:[1,0,3,2] row_mask:0xf bank_mask:0xf
	v_min_u32_dpp v34, v7, v7 quad_perm:[1,0,3,2] row_mask:0xf bank_mask:0xf
	v_max_u32_dpp v35, v7, v7 quad_perm:[1,0,3,2] row_mask:0xf bank_mask:0xf
	v_min_u32_dpp v36, v23, v23 quad_perm:[1,0,3,2] row_mask:0xf bank_mask:0xf
	v_max_u32_dpp v37, v23, v23 quad_perm:[1,0,3,2] row_mask:0xf bank_mask:0xf
	v_min_u32_dpp v38, v15, v15 quad_perm:[1,0,3,2] row_mask:0xf bank_mask:0xf
	v_max_u32_dpp v39, v15, v15 quad_perm:[1,0,3,2] row_mask:0xf bank_mask:0xf
	v_cndmask_b32_e64 v20, v25, v24, s[88:89]
	v_cndmask_b32_e64 v10, v27, v26, s[88:89]
	v_cndmask_b32_e64 v5, v29, v28, s[88:89]
	v_cndmask_b32_e64 v13, v31, v30, s[88:89]
	v_cndmask_b32_e64 v22, v33, v32, s[88:89]
	v_cndmask_b32_e64 v7, v35, v34, s[88:89]
	v_cndmask_b32_e64 v23, v37, v36, s[88:89]
	v_cndmask_b32_e64 v15, v39, v38, s[88:89]
	s_nop 1
	v_min_u32_e32 v16, v0, v20
	v_min_u32_e32 v2, v17, v10
	v_min_u32_e32 v1, v4, v5
	v_min_u32_e32 v21, v19, v13
	v_min_u32_e32 v18, v8, v22
	v_min_u32_e32 v12, v9, v7
	v_min_u32_e32 v3, v6, v23
	v_min_u32_e32 v11, v14, v15
	v_max_u32_e32 v20, v0, v20
	v_max_u32_e32 v10, v17, v10
	v_max_u32_e32 v5, v4, v5
	v_max_u32_e32 v13, v19, v13
	v_max_u32_e32 v22, v8, v22
	v_max_u32_e32 v7, v9, v7
	v_max_u32_e32 v23, v6, v23
	v_max_u32_e32 v15, v14, v15
	v_min_u32_e32 v0, v16, v18
	v_min_u32_e32 v17, v2, v12
	v_min_u32_e32 v4, v1, v3
	v_min_u32_e32 v19, v21, v11
	v_min_u32_e32 v8, v20, v22
	v_min_u32_e32 v9, v10, v7
	v_min_u32_e32 v6, v5, v23
	v_min_u32_e32 v14, v13, v15
	v_max_u32_e32 v18, v16, v18
	v_max_u32_e32 v12, v2, v12
	v_max_u32_e32 v3, v1, v3
	v_max_u32_e32 v11, v21, v11
	v_max_u32_e32 v22, v20, v22
	v_max_u32_e32 v7, v10, v7
	v_max_u32_e32 v23, v5, v23
	v_max_u32_e32 v15, v13, v15
	v_min_u32_e32 v16, v0, v4
	v_min_u32_e32 v2, v17, v19
	v_min_u32_e32 v1, v18, v3
	v_min_u32_e32 v21, v12, v11
	v_min_u32_e32 v20, v8, v6
	v_min_u32_e32 v10, v9, v14
	v_min_u32_e32 v5, v22, v23
	v_min_u32_e32 v13, v7, v15
	v_max_u32_e32 v4, v0, v4
	v_max_u32_e32 v19, v17, v19
	v_max_u32_e32 v3, v18, v3
	v_max_u32_e32 v11, v12, v11
	v_max_u32_e32 v6, v8, v6
	v_max_u32_e32 v14, v9, v14
	v_max_u32_e32 v23, v22, v23
	v_max_u32_e32 v15, v7, v15
	v_min_u32_e32 v0, v16, v2
	v_min_u32_e32 v17, v4, v19
	v_min_u32_e32 v18, v1, v21
	v_min_u32_e32 v12, v3, v11
	v_min_u32_e32 v8, v20, v10
	v_min_u32_e32 v9, v6, v14
	v_min_u32_e32 v22, v5, v13
	v_min_u32_e32 v7, v23, v15
	v_max_u32_e32 v2, v16, v2
	v_max_u32_e32 v19, v4, v19
	v_max_u32_e32 v21, v1, v21
	v_max_u32_e32 v11, v3, v11
	v_max_u32_e32 v10, v20, v10
	v_max_u32_e32 v14, v6, v14
	v_max_u32_e32 v13, v5, v13
	v_max_u32_e32 v15, v23, v15
	s_mov_b32 s88, 0xf0f0f0f
	s_mov_b32 s89, 0xf0f0f0f
	s_nop 1
	v_min_u32_dpp v24, v15, v0 row_half_mirror row_mask:0xf bank_mask:0xf
	v_max_u32_dpp v25, v15, v0 row_half_mirror row_mask:0xf bank_mask:0xf
	v_min_u32_dpp v26, v0, v15 row_half_mirror row_mask:0xf bank_mask:0xf
	v_max_u32_dpp v27, v0, v15 row_half_mirror row_mask:0xf bank_mask:0xf
	v_min_u32_dpp v28, v7, v2 row_half_mirror row_mask:0xf bank_mask:0xf
	v_max_u32_dpp v29, v7, v2 row_half_mirror row_mask:0xf bank_mask:0xf
	v_min_u32_dpp v30, v2, v7 row_half_mirror row_mask:0xf bank_mask:0xf
	v_max_u32_dpp v31, v2, v7 row_half_mirror row_mask:0xf bank_mask:0xf
	v_min_u32_dpp v32, v13, v17 row_half_mirror row_mask:0xf bank_mask:0xf
	v_max_u32_dpp v33, v13, v17 row_half_mirror row_mask:0xf bank_mask:0xf
	v_min_u32_dpp v34, v17, v13 row_half_mirror row_mask:0xf bank_mask:0xf
	v_max_u32_dpp v35, v17, v13 row_half_mirror row_mask:0xf bank_mask:0xf
	v_min_u32_dpp v36, v22, v19 row_half_mirror row_mask:0xf bank_mask:0xf
	v_max_u32_dpp v37, v22, v19 row_half_mirror row_mask:0xf bank_mask:0xf
	v_min_u32_dpp v38, v19, v22 row_half_mirror row_mask:0xf bank_mask:0xf
	v_max_u32_dpp v39, v19, v22 row_half_mirror row_mask:0xf bank_mask:0xf
	v_cndmask_b32_e64 v0, v25, v24, s[88:89]
	v_cndmask_b32_e64 v15, v27, v26, s[88:89]
	v_cndmask_b32_e64 v2, v29, v28, s[88:89]
	v_cndmask_b32_e64 v7, v31, v30, s[88:89]
	v_cndmask_b32_e64 v17, v33, v32, s[88:89]
; DEV void sort_lists(int lane, int& myi0, int& myi1, float& myg0, float& myg1) {
; #pragma unroll
;     for (int k = 2; k <= 128; k <<= 1) {
; #pragma unroll
;       for (int j = k >> 1; j >= 1; j >>= 1) {
;         if (j == 64) {
;           const bool sw_ = myi1 < myi0;
;           const int ti = sw_ ? myi1 : myi0, tj = sw_ ? myi0 : myi1; const float tg = sw_ ? myg1 : myg0, th = sw_ ? myg0 : myg1;
;           myi0 = ti; myi1 = tj; myg0 = tg; myg1 = th;
;         } else {
;           const bool lower = (lane & j) == 0;
;           {
;             const bool up = (k == 128) ? true : ((k == 64) ? true : ((lane & k) == 0));
;             const int oi = __shfl_xor(myi0, j); const float og = __shfl_xor(myg0, j);
;             const bool take = (lower == up) ? (oi < myi0) : (oi > myi0);
;             myi0 = take ? oi : myi0; myg0 = take ? og : myg0;
;           }
;           {
;             const bool up = (k == 128) ? true : ((k == 64) ? false : ((lane & k) == 0));
;             const int oi = __shfl_xor(myi1, j); const float og = __shfl_xor(myg1, j);
;             const bool take = (lower == up) ? (oi < myi1) : (oi > myi1);
;             myi1 = take ? oi : myi1; myg1 = take ? og : myg1;
;           }
;         }
;       }
;     }
; }
	v_cndmask_b32_e64 v13, v35, v34, s[88:89]
	v_cndmask_b32_e64 v19, v37, v36, s[88:89]
	v_cndmask_b32_e64 v22, v39, v38, s[88:89]
	s_nop 1
	v_min_u32_dpp v24, v14, v18 row_half_mirror row_mask:0xf bank_mask:0xf
	v_max_u32_dpp v25, v14, v18 row_half_mirror row_mask:0xf bank_mask:0xf
	v_min_u32_dpp v26, v18, v14 row_half_mirror row_mask:0xf bank_mask:0xf
	v_max_u32_dpp v27, v18, v14 row_half_mirror row_mask:0xf bank_mask:0xf
	v_min_u32_dpp v28, v9, v21 row_half_mirror row_mask:0xf bank_mask:0xf
	v_max_u32_dpp v29, v9, v21 row_half_mirror row_mask:0xf bank_mask:0xf
	v_min_u32_dpp v30, v21, v9 row_half_mirror row_mask:0xf bank_mask:0xf
	v_max_u32_dpp v31, v21, v9 row_half_mirror row_mask:0xf bank_mask:0xf
	v_min_u32_dpp v32, v10, v12 row_half_mirror row_mask:0xf bank_mask:0xf
	v_max_u32_dpp v33, v10, v12 row_half_mirror row_mask:0xf bank_mask:0xf
	v_min_u32_dpp v34, v12, v10 row_half_mirror row_mask:0xf bank_mask:0xf
	v_max_u32_dpp v35, v12, v10 row_half_mirror row_mask:0xf bank_mask:0xf
	v_min_u32_dpp v36, v8, v11 row_half_mirror row_mask:0xf bank_mask:0xf
	v_max_u32_dpp v37, v8, v11 row_half_mirror row_mask:0xf bank_mask:0xf
	v_min_u32_dpp v38, v11, v8 row_half_mirror row_mask:0xf bank_mask:0xf
	v_max_u32_dpp v39, v11, v8 row_half_mirror row_mask:0xf bank_mask:0xf
	v_cndmask_b32_e64 v18, v25, v24, s[88:89]
	v_cndmask_b32_e64 v14, v27, v26, s[88:89]
	v_cndmask_b32_e64 v21, v29, v28, s[88:89]
	v_cndmask_b32_e64 v9, v31, v30, s[88:89]
	v_cndmask_b32_e64 v12, v33, v32, s[88:89]
	v_cndmask_b32_e64 v10, v35, v34, s[88:89]
	v_cndmask_b32_e64 v11, v37, v36, s[88:89]
	v_cndmask_b32_e64 v8, v39, v38, s[88:89]
	s_nop 1
	s_mov_b32 s88, 0x33333333
	s_mov_b32 s89, 0x33333333
	s_nop 1
	v_min_u32_dpp v24, v0, v0 quad_perm:[2,3,0,1] row_mask:0xf bank_mask:0xf
	v_max_u32_dpp v25, v0, v0 quad_perm:[2,3,0,1] row_mask:0xf bank_mask:0xf
	v_min_u32_dpp v26, v2, v2 quad_perm:[2,3,0,1] row_mask:0xf bank_mask:0xf
	v_max_u32_dpp v27, v2, v2 quad_perm:[2,3,0,1] row_mask:0xf bank_mask:0xf
	v_min_u32_dpp v28, v17, v17 quad_perm:[2,3,0,1] row_mask:0xf bank_mask:0xf
	v_max_u32_dpp v29, v17, v17 quad_perm:[2,3,0,1] row_mask:0xf bank_mask:0xf
	v_min_u32_dpp v30, v19, v19 quad_perm:[2,3,0,1] row_mask:0xf bank_mask:0xf
	v_max_u32_dpp v31, v19, v19 quad_perm:[2,3,0,1] row_mask:0xf bank_mask:0xf
	v_min_u32_dpp v32, v18, v18 quad_perm:[2,3,0,1] row_mask:0xf bank_mask:0xf
	v_max_u32_dpp v33, v18, v18 quad_perm:[2,3,0,1] row_mask:0xf bank_mask:0xf
	v_min_u32_dpp v34, v21, v21 quad_perm:[2,3,0,1] row_mask:0xf bank_mask:0xf
	v_max_u32_dpp v35, v21, v21 quad_perm:[2,3,0,1] row_mask:0xf bank_mask:0xf
	v_min_u32_dpp v36, v12, v12 quad_perm:[2,3,0,1] row_mask:0xf bank_mask:0xf
	v_max_u32_dpp v37, v12, v12 quad_perm:[2,3,0,1] row_mask:0xf bank_mask:0xf
	v_min_u32_dpp v38, v11, v11 quad_perm:[2,3,0,1] row_mask:0xf bank_mask:0xf
	v_max_u32_dpp v39, v11, v11 quad_perm:[2,3,0,1] row_mask:0xf bank_mask:0xf
	v_cndmask_b32_e64 v0, v25, v24, s[88:89]
	v_cndmask_b32_e64 v2, v27, v26, s[88:89]
	v_cndmask_b32_e64 v17, v29, v28, s[88:89]
	v_cndmask_b32_e64 v19, v31, v30, s[88:89]
	v_cndmask_b32_e64 v18, v33, v32, s[88:89]
	v_cndmask_b32_e64 v21, v35, v34, s[88:89]
	v_cndmask_b32_e64 v12, v37, v36, s[88:89]
	v_cndmask_b32_e64 v11, v39, v38, s[88:89]
	s_nop 1
	v_min_u32_dpp v24, v8, v8 quad_perm:[2,3,0,1] row_mask:0xf bank_mask:0xf
	v_max_u32_dpp v25, v8, v8 quad_perm:[2,3,0,1] row_mask:0xf bank_mask:0xf
	v_min_u32_dpp v26, v10, v10 quad_perm:[2,3,0,1] row_mask:0xf bank_mask:0xf
	v_max_u32_dpp v27, v10, v10 quad_perm:[2,3,0,1] row_mask:0xf bank_mask:0xf
	v_min_u32_dpp v28, v9, v9 quad_perm:[2,3,0,1] row_mask:0xf bank_mask:0xf
	v_max_u32_dpp v29, v9, v9 quad_perm:[2,3,0,1] row_mask:0xf bank_mask:0xf
	v_min_u32_dpp v30, v14, v14 quad_perm:[2,3,0,1] row_mask:0xf bank_mask:0xf
	v_max_u32_dpp v31, v14, v14 quad_perm:[2,3,0,1] row_mask:0xf bank_mask:0xf
	v_min_u32_dpp v32, v22, v22 quad_perm:[2,3,0,1] row_mask:0xf bank_mask:0xf
	v_max_u32_dpp v33, v22, v22 quad_perm:[2,3,0,1] row_mask:0xf bank_mask:0xf
	v_min_u32_dpp v34, v13, v13 quad_perm:[2,3,0,1] row_mask:0xf bank_mask:0xf
	v_max_u32_dpp v35, v13, v13 quad_perm:[2,3,0,1] row_mask:0xf bank_mask:0xf
	v_min_u32_dpp v36, v7, v7 quad_perm:[2,3,0,1] row_mask:0xf bank_mask:0xf
	v_max_u32_dpp v37, v7, v7 quad_perm:[2,3,0,1] row_mask:0xf bank_mask:0xf
	v_min_u32_dpp v38, v15, v15 quad_perm:[2,3,0,1] row_mask:0xf bank_mask:0xf
	v_max_u32_dpp v39, v15, v15 quad_perm:[2,3,0,1] row_mask:0xf bank_mask:0xf
	v_cndmask_b32_e64 v8, v25, v24, s[88:89]
	v_cndmask_b32_e64 v10, v27, v26, s[88:89]
	v_cndmask_b32_e64 v9, v29, v28, s[88:89]
	v_cndmask_b32_e64 v14, v31, v30, s[88:89]
	v_cndmask_b32_e64 v22, v33, v32, s[88:89]
	v_cndmask_b32_e64 v13, v35, v34, s[88:89]
	v_cndmask_b32_e64 v7, v37, v36, s[88:89]
	v_cndmask_b32_e64 v15, v39, v38, s[88:89]
	s_nop 1
	s_mov_b32 s88, 0x55555555
	s_mov_b32 s89, 0x55555555
	s_nop 1
	v_min_u32_dpp v24, v0, v0 quad_perm:[1,0,3,2] row_mask:0xf bank_mask:0xf
	v_max_u32_dpp v25, v0, v0 quad_perm:[1,0,3,2] row_mask:0xf bank_mask:0xf
	v_min_u32_dpp v26, v2, v2 quad_perm:[1,0,3,2] row_mask:0xf bank_mask:0xf
	v_max_u32_dpp v27, v2, v2 quad_perm:[1,0,3,2] row_mask:0xf bank_mask:0xf
	v_min_u32_dpp v28, v17, v17 quad_perm:[1,0,3,2] row_mask:0xf bank_mask:0xf
	v_max_u32_dpp v29, v17, v17 quad_perm:[1,0,3,2] row_mask:0xf bank_mask:0xf
	v_min_u32_dpp v30, v19, v19 quad_perm:[1,0,3,2] row_mask:0xf bank_mask:0xf
	v_max_u32_dpp v31, v19, v19 quad_perm:[1,0,3,2] row_mask:0xf bank_mask:0xf
	v_min_u32_dpp v32, v18, v18 quad_perm:[1,0,3,2] row_mask:0xf bank_mask:0xf
	v_max_u32_dpp v33, v18, v18 quad_perm:[1,0,3,2] row_mask:0xf bank_mask:0xf
; DEV int tid_l() { int t = threadIdx.x; asm volatile("" : "+v"(t)); return t; }
; DEV void sort_lists(int lane, int& myi0, int& myi1, float& myg0, float& myg1) {
; #pragma unroll
;     for (int k = 2; k <= 128; k <<= 1) {
; #pragma unroll
;       for (int j = k >> 1; j >= 1; j >>= 1) {
;         if (j == 64) {
;           const bool sw_ = myi1 < myi0;
;           const int ti = sw_ ? myi1 : myi0, tj = sw_ ? myi0 : myi1; const float tg = sw_ ? myg1 : myg0, th = sw_ ? myg0 : myg1;
;           myi0 = ti; myi1 = tj; myg0 = tg; myg1 = th;
;         } else {
;           const bool lower = (lane & j) == 0;
;           {
;             const bool up = (k == 128) ? true : ((k == 64) ? true : ((lane & k) == 0));
;             const int oi = __shfl_xor(myi0, j); const float og = __shfl_xor(myg0, j);
;             const bool take = (lower == up) ? (oi < myi0) : (oi > myi0);
;             myi0 = take ? oi : myi0; myg0 = take ? og : myg0;
;           }
;           {
;             const bool up = (k == 128) ? true : ((k == 64) ? false : ((lane & k) == 0));
;             const int oi = __shfl_xor(myi1, j); const float og = __shfl_xor(myg1, j);
;             const bool take = (lower == up) ? (oi < myi1) : (oi > myi1);
;             myi1 = take ? oi : myi1; myg1 = take ? og : myg1;
;           }
;         }
;       }
;     }
; }
; DEV void peer_gather(const Params& P, int l, int m0, const int* idxs, const float* gs) {
;   const int tid = tid_l(), lane = tid & 63, wid = tid >> 6;
;   const unsigned char* U = P.ws + WS_TAB + (size_t)l * 32 * MB;
;   const unsigned char* V = U + 16 * MB;
;   bf16_t* hn = (bf16_t*)(P.ws + WS_HN);
;   const float* gp = P.norm_ple + l * DM;
;   const int row = lane >> 4, rmap = ((row & 1) << 1) | (row >> 1);
;   u32x4 nxa = *(const u32x4*)(hn + (size_t)(m0 + wid * 16) * DM + lane * 16), nxb = *(const u32x4*)(hn + (size_t)(m0 + wid * 16) * DM + lane * 16 + 8);
;   int ni0 = idxs[(wid * 16) * 128 + lane], ni1 = idxs[(wid * 16) * 128 + 64 + lane];
;   float ng0 = gs[(wid * 16) * 128 + lane], ng1 = gs[(wid * 16) * 128 + 64 + lane];
;   sort_lists(lane, ni0, ni1, ng0, ng1);
	v_min_u32_dpp v34, v21, v21 quad_perm:[1,0,3,2] row_mask:0xf bank_mask:0xf
	v_max_u32_dpp v35, v21, v21 quad_perm:[1,0,3,2] row_mask:0xf bank_mask:0xf
	v_min_u32_dpp v36, v12, v12 quad_perm:[1,0,3,2] row_mask:0xf bank_mask:0xf
	v_max_u32_dpp v37, v12, v12 quad_perm:[1,0,3,2] row_mask:0xf bank_mask:0xf
	v_min_u32_dpp v38, v11, v11 quad_perm:[1,0,3,2] row_mask:0xf bank_mask:0xf
	v_max_u32_dpp v39, v11, v11 quad_perm:[1,0,3,2] row_mask:0xf bank_mask:0xf
	v_cndmask_b32_e64 v0, v25, v24, s[88:89]
	v_cndmask_b32_e64 v2, v27, v26, s[88:89]
	v_cndmask_b32_e64 v17, v29, v28, s[88:89]
	v_cndmask_b32_e64 v19, v31, v30, s[88:89]
	v_cndmask_b32_e64 v18, v33, v32, s[88:89]
	v_cndmask_b32_e64 v21, v35, v34, s[88:89]
	v_cndmask_b32_e64 v12, v37, v36, s[88:89]
	v_cndmask_b32_e64 v11, v39, v38, s[88:89]
	s_nop 1
	v_min_u32_dpp v24, v8, v8 quad_perm:[1,0,3,2] row_mask:0xf bank_mask:0xf
	v_max_u32_dpp v25, v8, v8 quad_perm:[1,0,3,2] row_mask:0xf bank_mask:0xf
	v_min_u32_dpp v26, v10, v10 quad_perm:[1,0,3,2] row_mask:0xf bank_mask:0xf
	v_max_u32_dpp v27, v10, v10 quad_perm:[1,0,3,2] row_mask:0xf bank_mask:0xf
	v_min_u32_dpp v28, v9, v9 quad_perm:[1,0,3,2] row_mask:0xf bank_mask:0xf
	v_max_u32_dpp v29, v9, v9 quad_perm:[1,0,3,2] row_mask:0xf bank_mask:0xf
	v_min_u32_dpp v30, v14, v14 quad_perm:[1,0,3,2] row_mask:0xf bank_mask:0xf
	v_max_u32_dpp v31, v14, v14 quad_perm:[1,0,3,2] row_mask:0xf bank_mask:0xf
	v_min_u32_dpp v32, v22, v22 quad_perm:[1,0,3,2] row_mask:0xf bank_mask:0xf
	v_max_u32_dpp v33, v22, v22 quad_perm:[1,0,3,2] row_mask:0xf bank_mask:0xf
	v_min_u32_dpp v34, v13, v13 quad_perm:[1,0,3,2] row_mask:0xf bank_mask:0xf
	v_max_u32_dpp v35, v13, v13 quad_perm:[1,0,3,2] row_mask:0xf bank_mask:0xf
	v_min_u32_dpp v36, v7, v7 quad_perm:[1,0,3,2] row_mask:0xf bank_mask:0xf
	v_max_u32_dpp v37, v7, v7 quad_perm:[1,0,3,2] row_mask:0xf bank_mask:0xf
	v_min_u32_dpp v38, v15, v15 quad_perm:[1,0,3,2] row_mask:0xf bank_mask:0xf
	v_max_u32_dpp v39, v15, v15 quad_perm:[1,0,3,2] row_mask:0xf bank_mask:0xf
	v_cndmask_b32_e64 v8, v25, v24, s[88:89]
	v_cndmask_b32_e64 v10, v27, v26, s[88:89]
	v_cndmask_b32_e64 v9, v29, v28, s[88:89]
	v_cndmask_b32_e64 v14, v31, v30, s[88:89]
	v_cndmask_b32_e64 v22, v33, v32, s[88:89]
	v_cndmask_b32_e64 v13, v35, v34, s[88:89]
	v_cndmask_b32_e64 v7, v37, v36, s[88:89]
	v_cndmask_b32_e64 v15, v39, v38, s[88:89]
	s_nop 1
	v_min_u32_e32 v16, v0, v8
	v_min_u32_e32 v4, v2, v10
	v_min_u32_e32 v1, v17, v9
	v_min_u32_e32 v3, v19, v14
	v_min_u32_e32 v20, v18, v22
	v_min_u32_e32 v6, v21, v13
	v_min_u32_e32 v5, v12, v7
	v_min_u32_e32 v23, v11, v15
	v_max_u32_e32 v8, v0, v8
	v_max_u32_e32 v10, v2, v10
	v_max_u32_e32 v9, v17, v9
	v_max_u32_e32 v14, v19, v14
	v_max_u32_e32 v22, v18, v22
	v_max_u32_e32 v13, v21, v13
	v_max_u32_e32 v7, v12, v7
	v_max_u32_e32 v15, v11, v15
	v_min_u32_e32 v0, v16, v20
	v_min_u32_e32 v2, v4, v6
	v_min_u32_e32 v17, v1, v5
	v_min_u32_e32 v19, v3, v23
	v_min_u32_e32 v18, v8, v22
	v_min_u32_e32 v21, v10, v13
	v_min_u32_e32 v12, v9, v7
	v_min_u32_e32 v11, v14, v15
	v_max_u32_e32 v20, v16, v20
	v_max_u32_e32 v6, v4, v6
	v_max_u32_e32 v5, v1, v5
	v_max_u32_e32 v23, v3, v23
	v_max_u32_e32 v22, v8, v22
	v_max_u32_e32 v13, v10, v13
	v_max_u32_e32 v7, v9, v7
	v_max_u32_e32 v15, v14, v15
	v_min_u32_e32 v16, v0, v17
	v_min_u32_e32 v4, v2, v19
	v_min_u32_e32 v1, v20, v5
	v_min_u32_e32 v3, v6, v23
	v_min_u32_e32 v8, v18, v12
	v_min_u32_e32 v10, v21, v11
	v_min_u32_e32 v9, v22, v7
	v_min_u32_e32 v14, v13, v15
	v_max_u32_e32 v17, v0, v17
	v_max_u32_e32 v19, v2, v19
	v_max_u32_e32 v5, v20, v5
	v_max_u32_e32 v23, v6, v23
	v_max_u32_e32 v12, v18, v12
	v_max_u32_e32 v11, v21, v11
	v_max_u32_e32 v7, v22, v7
	v_max_u32_e32 v15, v13, v15
	v_min_u32_e32 v0, v16, v4
	v_min_u32_e32 v2, v17, v19
	v_min_u32_e32 v20, v1, v3
	v_min_u32_e32 v6, v5, v23
	v_min_u32_e32 v18, v8, v10
	v_min_u32_e32 v21, v12, v11
	v_min_u32_e32 v22, v9, v14
	v_min_u32_e32 v13, v7, v15
	v_max_u32_e32 v4, v16, v4
	v_max_u32_e32 v19, v17, v19
	v_max_u32_e32 v3, v1, v3
	v_max_u32_e32 v23, v5, v23
	v_max_u32_e32 v10, v8, v10
	v_max_u32_e32 v11, v12, v11
	v_max_u32_e32 v14, v9, v14
	v_max_u32_e32 v15, v7, v15
	ds_write_b32 v41, v0 offset:0
	ds_write_b32 v41, v4 offset:64
	ds_write_b32 v41, v2 offset:128
	ds_write_b32 v41, v19 offset:192
	ds_write_b32 v41, v20 offset:256
	ds_write_b32 v41, v3 offset:320
	ds_write_b32 v41, v6 offset:384
	ds_write_b32 v41, v23 offset:448
	ds_write_b32 v41, v18 offset:4
	ds_write_b32 v41, v10 offset:68
	ds_write_b32 v41, v21 offset:132
	ds_write_b32 v41, v11 offset:196
	ds_write_b32 v41, v22 offset:260
	ds_write_b32 v41, v14 offset:324
	ds_write_b32 v41, v13 offset:388
	ds_write_b32 v41, v15 offset:452
	global_load_dwordx4 v[0:3], v40, s[82:83] offset:0
	global_load_dwordx4 v[4:7], v40, s[82:83] offset:16
	global_load_dwordx4 v[8:11], v40, s[82:83] offset:32
	global_load_dwordx4 v[12:15], v40, s[82:83] offset:48
	s_waitcnt vmcnt(0)
; DEV void sort_lists(int lane, int& myi0, int& myi1, float& myg0, float& myg1) {
; #pragma unroll
;     for (int k = 2; k <= 128; k <<= 1) {
; #pragma unroll
;       for (int j = k >> 1; j >= 1; j >>= 1) {
;         if (j == 64) {
;           const bool sw_ = myi1 < myi0;
;           const int ti = sw_ ? myi1 : myi0, tj = sw_ ? myi0 : myi1; const float tg = sw_ ? myg1 : myg0, th = sw_ ? myg0 : myg1;
;           myi0 = ti; myi1 = tj; myg0 = tg; myg1 = th;
;         } else {
;           const bool lower = (lane & j) == 0;
;           {
;             const bool up = (k == 128) ? true : ((k == 64) ? true : ((lane & k) == 0));
;             const int oi = __shfl_xor(myi0, j); const float og = __shfl_xor(myg0, j);
;             const bool take = (lower == up) ? (oi < myi0) : (oi > myi0);
;             myi0 = take ? oi : myi0; myg0 = take ? og : myg0;
;           }
;           {
;             const bool up = (k == 128) ? true : ((k == 64) ? false : ((lane & k) == 0));
;             const int oi = __shfl_xor(myi1, j); const float og = __shfl_xor(myg1, j);
;             const bool take = (lower == up) ? (oi < myi1) : (oi > myi1);
;             myi1 = take ? oi : myi1; myg1 = take ? og : myg1;
;           }
;         }
;       }
;     }
; }
	v_lshl_or_b32 v0, v0, 7, v235
	v_lshl_or_b32 v1, v1, 7, v235
	v_lshl_or_b32 v2, v2, 7, v235
	v_lshl_or_b32 v3, v3, 7, v235
	v_lshl_or_b32 v4, v4, 7, v235
	v_lshl_or_b32 v5, v5, 7, v235
	v_lshl_or_b32 v6, v6, 7, v235
	v_lshl_or_b32 v7, v7, 7, v235
	v_lshl_or_b32 v8, v8, 7, v235
	v_lshl_or_b32 v9, v9, 7, v235
	v_lshl_or_b32 v10, v10, 7, v235
	v_lshl_or_b32 v11, v11, 7, v235
	v_lshl_or_b32 v12, v12, 7, v235
	v_lshl_or_b32 v13, v13, 7, v235
	v_lshl_or_b32 v14, v14, 7, v235
	v_lshl_or_b32 v15, v15, 7, v235
	v_or_b32_e32 v1, 1, v1
	v_or_b32_e32 v2, 2, v2
	v_or_b32_e32 v3, 3, v3
	v_or_b32_e32 v4, 4, v4
	v_or_b32_e32 v5, 5, v5
	v_or_b32_e32 v6, 6, v6
	v_or_b32_e32 v7, 7, v7
	v_or_b32_e32 v8, 8, v8
	v_or_b32_e32 v9, 9, v9
	v_or_b32_e32 v10, 10, v10
	v_or_b32_e32 v11, 11, v11
	v_or_b32_e32 v12, 12, v12
	v_or_b32_e32 v13, 13, v13
	v_or_b32_e32 v14, 14, v14
	v_or_b32_e32 v15, 15, v15
	v_min_u32_e32 v16, v0, v1
	v_min_u32_e32 v17, v2, v3
	v_min_u32_e32 v18, v4, v5
	v_min_u32_e32 v19, v6, v7
	v_min_u32_e32 v20, v8, v9
	v_min_u32_e32 v21, v10, v11
	v_min_u32_e32 v22, v12, v13
	v_min_u32_e32 v23, v14, v15
	v_max_u32_e32 v1, v0, v1
	v_max_u32_e32 v3, v2, v3
	v_max_u32_e32 v5, v4, v5
	v_max_u32_e32 v7, v6, v7
	v_max_u32_e32 v9, v8, v9
	v_max_u32_e32 v11, v10, v11
	v_max_u32_e32 v13, v12, v13
	v_max_u32_e32 v15, v14, v15
	v_min_u32_e32 v0, v16, v3
	v_min_u32_e32 v2, v1, v17
	v_min_u32_e32 v4, v18, v7
	v_min_u32_e32 v6, v5, v19
	v_min_u32_e32 v8, v20, v11
	v_min_u32_e32 v10, v9, v21
	v_min_u32_e32 v12, v22, v15
	v_min_u32_e32 v14, v13, v23
	v_max_u32_e32 v3, v16, v3
	v_max_u32_e32 v17, v1, v17
	v_max_u32_e32 v7, v18, v7
	v_max_u32_e32 v19, v5, v19
	v_max_u32_e32 v11, v20, v11
	v_max_u32_e32 v21, v9, v21
	v_max_u32_e32 v15, v22, v15
	v_max_u32_e32 v23, v13, v23
	v_min_u32_e32 v16, v0, v2
	v_min_u32_e32 v1, v17, v3
	v_min_u32_e32 v18, v4, v6
	v_min_u32_e32 v5, v19, v7
	v_min_u32_e32 v20, v8, v10
	v_min_u32_e32 v9, v21, v11
	v_min_u32_e32 v22, v12, v14
	v_min_u32_e32 v13, v23, v15
	v_max_u32_e32 v2, v0, v2
	v_max_u32_e32 v3, v17, v3
	v_max_u32_e32 v6, v4, v6
	v_max_u32_e32 v7, v19, v7
	v_max_u32_e32 v10, v8, v10
	v_max_u32_e32 v11, v21, v11
	v_max_u32_e32 v14, v12, v14
	v_max_u32_e32 v15, v23, v15
	v_min_u32_e32 v0, v16, v7
	v_min_u32_e32 v17, v2, v5
	v_min_u32_e32 v4, v1, v6
	v_min_u32_e32 v19, v3, v18
	v_min_u32_e32 v8, v20, v15
	v_min_u32_e32 v21, v10, v13
	v_min_u32_e32 v12, v9, v14
	v_min_u32_e32 v23, v11, v22
	v_max_u32_e32 v7, v16, v7
	v_max_u32_e32 v5, v2, v5
	v_max_u32_e32 v6, v1, v6
	v_max_u32_e32 v18, v3, v18
	v_max_u32_e32 v15, v20, v15
	v_max_u32_e32 v13, v10, v13
	v_max_u32_e32 v14, v9, v14
	v_max_u32_e32 v22, v11, v22
	v_min_u32_e32 v16, v0, v4
	v_min_u32_e32 v2, v17, v19
	v_min_u32_e32 v1, v18, v5
	v_min_u32_e32 v3, v6, v7
	v_min_u32_e32 v20, v8, v12
	v_min_u32_e32 v10, v21, v23
	v_min_u32_e32 v9, v22, v13
	v_min_u32_e32 v11, v14, v15
	v_max_u32_e32 v4, v0, v4
	v_max_u32_e32 v19, v17, v19
	v_max_u32_e32 v5, v18, v5
	v_max_u32_e32 v7, v6, v7
	v_max_u32_e32 v12, v8, v12
	v_max_u32_e32 v23, v21, v23
	v_max_u32_e32 v13, v22, v13
	v_max_u32_e32 v15, v14, v15
	v_min_u32_e32 v0, v16, v2
	v_min_u32_e32 v17, v4, v19
	v_min_u32_e32 v18, v1, v3
	v_min_u32_e32 v6, v5, v7
	v_min_u32_e32 v8, v20, v10
	v_min_u32_e32 v21, v12, v23
	v_min_u32_e32 v22, v9, v11
	v_min_u32_e32 v14, v13, v15
	v_max_u32_e32 v2, v16, v2
	v_max_u32_e32 v19, v4, v19
	v_max_u32_e32 v3, v1, v3
	v_max_u32_e32 v7, v5, v7
	v_max_u32_e32 v10, v20, v10
	v_max_u32_e32 v23, v12, v23
	v_max_u32_e32 v11, v9, v11
	v_max_u32_e32 v15, v13, v15
	v_min_u32_e32 v16, v0, v15
	v_min_u32_e32 v4, v2, v14
	v_min_u32_e32 v1, v17, v11
	v_min_u32_e32 v5, v19, v22
	v_min_u32_e32 v20, v18, v23
	v_min_u32_e32 v12, v3, v21
	v_min_u32_e32 v9, v6, v10
	v_min_u32_e32 v13, v7, v8
	v_max_u32_e32 v15, v0, v15
	v_max_u32_e32 v14, v2, v14
	v_max_u32_e32 v11, v17, v11
	v_max_u32_e32 v22, v19, v22
	v_max_u32_e32 v23, v18, v23
	v_max_u32_e32 v21, v3, v21
	v_max_u32_e32 v10, v6, v10
	v_max_u32_e32 v8, v7, v8
	v_min_u32_e32 v0, v16, v20
	v_min_u32_e32 v2, v4, v12
	v_min_u32_e32 v17, v1, v9
	v_min_u32_e32 v19, v5, v13
	v_min_u32_e32 v18, v8, v22
	v_min_u32_e32 v3, v10, v11
	v_min_u32_e32 v6, v21, v14
	v_min_u32_e32 v7, v23, v15
	v_max_u32_e32 v20, v16, v20
	v_max_u32_e32 v12, v4, v12
	v_max_u32_e32 v9, v1, v9
	v_max_u32_e32 v13, v5, v13
	v_max_u32_e32 v22, v8, v22
	v_max_u32_e32 v11, v10, v11
	v_max_u32_e32 v14, v21, v14
	v_max_u32_e32 v15, v23, v15
	v_min_u32_e32 v16, v0, v17
	v_min_u32_e32 v4, v2, v19
	v_min_u32_e32 v1, v20, v9
	v_min_u32_e32 v5, v12, v13
	v_min_u32_e32 v8, v18, v6
	v_min_u32_e32 v10, v3, v7
	v_min_u32_e32 v21, v22, v14
	v_min_u32_e32 v23, v11, v15
	v_max_u32_e32 v17, v0, v17
	v_max_u32_e32 v19, v2, v19
	v_max_u32_e32 v9, v20, v9
	v_max_u32_e32 v13, v12, v13
	v_max_u32_e32 v6, v18, v6
	v_max_u32_e32 v7, v3, v7
	v_max_u32_e32 v14, v22, v14
	v_max_u32_e32 v15, v11, v15
	v_min_u32_e32 v0, v16, v4
	v_min_u32_e32 v2, v17, v19
	v_min_u32_e32 v20, v1, v5
	v_min_u32_e32 v12, v9, v13
	v_min_u32_e32 v18, v8, v10
	v_min_u32_e32 v3, v6, v7
	v_min_u32_e32 v22, v21, v23
	v_min_u32_e32 v11, v14, v15
	v_max_u32_e32 v4, v16, v4
	v_max_u32_e32 v19, v17, v19
	v_max_u32_e32 v5, v1, v5
	v_max_u32_e32 v13, v9, v13
	v_max_u32_e32 v10, v8, v10
	v_max_u32_e32 v7, v6, v7
	v_max_u32_e32 v23, v21, v23
	v_max_u32_e32 v15, v14, v15
	s_mov_b32 s88, 0x55555555
	s_mov_b32 s89, 0x55555555
	s_nop 1
	v_min_u32_dpp v24, v15, v0 quad_perm:[1,0,3,2] row_mask:0xf bank_mask:0xf
	v_max_u32_dpp v25, v15, v0 quad_perm:[1,0,3,2] row_mask:0xf bank_mask:0xf
	v_min_u32_dpp v26, v0, v15 quad_perm:[1,0,3,2] row_mask:0xf bank_mask:0xf
; DEV void sort_lists(int lane, int& myi0, int& myi1, float& myg0, float& myg1) {
; #pragma unroll
;     for (int k = 2; k <= 128; k <<= 1) {
; #pragma unroll
;       for (int j = k >> 1; j >= 1; j >>= 1) {
;         if (j == 64) {
;           const bool sw_ = myi1 < myi0;
;           const int ti = sw_ ? myi1 : myi0, tj = sw_ ? myi0 : myi1; const float tg = sw_ ? myg1 : myg0, th = sw_ ? myg0 : myg1;
;           myi0 = ti; myi1 = tj; myg0 = tg; myg1 = th;
;         } else {
;           const bool lower = (lane & j) == 0;
;           {
;             const bool up = (k == 128) ? true : ((k == 64) ? true : ((lane & k) == 0));
;             const int oi = __shfl_xor(myi0, j); const float og = __shfl_xor(myg0, j);
;             const bool take = (lower == up) ? (oi < myi0) : (oi > myi0);
;             myi0 = take ? oi : myi0; myg0 = take ? og : myg0;
;           }
;           {
;             const bool up = (k == 128) ? true : ((k == 64) ? false : ((lane & k) == 0));
;             const int oi = __shfl_xor(myi1, j); const float og = __shfl_xor(myg1, j);
;             const bool take = (lower == up) ? (oi < myi1) : (oi > myi1);
;             myi1 = take ? oi : myi1; myg1 = take ? og : myg1;
;           }
;         }
;       }
;     }
; }
	v_max_u32_dpp v27, v0, v15 quad_perm:[1,0,3,2] row_mask:0xf bank_mask:0xf
	v_min_u32_dpp v28, v11, v4 quad_perm:[1,0,3,2] row_mask:0xf bank_mask:0xf
	v_max_u32_dpp v29, v11, v4 quad_perm:[1,0,3,2] row_mask:0xf bank_mask:0xf
	v_min_u32_dpp v30, v4, v11 quad_perm:[1,0,3,2] row_mask:0xf bank_mask:0xf
	v_max_u32_dpp v31, v4, v11 quad_perm:[1,0,3,2] row_mask:0xf bank_mask:0xf
	v_min_u32_dpp v32, v23, v2 quad_perm:[1,0,3,2] row_mask:0xf bank_mask:0xf
	v_max_u32_dpp v33, v23, v2 quad_perm:[1,0,3,2] row_mask:0xf bank_mask:0xf
	v_min_u32_dpp v34, v2, v23 quad_perm:[1,0,3,2] row_mask:0xf bank_mask:0xf
	v_max_u32_dpp v35, v2, v23 quad_perm:[1,0,3,2] row_mask:0xf bank_mask:0xf
	v_min_u32_dpp v36, v22, v19 quad_perm:[1,0,3,2] row_mask:0xf bank_mask:0xf
	v_max_u32_dpp v37, v22, v19 quad_perm:[1,0,3,2] row_mask:0xf bank_mask:0xf
	v_min_u32_dpp v38, v19, v22 quad_perm:[1,0,3,2] row_mask:0xf bank_mask:0xf
	v_max_u32_dpp v39, v19, v22 quad_perm:[1,0,3,2] row_mask:0xf bank_mask:0xf
	v_cndmask_b32_e64 v0, v25, v24, s[88:89]
	v_cndmask_b32_e64 v15, v27, v26, s[88:89]
	v_cndmask_b32_e64 v4, v29, v28, s[88:89]
	v_cndmask_b32_e64 v11, v31, v30, s[88:89]
	v_cndmask_b32_e64 v2, v33, v32, s[88:89]
	v_cndmask_b32_e64 v23, v35, v34, s[88:89]
	v_cndmask_b32_e64 v19, v37, v36, s[88:89]
	v_cndmask_b32_e64 v22, v39, v38, s[88:89]
	s_nop 1
	v_min_u32_dpp v24, v7, v20 quad_perm:[1,0,3,2] row_mask:0xf bank_mask:0xf
	v_max_u32_dpp v25, v7, v20 quad_perm:[1,0,3,2] row_mask:0xf bank_mask:0xf
	v_min_u32_dpp v26, v20, v7 quad_perm:[1,0,3,2] row_mask:0xf bank_mask:0xf
	v_max_u32_dpp v27, v20, v7 quad_perm:[1,0,3,2] row_mask:0xf bank_mask:0xf
	v_min_u32_dpp v28, v3, v5 quad_perm:[1,0,3,2] row_mask:0xf bank_mask:0xf
	v_max_u32_dpp v29, v3, v5 quad_perm:[1,0,3,2] row_mask:0xf bank_mask:0xf
	v_min_u32_dpp v30, v5, v3 quad_perm:[1,0,3,2] row_mask:0xf bank_mask:0xf
	v_max_u32_dpp v31, v5, v3 quad_perm:[1,0,3,2] row_mask:0xf bank_mask:0xf
	v_min_u32_dpp v32, v10, v12 quad_perm:[1,0,3,2] row_mask:0xf bank_mask:0xf
	v_max_u32_dpp v33, v10, v12 quad_perm:[1,0,3,2] row_mask:0xf bank_mask:0xf
	v_min_u32_dpp v34, v12, v10 quad_perm:[1,0,3,2] row_mask:0xf bank_mask:0xf
	v_max_u32_dpp v35, v12, v10 quad_perm:[1,0,3,2] row_mask:0xf bank_mask:0xf
	v_min_u32_dpp v36, v18, v13 quad_perm:[1,0,3,2] row_mask:0xf bank_mask:0xf
	v_max_u32_dpp v37, v18, v13 quad_perm:[1,0,3,2] row_mask:0xf bank_mask:0xf
	v_min_u32_dpp v38, v13, v18 quad_perm:[1,0,3,2] row_mask:0xf bank_mask:0xf
	v_max_u32_dpp v39, v13, v18 quad_perm:[1,0,3,2] row_mask:0xf bank_mask:0xf
	v_cndmask_b32_e64 v20, v25, v24, s[88:89]
	v_cndmask_b32_e64 v7, v27, v26, s[88:89]
	v_cndmask_b32_e64 v5, v29, v28, s[88:89]
	v_cndmask_b32_e64 v3, v31, v30, s[88:89]
	v_cndmask_b32_e64 v12, v33, v32, s[88:89]
	v_cndmask_b32_e64 v10, v35, v34, s[88:89]
	v_cndmask_b32_e64 v13, v37, v36, s[88:89]
	v_cndmask_b32_e64 v18, v39, v38, s[88:89]
	s_nop 1
	v_min_u32_e32 v16, v0, v18
	v_min_u32_e32 v17, v4, v10
	v_min_u32_e32 v1, v2, v3
	v_min_u32_e32 v9, v19, v7
	v_min_u32_e32 v8, v20, v22
	v_min_u32_e32 v6, v5, v23
	v_min_u32_e32 v21, v12, v11
	v_min_u32_e32 v14, v13, v15
	v_max_u32_e32 v18, v0, v18
	v_max_u32_e32 v10, v4, v10
	v_max_u32_e32 v3, v2, v3
	v_max_u32_e32 v7, v19, v7
	v_max_u32_e32 v22, v20, v22
	v_max_u32_e32 v23, v5, v23
	v_max_u32_e32 v11, v12, v11
	v_max_u32_e32 v15, v13, v15
	v_min_u32_e32 v0, v16, v8
	v_min_u32_e32 v4, v17, v6
	v_min_u32_e32 v2, v1, v21
	v_min_u32_e32 v19, v9, v14
	v_min_u32_e32 v20, v18, v22
	v_min_u32_e32 v5, v10, v23
	v_min_u32_e32 v12, v3, v11
	v_min_u32_e32 v13, v7, v15
	v_max_u32_e32 v8, v16, v8
	v_max_u32_e32 v6, v17, v6
	v_max_u32_e32 v21, v1, v21
	v_max_u32_e32 v14, v9, v14
	v_max_u32_e32 v22, v18, v22
	v_max_u32_e32 v23, v10, v23
	v_max_u32_e32 v11, v3, v11
	v_max_u32_e32 v15, v7, v15
	v_min_u32_e32 v16, v0, v2
	v_min_u32_e32 v17, v4, v19
	v_min_u32_e32 v1, v8, v21
	v_min_u32_e32 v9, v6, v14
	v_min_u32_e32 v18, v20, v12
	v_min_u32_e32 v10, v5, v13
	v_min_u32_e32 v3, v22, v11
	v_min_u32_e32 v7, v23, v15
	v_max_u32_e32 v2, v0, v2
	v_max_u32_e32 v19, v4, v19
	v_max_u32_e32 v21, v8, v21
	v_max_u32_e32 v14, v6, v14
	v_max_u32_e32 v12, v20, v12
	v_max_u32_e32 v13, v5, v13
	v_max_u32_e32 v11, v22, v11
	v_max_u32_e32 v15, v23, v15
	v_min_u32_e32 v0, v16, v17
	v_min_u32_e32 v4, v2, v19
	v_min_u32_e32 v8, v1, v9
	v_min_u32_e32 v6, v21, v14
	v_min_u32_e32 v20, v18, v10
	v_min_u32_e32 v5, v12, v13
	v_min_u32_e32 v22, v3, v7
	v_min_u32_e32 v23, v11, v15
	v_max_u32_e32 v17, v16, v17
	v_max_u32_e32 v19, v2, v19
	v_max_u32_e32 v9, v1, v9
	v_max_u32_e32 v14, v21, v14
	v_max_u32_e32 v10, v18, v10
	v_max_u32_e32 v13, v12, v13
	v_max_u32_e32 v7, v3, v7
	v_max_u32_e32 v15, v11, v15
	s_mov_b32 s88, 0x33333333
	s_mov_b32 s89, 0x33333333
	s_nop 1
	v_min_u32_dpp v24, v15, v0 quad_perm:[3,2,1,0] row_mask:0xf bank_mask:0xf
	v_max_u32_dpp v25, v15, v0 quad_perm:[3,2,1,0] row_mask:0xf bank_mask:0xf
	v_min_u32_dpp v26, v0, v15 quad_perm:[3,2,1,0] row_mask:0xf bank_mask:0xf
	v_max_u32_dpp v27, v0, v15 quad_perm:[3,2,1,0] row_mask:0xf bank_mask:0xf
	v_min_u32_dpp v28, v23, v17 quad_perm:[3,2,1,0] row_mask:0xf bank_mask:0xf
	v_max_u32_dpp v29, v23, v17 quad_perm:[3,2,1,0] row_mask:0xf bank_mask:0xf
	v_min_u32_dpp v30, v17, v23 quad_perm:[3,2,1,0] row_mask:0xf bank_mask:0xf
	v_max_u32_dpp v31, v17, v23 quad_perm:[3,2,1,0] row_mask:0xf bank_mask:0xf
	v_min_u32_dpp v32, v7, v4 quad_perm:[3,2,1,0] row_mask:0xf bank_mask:0xf
	v_max_u32_dpp v33, v7, v4 quad_perm:[3,2,1,0] row_mask:0xf bank_mask:0xf
	v_min_u32_dpp v34, v4, v7 quad_perm:[3,2,1,0] row_mask:0xf bank_mask:0xf
	v_max_u32_dpp v35, v4, v7 quad_perm:[3,2,1,0] row_mask:0xf bank_mask:0xf
; DEV void sort_lists(int lane, int& myi0, int& myi1, float& myg0, float& myg1) {
; #pragma unroll
;     for (int k = 2; k <= 128; k <<= 1) {
; #pragma unroll
;       for (int j = k >> 1; j >= 1; j >>= 1) {
;         if (j == 64) {
;           const bool sw_ = myi1 < myi0;
;           const int ti = sw_ ? myi1 : myi0, tj = sw_ ? myi0 : myi1; const float tg = sw_ ? myg1 : myg0, th = sw_ ? myg0 : myg1;
;           myi0 = ti; myi1 = tj; myg0 = tg; myg1 = th;
;         } else {
;           const bool lower = (lane & j) == 0;
;           {
;             const bool up = (k == 128) ? true : ((k == 64) ? true : ((lane & k) == 0));
;             const int oi = __shfl_xor(myi0, j); const float og = __shfl_xor(myg0, j);
;             const bool take = (lower == up) ? (oi < myi0) : (oi > myi0);
;             myi0 = take ? oi : myi0; myg0 = take ? og : myg0;
;           }
;           {
;             const bool up = (k == 128) ? true : ((k == 64) ? false : ((lane & k) == 0));
;             const int oi = __shfl_xor(myi1, j); const float og = __shfl_xor(myg1, j);
;             const bool take = (lower == up) ? (oi < myi1) : (oi > myi1);
;             myi1 = take ? oi : myi1; myg1 = take ? og : myg1;
;           }
;         }
;       }
;     }
; }
	v_min_u32_dpp v36, v22, v19 quad_perm:[3,2,1,0] row_mask:0xf bank_mask:0xf
	v_max_u32_dpp v37, v22, v19 quad_perm:[3,2,1,0] row_mask:0xf bank_mask:0xf
	v_min_u32_dpp v38, v19, v22 quad_perm:[3,2,1,0] row_mask:0xf bank_mask:0xf
	v_max_u32_dpp v39, v19, v22 quad_perm:[3,2,1,0] row_mask:0xf bank_mask:0xf
	v_cndmask_b32_e64 v0, v25, v24, s[88:89]
	v_cndmask_b32_e64 v15, v27, v26, s[88:89]
	v_cndmask_b32_e64 v17, v29, v28, s[88:89]
	v_cndmask_b32_e64 v23, v31, v30, s[88:89]
	v_cndmask_b32_e64 v4, v33, v32, s[88:89]
	v_cndmask_b32_e64 v7, v35, v34, s[88:89]
	v_cndmask_b32_e64 v19, v37, v36, s[88:89]
	v_cndmask_b32_e64 v22, v39, v38, s[88:89]
	s_nop 1
	v_min_u32_dpp v24, v13, v8 quad_perm:[3,2,1,0] row_mask:0xf bank_mask:0xf
	v_max_u32_dpp v25, v13, v8 quad_perm:[3,2,1,0] row_mask:0xf bank_mask:0xf
	v_min_u32_dpp v26, v8, v13 quad_perm:[3,2,1,0] row_mask:0xf bank_mask:0xf
	v_max_u32_dpp v27, v8, v13 quad_perm:[3,2,1,0] row_mask:0xf bank_mask:0xf
	v_min_u32_dpp v28, v5, v9 quad_perm:[3,2,1,0] row_mask:0xf bank_mask:0xf
	v_max_u32_dpp v29, v5, v9 quad_perm:[3,2,1,0] row_mask:0xf bank_mask:0xf
	v_min_u32_dpp v30, v9, v5 quad_perm:[3,2,1,0] row_mask:0xf bank_mask:0xf
	v_max_u32_dpp v31, v9, v5 quad_perm:[3,2,1,0] row_mask:0xf bank_mask:0xf
	v_min_u32_dpp v32, v10, v6 quad_perm:[3,2,1,0] row_mask:0xf bank_mask:0xf
	v_max_u32_dpp v33, v10, v6 quad_perm:[3,2,1,0] row_mask:0xf bank_mask:0xf
	v_min_u32_dpp v34, v6, v10 quad_perm:[3,2,1,0] row_mask:0xf bank_mask:0xf
	v_max_u32_dpp v35, v6, v10 quad_perm:[3,2,1,0] row_mask:0xf bank_mask:0xf
	v_min_u32_dpp v36, v20, v14 quad_perm:[3,2,1,0] row_mask:0xf bank_mask:0xf
	v_max_u32_dpp v37, v20, v14 quad_perm:[3,2,1,0] row_mask:0xf bank_mask:0xf
	v_min_u32_dpp v38, v14, v20 quad_perm:[3,2,1,0] row_mask:0xf bank_mask:0xf
	v_max_u32_dpp v39, v14, v20 quad_perm:[3,2,1,0] row_mask:0xf bank_mask:0xf
	v_cndmask_b32_e64 v8, v25, v24, s[88:89]
	v_cndmask_b32_e64 v13, v27, v26, s[88:89]
	v_cndmask_b32_e64 v9, v29, v28, s[88:89]
	v_cndmask_b32_e64 v5, v31, v30, s[88:89]
	v_cndmask_b32_e64 v6, v33, v32, s[88:89]
	v_cndmask_b32_e64 v10, v35, v34, s[88:89]
	v_cndmask_b32_e64 v14, v37, v36, s[88:89]
	v_cndmask_b32_e64 v20, v39, v38, s[88:89]
	s_nop 1
	s_mov_b32 s88, 0x55555555
	s_mov_b32 s89, 0x55555555
	s_nop 1
	v_min_u32_dpp v24, v0, v0 quad_perm:[1,0,3,2] row_mask:0xf bank_mask:0xf
	v_max_u32_dpp v25, v0, v0 quad_perm:[1,0,3,2] row_mask:0xf bank_mask:0xf
	v_min_u32_dpp v26, v17, v17 quad_perm:[1,0,3,2] row_mask:0xf bank_mask:0xf
	v_max_u32_dpp v27, v17, v17 quad_perm:[1,0,3,2] row_mask:0xf bank_mask:0xf
	v_min_u32_dpp v28, v4, v4 quad_perm:[1,0,3,2] row_mask:0xf bank_mask:0xf
	v_max_u32_dpp v29, v4, v4 quad_perm:[1,0,3,2] row_mask:0xf bank_mask:0xf
	v_min_u32_dpp v30, v19, v19 quad_perm:[1,0,3,2] row_mask:0xf bank_mask:0xf
	v_max_u32_dpp v31, v19, v19 quad_perm:[1,0,3,2] row_mask:0xf bank_mask:0xf
	v_min_u32_dpp v32, v8, v8 quad_perm:[1,0,3,2] row_mask:0xf bank_mask:0xf
	v_max_u32_dpp v33, v8, v8 quad_perm:[1,0,3,2] row_mask:0xf bank_mask:0xf
	v_min_u32_dpp v34, v9, v9 quad_perm:[1,0,3,2] row_mask:0xf bank_mask:0xf
	v_max_u32_dpp v35, v9, v9 quad_perm:[1,0,3,2] row_mask:0xf bank_mask:0xf
	v_min_u32_dpp v36, v6, v6 quad_perm:[1,0,3,2] row_mask:0xf bank_mask:0xf
	v_max_u32_dpp v37, v6, v6 quad_perm:[1,0,3,2] row_mask:0xf bank_mask:0xf
	v_min_u32_dpp v38, v14, v14 quad_perm:[1,0,3,2] row_mask:0xf bank_mask:0xf
	v_max_u32_dpp v39, v14, v14 quad_perm:[1,0,3,2] row_mask:0xf bank_mask:0xf
	v_cndmask_b32_e64 v0, v25, v24, s[88:89]
	v_cndmask_b32_e64 v17, v27, v26, s[88:89]
	v_cndmask_b32_e64 v4, v29, v28, s[88:89]
	v_cndmask_b32_e64 v19, v31, v30, s[88:89]
	v_cndmask_b32_e64 v8, v33, v32, s[88:89]
	v_cndmask_b32_e64 v9, v35, v34, s[88:89]
	v_cndmask_b32_e64 v6, v37, v36, s[88:89]
	v_cndmask_b32_e64 v14, v39, v38, s[88:89]
	s_nop 1
	v_min_u32_dpp v24, v20, v20 quad_perm:[1,0,3,2] row_mask:0xf bank_mask:0xf
	v_max_u32_dpp v25, v20, v20 quad_perm:[1,0,3,2] row_mask:0xf bank_mask:0xf
	v_min_u32_dpp v26, v10, v10 quad_perm:[1,0,3,2] row_mask:0xf bank_mask:0xf
	v_max_u32_dpp v27, v10, v10 quad_perm:[1,0,3,2] row_mask:0xf bank_mask:0xf
	v_min_u32_dpp v28, v5, v5 quad_perm:[1,0,3,2] row_mask:0xf bank_mask:0xf
	v_max_u32_dpp v29, v5, v5 quad_perm:[1,0,3,2] row_mask:0xf bank_mask:0xf
	v_min_u32_dpp v30, v13, v13 quad_perm:[1,0,3,2] row_mask:0xf bank_mask:0xf
	v_max_u32_dpp v31, v13, v13 quad_perm:[1,0,3,2] row_mask:0xf bank_mask:0xf
	v_min_u32_dpp v32, v22, v22 quad_perm:[1,0,3,2] row_mask:0xf bank_mask:0xf
	v_max_u32_dpp v33, v22, v22 quad_perm:[1,0,3,2] row_mask:0xf bank_mask:0xf
	v_min_u32_dpp v34, v7, v7 quad_perm:[1,0,3,2] row_mask:0xf bank_mask:0xf
	v_max_u32_dpp v35, v7, v7 quad_perm:[1,0,3,2] row_mask:0xf bank_mask:0xf
	v_min_u32_dpp v36, v23, v23 quad_perm:[1,0,3,2] row_mask:0xf bank_mask:0xf
	v_max_u32_dpp v37, v23, v23 quad_perm:[1,0,3,2] row_mask:0xf bank_mask:0xf
	v_min_u32_dpp v38, v15, v15 quad_perm:[1,0,3,2] row_mask:0xf bank_mask:0xf
	v_max_u32_dpp v39, v15, v15 quad_perm:[1,0,3,2] row_mask:0xf bank_mask:0xf
	v_cndmask_b32_e64 v20, v25, v24, s[88:89]
	v_cndmask_b32_e64 v10, v27, v26, s[88:89]
	v_cndmask_b32_e64 v5, v29, v28, s[88:89]
	v_cndmask_b32_e64 v13, v31, v30, s[88:89]
	v_cndmask_b32_e64 v22, v33, v32, s[88:89]
	v_cndmask_b32_e64 v7, v35, v34, s[88:89]
	v_cndmask_b32_e64 v23, v37, v36, s[88:89]
	v_cndmask_b32_e64 v15, v39, v38, s[88:89]
	s_nop 1
	v_min_u32_e32 v16, v0, v20
	v_min_u32_e32 v2, v17, v10
	v_min_u32_e32 v1, v4, v5
	v_min_u32_e32 v21, v19, v13
	v_min_u32_e32 v18, v8, v22
	v_min_u32_e32 v12, v9, v7
	v_min_u32_e32 v3, v6, v23
	v_min_u32_e32 v11, v14, v15
	v_max_u32_e32 v20, v0, v20
	v_max_u32_e32 v10, v17, v10
; DEV void sort_lists(int lane, int& myi0, int& myi1, float& myg0, float& myg1) {
; #pragma unroll
;     for (int k = 2; k <= 128; k <<= 1) {
; #pragma unroll
;       for (int j = k >> 1; j >= 1; j >>= 1) {
;         if (j == 64) {
;           const bool sw_ = myi1 < myi0;
;           const int ti = sw_ ? myi1 : myi0, tj = sw_ ? myi0 : myi1; const float tg = sw_ ? myg1 : myg0, th = sw_ ? myg0 : myg1;
;           myi0 = ti; myi1 = tj; myg0 = tg; myg1 = th;
;         } else {
;           const bool lower = (lane & j) == 0;
;           {
;             const bool up = (k == 128) ? true : ((k == 64) ? true : ((lane & k) == 0));
;             const int oi = __shfl_xor(myi0, j); const float og = __shfl_xor(myg0, j);
;             const bool take = (lower == up) ? (oi < myi0) : (oi > myi0);
;             myi0 = take ? oi : myi0; myg0 = take ? og : myg0;
;           }
;           {
;             const bool up = (k == 128) ? true : ((k == 64) ? false : ((lane & k) == 0));
;             const int oi = __shfl_xor(myi1, j); const float og = __shfl_xor(myg1, j);
;             const bool take = (lower == up) ? (oi < myi1) : (oi > myi1);
;             myi1 = take ? oi : myi1; myg1 = take ? og : myg1;
;           }
;         }
;       }
;     }
; }
	v_max_u32_e32 v5, v4, v5
	v_max_u32_e32 v13, v19, v13
	v_max_u32_e32 v22, v8, v22
	v_max_u32_e32 v7, v9, v7
	v_max_u32_e32 v23, v6, v23
	v_max_u32_e32 v15, v14, v15
	v_min_u32_e32 v0, v16, v18
	v_min_u32_e32 v17, v2, v12
	v_min_u32_e32 v4, v1, v3
	v_min_u32_e32 v19, v21, v11
	v_min_u32_e32 v8, v20, v22
	v_min_u32_e32 v9, v10, v7
	v_min_u32_e32 v6, v5, v23
	v_min_u32_e32 v14, v13, v15
	v_max_u32_e32 v18, v16, v18
	v_max_u32_e32 v12, v2, v12
	v_max_u32_e32 v3, v1, v3
	v_max_u32_e32 v11, v21, v11
	v_max_u32_e32 v22, v20, v22
	v_max_u32_e32 v7, v10, v7
	v_max_u32_e32 v23, v5, v23
	v_max_u32_e32 v15, v13, v15
	v_min_u32_e32 v16, v0, v4
	v_min_u32_e32 v2, v17, v19
	v_min_u32_e32 v1, v18, v3
	v_min_u32_e32 v21, v12, v11
	v_min_u32_e32 v20, v8, v6
	v_min_u32_e32 v10, v9, v14
	v_min_u32_e32 v5, v22, v23
	v_min_u32_e32 v13, v7, v15
	v_max_u32_e32 v4, v0, v4
	v_max_u32_e32 v19, v17, v19
	v_max_u32_e32 v3, v18, v3
	v_max_u32_e32 v11, v12, v11
	v_max_u32_e32 v6, v8, v6
	v_max_u32_e32 v14, v9, v14
	v_max_u32_e32 v23, v22, v23
	v_max_u32_e32 v15, v7, v15
	v_min_u32_e32 v0, v16, v2
	v_min_u32_e32 v17, v4, v19
	v_min_u32_e32 v18, v1, v21
	v_min_u32_e32 v12, v3, v11
	v_min_u32_e32 v8, v20, v10
	v_min_u32_e32 v9, v6, v14
	v_min_u32_e32 v22, v5, v13
	v_min_u32_e32 v7, v23, v15
	v_max_u32_e32 v2, v16, v2
	v_max_u32_e32 v19, v4, v19
	v_max_u32_e32 v21, v1, v21
	v_max_u32_e32 v11, v3, v11
	v_max_u32_e32 v10, v20, v10
	v_max_u32_e32 v14, v6, v14
	v_max_u32_e32 v13, v5, v13
	v_max_u32_e32 v15, v23, v15
	s_mov_b32 s88, 0xf0f0f0f
	s_mov_b32 s89, 0xf0f0f0f
	s_nop 1
	v_min_u32_dpp v24, v15, v0 row_half_mirror row_mask:0xf bank_mask:0xf
	v_max_u32_dpp v25, v15, v0 row_half_mirror row_mask:0xf bank_mask:0xf
	v_min_u32_dpp v26, v0, v15 row_half_mirror row_mask:0xf bank_mask:0xf
	v_max_u32_dpp v27, v0, v15 row_half_mirror row_mask:0xf bank_mask:0xf
	v_min_u32_dpp v28, v7, v2 row_half_mirror row_mask:0xf bank_mask:0xf
	v_max_u32_dpp v29, v7, v2 row_half_mirror row_mask:0xf bank_mask:0xf
	v_min_u32_dpp v30, v2, v7 row_half_mirror row_mask:0xf bank_mask:0xf
	v_max_u32_dpp v31, v2, v7 row_half_mirror row_mask:0xf bank_mask:0xf
	v_min_u32_dpp v32, v13, v17 row_half_mirror row_mask:0xf bank_mask:0xf
	v_max_u32_dpp v33, v13, v17 row_half_mirror row_mask:0xf bank_mask:0xf
	v_min_u32_dpp v34, v17, v13 row_half_mirror row_mask:0xf bank_mask:0xf
	v_max_u32_dpp v35, v17, v13 row_half_mirror row_mask:0xf bank_mask:0xf
	v_min_u32_dpp v36, v22, v19 row_half_mirror row_mask:0xf bank_mask:0xf
	v_max_u32_dpp v37, v22, v19 row_half_mirror row_mask:0xf bank_mask:0xf
	v_min_u32_dpp v38, v19, v22 row_half_mirror row_mask:0xf bank_mask:0xf
	v_max_u32_dpp v39, v19, v22 row_half_mirror row_mask:0xf bank_mask:0xf
	v_cndmask_b32_e64 v0, v25, v24, s[88:89]
	v_cndmask_b32_e64 v15, v27, v26, s[88:89]
	v_cndmask_b32_e64 v2, v29, v28, s[88:89]
	v_cndmask_b32_e64 v7, v31, v30, s[88:89]
	v_cndmask_b32_e64 v17, v33, v32, s[88:89]
	v_cndmask_b32_e64 v13, v35, v34, s[88:89]
	v_cndmask_b32_e64 v19, v37, v36, s[88:89]
	v_cndmask_b32_e64 v22, v39, v38, s[88:89]
	s_nop 1
	v_min_u32_dpp v24, v14, v18 row_half_mirror row_mask:0xf bank_mask:0xf
	v_max_u32_dpp v25, v14, v18 row_half_mirror row_mask:0xf bank_mask:0xf
	v_min_u32_dpp v26, v18, v14 row_half_mirror row_mask:0xf bank_mask:0xf
	v_max_u32_dpp v27, v18, v14 row_half_mirror row_mask:0xf bank_mask:0xf
	v_min_u32_dpp v28, v9, v21 row_half_mirror row_mask:0xf bank_mask:0xf
	v_max_u32_dpp v29, v9, v21 row_half_mirror row_mask:0xf bank_mask:0xf
	v_min_u32_dpp v30, v21, v9 row_half_mirror row_mask:0xf bank_mask:0xf
	v_max_u32_dpp v31, v21, v9 row_half_mirror row_mask:0xf bank_mask:0xf
	v_min_u32_dpp v32, v10, v12 row_half_mirror row_mask:0xf bank_mask:0xf
	v_max_u32_dpp v33, v10, v12 row_half_mirror row_mask:0xf bank_mask:0xf
	v_min_u32_dpp v34, v12, v10 row_half_mirror row_mask:0xf bank_mask:0xf
	v_max_u32_dpp v35, v12, v10 row_half_mirror row_mask:0xf bank_mask:0xf
	v_min_u32_dpp v36, v8, v11 row_half_mirror row_mask:0xf bank_mask:0xf
	v_max_u32_dpp v37, v8, v11 row_half_mirror row_mask:0xf bank_mask:0xf
	v_min_u32_dpp v38, v11, v8 row_half_mirror row_mask:0xf bank_mask:0xf
	v_max_u32_dpp v39, v11, v8 row_half_mirror row_mask:0xf bank_mask:0xf
	v_cndmask_b32_e64 v18, v25, v24, s[88:89]
	v_cndmask_b32_e64 v14, v27, v26, s[88:89]
	v_cndmask_b32_e64 v21, v29, v28, s[88:89]
	v_cndmask_b32_e64 v9, v31, v30, s[88:89]
	v_cndmask_b32_e64 v12, v33, v32, s[88:89]
	v_cndmask_b32_e64 v10, v35, v34, s[88:89]
	v_cndmask_b32_e64 v11, v37, v36, s[88:89]
	v_cndmask_b32_e64 v8, v39, v38, s[88:89]
	s_nop 1
	s_mov_b32 s88, 0x33333333
	s_mov_b32 s89, 0x33333333
	s_nop 1
	v_min_u32_dpp v24, v0, v0 quad_perm:[2,3,0,1] row_mask:0xf bank_mask:0xf
	v_max_u32_dpp v25, v0, v0 quad_perm:[2,3,0,1] row_mask:0xf bank_mask:0xf
	v_min_u32_dpp v26, v2, v2 quad_perm:[2,3,0,1] row_mask:0xf bank_mask:0xf
	v_max_u32_dpp v27, v2, v2 quad_perm:[2,3,0,1] row_mask:0xf bank_mask:0xf
	v_min_u32_dpp v28, v17, v17 quad_perm:[2,3,0,1] row_mask:0xf bank_mask:0xf
	v_max_u32_dpp v29, v17, v17 quad_perm:[2,3,0,1] row_mask:0xf bank_mask:0xf
	v_min_u32_dpp v30, v19, v19 quad_perm:[2,3,0,1] row_mask:0xf bank_mask:0xf
	v_max_u32_dpp v31, v19, v19 quad_perm:[2,3,0,1] row_mask:0xf bank_mask:0xf
	v_min_u32_dpp v32, v18, v18 quad_perm:[2,3,0,1] row_mask:0xf bank_mask:0xf
	v_max_u32_dpp v33, v18, v18 quad_perm:[2,3,0,1] row_mask:0xf bank_mask:0xf
	v_min_u32_dpp v34, v21, v21 quad_perm:[2,3,0,1] row_mask:0xf bank_mask:0xf
	v_max_u32_dpp v35, v21, v21 quad_perm:[2,3,0,1] row_mask:0xf bank_mask:0xf
	v_min_u32_dpp v36, v12, v12 quad_perm:[2,3,0,1] row_mask:0xf bank_mask:0xf
	v_max_u32_dpp v37, v12, v12 quad_perm:[2,3,0,1] row_mask:0xf bank_mask:0xf
; DEV void sort_lists(int lane, int& myi0, int& myi1, float& myg0, float& myg1) {
; #pragma unroll
;     for (int k = 2; k <= 128; k <<= 1) {
; #pragma unroll
;       for (int j = k >> 1; j >= 1; j >>= 1) {
;         if (j == 64) {
;           const bool sw_ = myi1 < myi0;
;           const int ti = sw_ ? myi1 : myi0, tj = sw_ ? myi0 : myi1; const float tg = sw_ ? myg1 : myg0, th = sw_ ? myg0 : myg1;
;           myi0 = ti; myi1 = tj; myg0 = tg; myg1 = th;
;         } else {
;           const bool lower = (lane & j) == 0;
;           {
;             const bool up = (k == 128) ? true : ((k == 64) ? true : ((lane & k) == 0));
;             const int oi = __shfl_xor(myi0, j); const float og = __shfl_xor(myg0, j);
;             const bool take = (lower == up) ? (oi < myi0) : (oi > myi0);
;             myi0 = take ? oi : myi0; myg0 = take ? og : myg0;
;           }
;           {
;             const bool up = (k == 128) ? true : ((k == 64) ? false : ((lane & k) == 0));
;             const int oi = __shfl_xor(myi1, j); const float og = __shfl_xor(myg1, j);
;             const bool take = (lower == up) ? (oi < myi1) : (oi > myi1);
;             myi1 = take ? oi : myi1; myg1 = take ? og : myg1;
;           }
;         }
;       }
;     }
; }
	v_min_u32_dpp v38, v11, v11 quad_perm:[2,3,0,1] row_mask:0xf bank_mask:0xf
	v_max_u32_dpp v39, v11, v11 quad_perm:[2,3,0,1] row_mask:0xf bank_mask:0xf
	v_cndmask_b32_e64 v0, v25, v24, s[88:89]
	v_cndmask_b32_e64 v2, v27, v26, s[88:89]
	v_cndmask_b32_e64 v17, v29, v28, s[88:89]
	v_cndmask_b32_e64 v19, v31, v30, s[88:89]
	v_cndmask_b32_e64 v18, v33, v32, s[88:89]
	v_cndmask_b32_e64 v21, v35, v34, s[88:89]
	v_cndmask_b32_e64 v12, v37, v36, s[88:89]
	v_cndmask_b32_e64 v11, v39, v38, s[88:89]
	s_nop 1
	v_min_u32_dpp v24, v8, v8 quad_perm:[2,3,0,1] row_mask:0xf bank_mask:0xf
	v_max_u32_dpp v25, v8, v8 quad_perm:[2,3,0,1] row_mask:0xf bank_mask:0xf
	v_min_u32_dpp v26, v10, v10 quad_perm:[2,3,0,1] row_mask:0xf bank_mask:0xf
	v_max_u32_dpp v27, v10, v10 quad_perm:[2,3,0,1] row_mask:0xf bank_mask:0xf
	v_min_u32_dpp v28, v9, v9 quad_perm:[2,3,0,1] row_mask:0xf bank_mask:0xf
	v_max_u32_dpp v29, v9, v9 quad_perm:[2,3,0,1] row_mask:0xf bank_mask:0xf
	v_min_u32_dpp v30, v14, v14 quad_perm:[2,3,0,1] row_mask:0xf bank_mask:0xf
	v_max_u32_dpp v31, v14, v14 quad_perm:[2,3,0,1] row_mask:0xf bank_mask:0xf
	v_min_u32_dpp v32, v22, v22 quad_perm:[2,3,0,1] row_mask:0xf bank_mask:0xf
	v_max_u32_dpp v33, v22, v22 quad_perm:[2,3,0,1] row_mask:0xf bank_mask:0xf
	v_min_u32_dpp v34, v13, v13 quad_perm:[2,3,0,1] row_mask:0xf bank_mask:0xf
	v_max_u32_dpp v35, v13, v13 quad_perm:[2,3,0,1] row_mask:0xf bank_mask:0xf
	v_min_u32_dpp v36, v7, v7 quad_perm:[2,3,0,1] row_mask:0xf bank_mask:0xf
	v_max_u32_dpp v37, v7, v7 quad_perm:[2,3,0,1] row_mask:0xf bank_mask:0xf
	v_min_u32_dpp v38, v15, v15 quad_perm:[2,3,0,1] row_mask:0xf bank_mask:0xf
	v_max_u32_dpp v39, v15, v15 quad_perm:[2,3,0,1] row_mask:0xf bank_mask:0xf
	v_cndmask_b32_e64 v8, v25, v24, s[88:89]
	v_cndmask_b32_e64 v10, v27, v26, s[88:89]
	v_cndmask_b32_e64 v9, v29, v28, s[88:89]
	v_cndmask_b32_e64 v14, v31, v30, s[88:89]
	v_cndmask_b32_e64 v22, v33, v32, s[88:89]
	v_cndmask_b32_e64 v13, v35, v34, s[88:89]
	v_cndmask_b32_e64 v7, v37, v36, s[88:89]
	v_cndmask_b32_e64 v15, v39, v38, s[88:89]
	s_nop 1
	s_mov_b32 s88, 0x55555555
	s_mov_b32 s89, 0x55555555
	s_nop 1
	v_min_u32_dpp v24, v0, v0 quad_perm:[1,0,3,2] row_mask:0xf bank_mask:0xf
	v_max_u32_dpp v25, v0, v0 quad_perm:[1,0,3,2] row_mask:0xf bank_mask:0xf
	v_min_u32_dpp v26, v2, v2 quad_perm:[1,0,3,2] row_mask:0xf bank_mask:0xf
	v_max_u32_dpp v27, v2, v2 quad_perm:[1,0,3,2] row_mask:0xf bank_mask:0xf
	v_min_u32_dpp v28, v17, v17 quad_perm:[1,0,3,2] row_mask:0xf bank_mask:0xf
	v_max_u32_dpp v29, v17, v17 quad_perm:[1,0,3,2] row_mask:0xf bank_mask:0xf
	v_min_u32_dpp v30, v19, v19 quad_perm:[1,0,3,2] row_mask:0xf bank_mask:0xf
	v_max_u32_dpp v31, v19, v19 quad_perm:[1,0,3,2] row_mask:0xf bank_mask:0xf
	v_min_u32_dpp v32, v18, v18 quad_perm:[1,0,3,2] row_mask:0xf bank_mask:0xf
	v_max_u32_dpp v33, v18, v18 quad_perm:[1,0,3,2] row_mask:0xf bank_mask:0xf
	v_min_u32_dpp v34, v21, v21 quad_perm:[1,0,3,2] row_mask:0xf bank_mask:0xf
	v_max_u32_dpp v35, v21, v21 quad_perm:[1,0,3,2] row_mask:0xf bank_mask:0xf
	v_min_u32_dpp v36, v12, v12 quad_perm:[1,0,3,2] row_mask:0xf bank_mask:0xf
	v_max_u32_dpp v37, v12, v12 quad_perm:[1,0,3,2] row_mask:0xf bank_mask:0xf
	v_min_u32_dpp v38, v11, v11 quad_perm:[1,0,3,2] row_mask:0xf bank_mask:0xf
	v_max_u32_dpp v39, v11, v11 quad_perm:[1,0,3,2] row_mask:0xf bank_mask:0xf
	v_cndmask_b32_e64 v0, v25, v24, s[88:89]
	v_cndmask_b32_e64 v2, v27, v26, s[88:89]
	v_cndmask_b32_e64 v17, v29, v28, s[88:89]
	v_cndmask_b32_e64 v19, v31, v30, s[88:89]
	v_cndmask_b32_e64 v18, v33, v32, s[88:89]
	v_cndmask_b32_e64 v21, v35, v34, s[88:89]
	v_cndmask_b32_e64 v12, v37, v36, s[88:89]
	v_cndmask_b32_e64 v11, v39, v38, s[88:89]
	s_nop 1
	v_min_u32_dpp v24, v8, v8 quad_perm:[1,0,3,2] row_mask:0xf bank_mask:0xf
	v_max_u32_dpp v25, v8, v8 quad_perm:[1,0,3,2] row_mask:0xf bank_mask:0xf
	v_min_u32_dpp v26, v10, v10 quad_perm:[1,0,3,2] row_mask:0xf bank_mask:0xf
	v_max_u32_dpp v27, v10, v10 quad_perm:[1,0,3,2] row_mask:0xf bank_mask:0xf
	v_min_u32_dpp v28, v9, v9 quad_perm:[1,0,3,2] row_mask:0xf bank_mask:0xf
	v_max_u32_dpp v29, v9, v9 quad_perm:[1,0,3,2] row_mask:0xf bank_mask:0xf
	v_min_u32_dpp v30, v14, v14 quad_perm:[1,0,3,2] row_mask:0xf bank_mask:0xf
	v_max_u32_dpp v31, v14, v14 quad_perm:[1,0,3,2] row_mask:0xf bank_mask:0xf
	v_min_u32_dpp v32, v22, v22 quad_perm:[1,0,3,2] row_mask:0xf bank_mask:0xf
	v_max_u32_dpp v33, v22, v22 quad_perm:[1,0,3,2] row_mask:0xf bank_mask:0xf
	v_min_u32_dpp v34, v13, v13 quad_perm:[1,0,3,2] row_mask:0xf bank_mask:0xf
	v_max_u32_dpp v35, v13, v13 quad_perm:[1,0,3,2] row_mask:0xf bank_mask:0xf
	v_min_u32_dpp v36, v7, v7 quad_perm:[1,0,3,2] row_mask:0xf bank_mask:0xf
	v_max_u32_dpp v37, v7, v7 quad_perm:[1,0,3,2] row_mask:0xf bank_mask:0xf
	v_min_u32_dpp v38, v15, v15 quad_perm:[1,0,3,2] row_mask:0xf bank_mask:0xf
	v_max_u32_dpp v39, v15, v15 quad_perm:[1,0,3,2] row_mask:0xf bank_mask:0xf
	v_cndmask_b32_e64 v8, v25, v24, s[88:89]
	v_cndmask_b32_e64 v10, v27, v26, s[88:89]
	v_cndmask_b32_e64 v9, v29, v28, s[88:89]
	v_cndmask_b32_e64 v14, v31, v30, s[88:89]
; #define PG_ISSUE(BUF, TAB, e0_) do { const int isrc_ = ((e0_) < 64) ? myi0 : myi1; \
;       _Pragma("unroll") for (int e = 0; e < 8; ++e) { const int idx_ = __builtin_amdgcn_readlane(isrc_, ((e0_) + e) & 63); \
;         BUF[e] = *(const u32x4*)((TAB) + (size_t)idx_ * 1024 + lane * 16); } } while (0)
; DEV void sort_lists(int lane, int& myi0, int& myi1, float& myg0, float& myg1) {
; #pragma unroll
;     for (int k = 2; k <= 128; k <<= 1) {
; #pragma unroll
;       for (int j = k >> 1; j >= 1; j >>= 1) {
;         if (j == 64) {
;           const bool sw_ = myi1 < myi0;
;           const int ti = sw_ ? myi1 : myi0, tj = sw_ ? myi0 : myi1; const float tg = sw_ ? myg1 : myg0, th = sw_ ? myg0 : myg1;
;           myi0 = ti; myi1 = tj; myg0 = tg; myg1 = th;
;         } else {
;           const bool lower = (lane & j) == 0;
;           {
;             const bool up = (k == 128) ? true : ((k == 64) ? true : ((lane & k) == 0));
;             const int oi = __shfl_xor(myi0, j); const float og = __shfl_xor(myg0, j);
;             const bool take = (lower == up) ? (oi < myi0) : (oi > myi0);
;             myi0 = take ? oi : myi0; myg0 = take ? og : myg0;
;           }
;           {
;             const bool up = (k == 128) ? true : ((k == 64) ? false : ((lane & k) == 0));
;             const int oi = __shfl_xor(myi1, j); const float og = __shfl_xor(myg1, j);
;             const bool take = (lower == up) ? (oi < myi1) : (oi > myi1);
;             myi1 = take ? oi : myi1; myg1 = take ? og : myg1;
;           }
;         }
;       }
;     }
; }
; DEV void peer_gather(const Params& P, int l, int m0, const int* idxs, const float* gs) {
;     ...
;     PG_ISSUE(b0, U, 0);
; #pragma nounroll
;     for (int e0 = 0; e0 < 128; e0 += 16) {
;       PG_ISSUE(b1, U, e0 + 8);
	v_cndmask_b32_e64 v22, v33, v32, s[88:89]
	v_cndmask_b32_e64 v13, v35, v34, s[88:89]
	v_cndmask_b32_e64 v7, v37, v36, s[88:89]
	v_cndmask_b32_e64 v15, v39, v38, s[88:89]
	s_nop 1
	v_min_u32_e32 v16, v0, v8
	v_min_u32_e32 v4, v2, v10
	v_min_u32_e32 v1, v17, v9
	v_min_u32_e32 v3, v19, v14
	v_min_u32_e32 v20, v18, v22
	v_min_u32_e32 v6, v21, v13
	v_min_u32_e32 v5, v12, v7
	v_min_u32_e32 v23, v11, v15
	v_max_u32_e32 v8, v0, v8
	v_max_u32_e32 v10, v2, v10
	v_max_u32_e32 v9, v17, v9
	v_max_u32_e32 v14, v19, v14
	v_max_u32_e32 v22, v18, v22
	v_max_u32_e32 v13, v21, v13
	v_max_u32_e32 v7, v12, v7
	v_max_u32_e32 v15, v11, v15
	v_min_u32_e32 v0, v16, v20
	v_min_u32_e32 v2, v4, v6
	v_min_u32_e32 v17, v1, v5
	v_min_u32_e32 v19, v3, v23
	v_min_u32_e32 v18, v8, v22
	v_min_u32_e32 v21, v10, v13
	v_min_u32_e32 v12, v9, v7
	v_min_u32_e32 v11, v14, v15
	v_max_u32_e32 v20, v16, v20
	v_max_u32_e32 v6, v4, v6
	v_max_u32_e32 v5, v1, v5
	v_max_u32_e32 v23, v3, v23
	v_max_u32_e32 v22, v8, v22
	v_max_u32_e32 v13, v10, v13
	v_max_u32_e32 v7, v9, v7
	v_max_u32_e32 v15, v14, v15
	v_min_u32_e32 v16, v0, v17
	v_min_u32_e32 v4, v2, v19
	v_min_u32_e32 v1, v20, v5
	v_min_u32_e32 v3, v6, v23
	v_min_u32_e32 v8, v18, v12
	v_min_u32_e32 v10, v21, v11
	v_min_u32_e32 v9, v22, v7
	v_min_u32_e32 v14, v13, v15
	v_max_u32_e32 v17, v0, v17
	v_max_u32_e32 v19, v2, v19
	v_max_u32_e32 v5, v20, v5
	v_max_u32_e32 v23, v6, v23
	v_max_u32_e32 v12, v18, v12
	v_max_u32_e32 v11, v21, v11
	v_max_u32_e32 v7, v22, v7
	v_max_u32_e32 v15, v13, v15
	v_min_u32_e32 v0, v16, v4
	v_min_u32_e32 v2, v17, v19
	v_min_u32_e32 v20, v1, v3
	v_min_u32_e32 v6, v5, v23
	v_min_u32_e32 v18, v8, v10
	v_min_u32_e32 v21, v12, v11
	v_min_u32_e32 v22, v9, v14
	v_min_u32_e32 v13, v7, v15
	v_max_u32_e32 v4, v16, v4
	v_max_u32_e32 v19, v17, v19
	v_max_u32_e32 v3, v1, v3
	v_max_u32_e32 v23, v5, v23
	v_max_u32_e32 v10, v8, v10
	v_max_u32_e32 v11, v12, v11
	v_max_u32_e32 v14, v9, v14
	v_max_u32_e32 v15, v7, v15
	ds_write_b32 v41, v0 offset:4096
	ds_write_b32 v41, v4 offset:4160
	ds_write_b32 v41, v2 offset:4224
	ds_write_b32 v41, v19 offset:4288
	ds_write_b32 v41, v20 offset:4352
	ds_write_b32 v41, v3 offset:4416
	ds_write_b32 v41, v6 offset:4480
	ds_write_b32 v41, v23 offset:4544
	ds_write_b32 v41, v18 offset:4100
	ds_write_b32 v41, v10 offset:4164
	ds_write_b32 v41, v21 offset:4228
	ds_write_b32 v41, v11 offset:4292
	ds_write_b32 v41, v22 offset:4356
	ds_write_b32 v41, v14 offset:4420
	ds_write_b32 v41, v13 offset:4484
	ds_write_b32 v41, v15 offset:4548
	s_waitcnt lgkmcnt(0)
	v_readfirstlane_b32 s82, v128
	v_readfirstlane_b32 s83, v129
	s_nop 4
	v_readfirstlane_b32 s80, v124
	v_readfirstlane_b32 s81, v125
	s_nop 4
	s_mov_b32 s2, 0xffffff80
	s_mov_b32 s86, 0xcccccccc
	s_mov_b32 s87, 0xcccccccc
	s_mov_b32 s88, 0xaaaaaaaa
	s_mov_b32 s89, 0xaaaaaaaa
	s_mov_b32 s90, 0xf0f0f0f0
	s_mov_b32 s91, 0xf0f0f0f0
	s_lshl_b32 vcc_lo, s3, 11
	s_add_u32 s82, s82, vcc_lo
	s_addc_u32 s83, s83, 0
	v_lshl_add_u32 v246, v237, 4, s101
	v_lshrrev_b32_e32 v247, 2, v235
	v_add_u32_e32 v247, v247, v246
	v_add_u32_e32 v247, 0x10000, v247
	s_mov_b32 s100, 0
	s_mov_b32 s98, 0
	s_mov_b32 s99, 0
	s_lshl3_add_u32 vcc_lo, s98, s99
	v_lshl_add_u32 v119, vcc_lo, 8, v236
	global_load_dwordx4 v[80:83], v119, s[82:83]
	global_load_dwordx4 v[84:87], v119, s[82:83] offset:16
	v_lshl_add_u32 v116, s98, 9, v246
	ds_read_b128 v[112:115], v116
	ds_read_b128 v[138:141], v116 offset:16
	ds_read_b128 v[250:253], v116 offset:32
	ds_read_b128 v[242:245], v116 offset:48
	v_lshl_or_b32 v240, s99, 21, v235
	s_waitcnt lgkmcnt(0)
	v_and_or_b32 v112, v112, s2, v240
	v_and_or_b32 v113, v113, s2, v240
	global_load_dwordx4 v[0:3], v112, s[80:81]
	global_load_dwordx4 v[4:7], v113, s[80:81]
	v_and_or_b32 v114, v114, s2, v240
	v_and_or_b32 v115, v115, s2, v240
	global_load_dwordx4 v[8:11], v114, s[80:81]
	global_load_dwordx4 v[12:15], v115, s[80:81]
	v_and_or_b32 v138, v138, s2, v240
	v_and_or_b32 v139, v139, s2, v240
	global_load_dwordx4 v[16:19], v138, s[80:81]
	global_load_dwordx4 v[20:23], v139, s[80:81]
	v_and_or_b32 v140, v140, s2, v240
	v_and_or_b32 v141, v141, s2, v240
	global_load_dwordx4 v[24:27], v140, s[80:81]
	global_load_dwordx4 v[28:31], v141, s[80:81]
	v_and_or_b32 v250, v250, s2, v240
	v_and_or_b32 v251, v251, s2, v240
	global_load_dwordx4 v[32:35], v250, s[80:81]
	global_load_dwordx4 v[36:39], v251, s[80:81]
	v_and_or_b32 v252, v252, s2, v240
	v_and_or_b32 v253, v253, s2, v240
	global_load_dwordx4 v[40:43], v252, s[80:81]
	global_load_dwordx4 v[44:47], v253, s[80:81]
	v_and_or_b32 v242, v242, s2, v240
	v_and_or_b32 v243, v243, s2, v240
	global_load_dwordx4 v[48:51], v242, s[80:81]
	global_load_dwordx4 v[52:55], v243, s[80:81]
	v_and_or_b32 v244, v244, s2, v240
	v_and_or_b32 v245, v245, s2, v240
	global_load_dwordx4 v[56:59], v244, s[80:81]
	global_load_dwordx4 v[60:63], v245, s[80:81]
	s_mov_b32 s92, 1
	v_lshl_add_u32 v116, s92, 9, v246
	ds_read_b128 v[112:115], v116
	ds_read_b128 v[138:141], v116 offset:16
	ds_read_b128 v[250:253], v116 offset:32
	ds_read_b128 v[242:245], v116 offset:48

; DEV int tid_l() { int t = threadIdx.x; asm volatile("" : "+v"(t)); return t; }
; DEV void sort_lists(int lane, int& myi0, int& myi1, float& myg0, float& myg1) {
; #pragma unroll
;     for (int k = 2; k <= 128; k <<= 1) {
; #pragma unroll
;       for (int j = k >> 1; j >= 1; j >>= 1) {
;         if (j == 64) {
;           const bool sw_ = myi1 < myi0;
;           const int ti = sw_ ? myi1 : myi0, tj = sw_ ? myi0 : myi1; const float tg = sw_ ? myg1 : myg0, th = sw_ ? myg0 : myg1;
;           myi0 = ti; myi1 = tj; myg0 = tg; myg1 = th;
;         } else {
;           const bool lower = (lane & j) == 0;
;           {
;             const bool up = (k == 128) ? true : ((k == 64) ? true : ((lane & k) == 0));
;             const int oi = __shfl_xor(myi0, j); const float og = __shfl_xor(myg0, j);
;             const bool take = (lower == up) ? (oi < myi0) : (oi > myi0);
;             myi0 = take ? oi : myi0; myg0 = take ? og : myg0;
;           }
;           {
;             const bool up = (k == 128) ? true : ((k == 64) ? false : ((lane & k) == 0));
;             const int oi = __shfl_xor(myi1, j); const float og = __shfl_xor(myg1, j);
;             const bool take = (lower == up) ? (oi < myi1) : (oi > myi1);
;             myi1 = take ? oi : myi1; myg1 = take ? og : myg1;
;           }
;         }
;       }
;     }
; }
; DEV void peer_gather(const Params& P, int l, int m0, const int* idxs, const float* gs) {
;   const int tid = tid_l(), lane = tid & 63, wid = tid >> 6;
;   const unsigned char* U = P.ws + WS_TAB + (size_t)l * 32 * MB;
;   const unsigned char* V = U + 16 * MB;
;   bf16_t* hn = (bf16_t*)(P.ws + WS_HN);
;   const float* gp = P.norm_ple + l * DM;
;   const int row = lane >> 4, rmap = ((row & 1) << 1) | (row >> 1);
;   u32x4 nxa = *(const u32x4*)(hn + (size_t)(m0 + wid * 16) * DM + lane * 16), nxb = *(const u32x4*)(hn + (size_t)(m0 + wid * 16) * DM + lane * 16 + 8);
;   int ni0 = idxs[(wid * 16) * 128 + lane], ni1 = idxs[(wid * 16) * 128 + 64 + lane];
;   float ng0 = gs[(wid * 16) * 128 + lane], ng1 = gs[(wid * 16) * 128 + 64 + lane];
;   sort_lists(lane, ni0, ni1, ng0, ng1);
.LBB0_752:
	s_waitcnt vmcnt(0) lgkmcnt(0)
	v_and_b32_e32 v233, 63, v176
	v_lshlrev_b32_e32 v234, 2, v233
	v_and_b32_e32 v116, 7, v233
	v_lshlrev_b32_e32 v235, 4, v116
	v_lshlrev_b32_e32 v236, 5, v116
	v_lshrrev_b32_e32 v117, 3, v233
	v_lshlrev_b32_e32 v237, 2, v117
	v_lshl_add_u32 v239, v116, 3, v117
	v_lshlrev_b32_e32 v239, 2, v239
	v_lshlrev_b32_e32 v238, 4, v116
	v_and_b32_e32 v117, 1, v117
	v_lshl_add_u32 v238, v117, 2, v238
	v_bfe_u32 v117, v233, 4, 1
	v_lshl_add_u32 v238, v117, 1, v238
	v_lshrrev_b32_e32 v117, 5, v233
	v_add_u32_e32 v238, v117, v238
	v_lshlrev_b32_e32 v238, 2, v238
	v_add_u32_e32 v249, 0, v237
	v_add_u32_e32 v250, 32, v237
	v_add_u32_e32 v251, 64, v237
	v_add_u32_e32 v252, 96, v237
	v_add_u32_e32 v253, 128, v237
	v_add_u32_e32 v254, 160, v237
	v_add_u32_e32 v255, 192, v237
	v_add_u32_e32 v153, 224, v237
	v_readfirstlane_b32 s33, v176
	s_lshr_b32 s33, s33, 6
	s_lshl_b32 s101, s33, 13
	s_lshl_b32 s33, s33, 4
	v_readlane_b32 s3, v231, 15
	s_add_u32 s3, s3, s33
	v_readlane_b32 s82, v231, 13
	v_readlane_b32 s83, v231, 14
	s_nop 4
	s_lshl_b32 vcc_lo, s33, 9
	s_add_u32 s82, s82, vcc_lo
	s_addc_u32 s83, s83, 0
	v_lshlrev_b32_e32 v40, 7, v237
	v_lshrrev_b32_e32 v41, 1, v235
	v_add3_u32 v41, v41, v40, s101
	v_lshl_add_u32 v40, v235, 2, v40
	v_mov_b32_e32 v24, 0
	v_add_u32_e32 v42, s101, v234
	v_add_u32_e32 v42, 0x10000, v42
	ds_write_b32 v42, v24 offset:0
	ds_write_b32 v42, v24 offset:256
	ds_write_b32 v42, v24 offset:512
	ds_write_b32 v42, v24 offset:768
	ds_write_b32 v42, v24 offset:1024
	ds_write_b32 v42, v24 offset:1280
	ds_write_b32 v42, v24 offset:1536
	ds_write_b32 v42, v24 offset:1792
	ds_write_b32 v42, v24 offset:2048
	ds_write_b32 v42, v24 offset:2304
	ds_write_b32 v42, v24 offset:2560
	ds_write_b32 v42, v24 offset:2816
	ds_write_b32 v42, v24 offset:3072
	ds_write_b32 v42, v24 offset:3328
	ds_write_b32 v42, v24 offset:3584
	ds_write_b32 v42, v24 offset:3840
	ds_write_b32 v42, v24 offset:4096
	ds_write_b32 v42, v24 offset:4352
	ds_write_b32 v42, v24 offset:4608
	ds_write_b32 v42, v24 offset:4864
	ds_write_b32 v42, v24 offset:5120
	ds_write_b32 v42, v24 offset:5376
	ds_write_b32 v42, v24 offset:5632
	ds_write_b32 v42, v24 offset:5888
	ds_write_b32 v42, v24 offset:6144
	ds_write_b32 v42, v24 offset:6400
	ds_write_b32 v42, v24 offset:6656
	ds_write_b32 v42, v24 offset:6912
	ds_write_b32 v42, v24 offset:7168
	ds_write_b32 v42, v24 offset:7424
	ds_write_b32 v42, v24 offset:7680
	ds_write_b32 v42, v24 offset:7936
	global_load_dwordx4 v[0:3], v40, s[82:83] offset:0
	global_load_dwordx4 v[4:7], v40, s[82:83] offset:16
	global_load_dwordx4 v[8:11], v40, s[82:83] offset:32
	global_load_dwordx4 v[12:15], v40, s[82:83] offset:48
	s_waitcnt vmcnt(0)
	s_add_u32 s82, s82, 0x1000
	s_addc_u32 s83, s83, 0
	v_lshl_or_b32 v0, v0, 7, v235
	v_lshl_or_b32 v1, v1, 7, v235
	v_lshl_or_b32 v2, v2, 7, v235
	v_lshl_or_b32 v3, v3, 7, v235
	v_lshl_or_b32 v4, v4, 7, v235
	v_lshl_or_b32 v5, v5, 7, v235
	v_lshl_or_b32 v6, v6, 7, v235
	v_lshl_or_b32 v7, v7, 7, v235
	v_lshl_or_b32 v8, v8, 7, v235
	v_lshl_or_b32 v9, v9, 7, v235
	v_lshl_or_b32 v10, v10, 7, v235
	v_lshl_or_b32 v11, v11, 7, v235
	v_lshl_or_b32 v12, v12, 7, v235
	v_lshl_or_b32 v13, v13, 7, v235
	v_lshl_or_b32 v14, v14, 7, v235
	v_lshl_or_b32 v15, v15, 7, v235
	v_or_b32_e32 v1, 1, v1
	v_or_b32_e32 v2, 2, v2
	v_or_b32_e32 v3, 3, v3
	v_or_b32_e32 v4, 4, v4
	v_or_b32_e32 v5, 5, v5
	v_or_b32_e32 v6, 6, v6
	v_or_b32_e32 v7, 7, v7
	v_or_b32_e32 v8, 8, v8
	v_or_b32_e32 v9, 9, v9
	v_or_b32_e32 v10, 10, v10
	v_or_b32_e32 v11, 11, v11
	v_or_b32_e32 v12, 12, v12
	v_or_b32_e32 v13, 13, v13
	v_or_b32_e32 v14, 14, v14
	v_or_b32_e32 v15, 15, v15
	v_min_u32_e32 v16, v0, v1
	v_min_u32_e32 v17, v2, v3
	v_min_u32_e32 v18, v4, v5
	v_min_u32_e32 v19, v6, v7
	v_min_u32_e32 v20, v8, v9
	v_min_u32_e32 v21, v10, v11
	v_min_u32_e32 v22, v12, v13
	v_min_u32_e32 v23, v14, v15
	v_max_u32_e32 v1, v0, v1
	v_max_u32_e32 v3, v2, v3
	v_max_u32_e32 v5, v4, v5
	v_max_u32_e32 v7, v6, v7
	v_max_u32_e32 v9, v8, v9
	v_max_u32_e32 v11, v10, v11
	v_max_u32_e32 v13, v12, v13
	v_max_u32_e32 v15, v14, v15
	v_min_u32_e32 v0, v16, v3
	v_min_u32_e32 v2, v1, v17
	v_min_u32_e32 v4, v18, v7
	v_min_u32_e32 v6, v5, v19
	v_min_u32_e32 v8, v20, v11
	v_min_u32_e32 v10, v9, v21
	v_min_u32_e32 v12, v22, v15
	v_min_u32_e32 v14, v13, v23
	v_max_u32_e32 v3, v16, v3
	v_max_u32_e32 v17, v1, v17
	v_max_u32_e32 v7, v18, v7
	v_max_u32_e32 v19, v5, v19
	v_max_u32_e32 v11, v20, v11
	v_max_u32_e32 v21, v9, v21
	v_max_u32_e32 v15, v22, v15
	v_max_u32_e32 v23, v13, v23
	v_min_u32_e32 v16, v0, v2
	v_min_u32_e32 v1, v17, v3
	v_min_u32_e32 v18, v4, v6
	v_min_u32_e32 v5, v19, v7
	v_min_u32_e32 v20, v8, v10
	v_min_u32_e32 v9, v21, v11
	v_min_u32_e32 v22, v12, v14
	v_min_u32_e32 v13, v23, v15
	v_max_u32_e32 v2, v0, v2
	v_max_u32_e32 v3, v17, v3
	v_max_u32_e32 v6, v4, v6
	v_max_u32_e32 v7, v19, v7
	v_max_u32_e32 v10, v8, v10
	v_max_u32_e32 v11, v21, v11
	v_max_u32_e32 v14, v12, v14
	v_max_u32_e32 v15, v23, v15
	v_min_u32_e32 v0, v16, v7
	v_min_u32_e32 v17, v2, v5
	v_min_u32_e32 v4, v1, v6
	v_min_u32_e32 v19, v3, v18
	v_min_u32_e32 v8, v20, v15
	v_min_u32_e32 v21, v10, v13
	v_min_u32_e32 v12, v9, v14
	v_min_u32_e32 v23, v11, v22
	v_max_u32_e32 v7, v16, v7
	v_max_u32_e32 v5, v2, v5
	v_max_u32_e32 v6, v1, v6
	v_max_u32_e32 v18, v3, v18
	v_max_u32_e32 v15, v20, v15
	v_max_u32_e32 v13, v10, v13
	v_max_u32_e32 v14, v9, v14
	v_max_u32_e32 v22, v11, v22
	v_min_u32_e32 v16, v0, v4
	v_min_u32_e32 v2, v17, v19
	v_min_u32_e32 v1, v18, v5
	v_min_u32_e32 v3, v6, v7
	v_min_u32_e32 v20, v8, v12
	v_min_u32_e32 v10, v21, v23
	v_min_u32_e32 v9, v22, v13
	v_min_u32_e32 v11, v14, v15
; DEV void sort_lists(int lane, int& myi0, int& myi1, float& myg0, float& myg1) {
; #pragma unroll
;     for (int k = 2; k <= 128; k <<= 1) {
; #pragma unroll
;       for (int j = k >> 1; j >= 1; j >>= 1) {
;         if (j == 64) {
;           const bool sw_ = myi1 < myi0;
;           const int ti = sw_ ? myi1 : myi0, tj = sw_ ? myi0 : myi1; const float tg = sw_ ? myg1 : myg0, th = sw_ ? myg0 : myg1;
;           myi0 = ti; myi1 = tj; myg0 = tg; myg1 = th;
;         } else {
;           const bool lower = (lane & j) == 0;
;           {
;             const bool up = (k == 128) ? true : ((k == 64) ? true : ((lane & k) == 0));
;             const int oi = __shfl_xor(myi0, j); const float og = __shfl_xor(myg0, j);
;             const bool take = (lower == up) ? (oi < myi0) : (oi > myi0);
;             myi0 = take ? oi : myi0; myg0 = take ? og : myg0;
;           }
;           {
;             const bool up = (k == 128) ? true : ((k == 64) ? false : ((lane & k) == 0));
;             const int oi = __shfl_xor(myi1, j); const float og = __shfl_xor(myg1, j);
;             const bool take = (lower == up) ? (oi < myi1) : (oi > myi1);
;             myi1 = take ? oi : myi1; myg1 = take ? og : myg1;
;           }
;         }
;       }
;     }
; }
	v_max_u32_e32 v4, v0, v4
	v_max_u32_e32 v19, v17, v19
	v_max_u32_e32 v5, v18, v5
	v_max_u32_e32 v7, v6, v7
	v_max_u32_e32 v12, v8, v12
	v_max_u32_e32 v23, v21, v23
	v_max_u32_e32 v13, v22, v13
	v_max_u32_e32 v15, v14, v15
	v_min_u32_e32 v0, v16, v2
	v_min_u32_e32 v17, v4, v19
	v_min_u32_e32 v18, v1, v3
	v_min_u32_e32 v6, v5, v7
	v_min_u32_e32 v8, v20, v10
	v_min_u32_e32 v21, v12, v23
	v_min_u32_e32 v22, v9, v11
	v_min_u32_e32 v14, v13, v15
	v_max_u32_e32 v2, v16, v2
	v_max_u32_e32 v19, v4, v19
	v_max_u32_e32 v3, v1, v3
	v_max_u32_e32 v7, v5, v7
	v_max_u32_e32 v10, v20, v10
	v_max_u32_e32 v23, v12, v23
	v_max_u32_e32 v11, v9, v11
	v_max_u32_e32 v15, v13, v15
	v_min_u32_e32 v16, v0, v15
	v_min_u32_e32 v4, v2, v14
	v_min_u32_e32 v1, v17, v11
	v_min_u32_e32 v5, v19, v22
	v_min_u32_e32 v20, v18, v23
	v_min_u32_e32 v12, v3, v21
	v_min_u32_e32 v9, v6, v10
	v_min_u32_e32 v13, v7, v8
	v_max_u32_e32 v15, v0, v15
	v_max_u32_e32 v14, v2, v14
	v_max_u32_e32 v11, v17, v11
	v_max_u32_e32 v22, v19, v22
	v_max_u32_e32 v23, v18, v23
	v_max_u32_e32 v21, v3, v21
	v_max_u32_e32 v10, v6, v10
	v_max_u32_e32 v8, v7, v8
	v_min_u32_e32 v0, v16, v20
	v_min_u32_e32 v2, v4, v12
	v_min_u32_e32 v17, v1, v9
	v_min_u32_e32 v19, v5, v13
	v_min_u32_e32 v18, v8, v22
	v_min_u32_e32 v3, v10, v11
	v_min_u32_e32 v6, v21, v14
	v_min_u32_e32 v7, v23, v15
	v_max_u32_e32 v20, v16, v20
	v_max_u32_e32 v12, v4, v12
	v_max_u32_e32 v9, v1, v9
	v_max_u32_e32 v13, v5, v13
	v_max_u32_e32 v22, v8, v22
	v_max_u32_e32 v11, v10, v11
	v_max_u32_e32 v14, v21, v14
	v_max_u32_e32 v15, v23, v15
	v_min_u32_e32 v16, v0, v17
	v_min_u32_e32 v4, v2, v19
	v_min_u32_e32 v1, v20, v9
	v_min_u32_e32 v5, v12, v13
	v_min_u32_e32 v8, v18, v6
	v_min_u32_e32 v10, v3, v7
	v_min_u32_e32 v21, v22, v14
	v_min_u32_e32 v23, v11, v15
	v_max_u32_e32 v17, v0, v17
	v_max_u32_e32 v19, v2, v19
	v_max_u32_e32 v9, v20, v9
	v_max_u32_e32 v13, v12, v13
	v_max_u32_e32 v6, v18, v6
	v_max_u32_e32 v7, v3, v7
	v_max_u32_e32 v14, v22, v14
	v_max_u32_e32 v15, v11, v15
	v_min_u32_e32 v0, v16, v4
	v_min_u32_e32 v2, v17, v19
	v_min_u32_e32 v20, v1, v5
	v_min_u32_e32 v12, v9, v13
	v_min_u32_e32 v18, v8, v10
	v_min_u32_e32 v3, v6, v7
	v_min_u32_e32 v22, v21, v23
	v_min_u32_e32 v11, v14, v15
	v_max_u32_e32 v4, v16, v4
	v_max_u32_e32 v19, v17, v19
	v_max_u32_e32 v5, v1, v5
	v_max_u32_e32 v13, v9, v13
	v_max_u32_e32 v10, v8, v10
	v_max_u32_e32 v7, v6, v7
	v_max_u32_e32 v23, v21, v23
	v_max_u32_e32 v15, v14, v15
	s_mov_b32 s88, 0x55555555
	s_mov_b32 s89, 0x55555555
	s_nop 1
	v_min_u32_dpp v24, v15, v0 quad_perm:[1,0,3,2] row_mask:0xf bank_mask:0xf
	v_max_u32_dpp v25, v15, v0 quad_perm:[1,0,3,2] row_mask:0xf bank_mask:0xf
	v_min_u32_dpp v26, v0, v15 quad_perm:[1,0,3,2] row_mask:0xf bank_mask:0xf
	v_max_u32_dpp v27, v0, v15 quad_perm:[1,0,3,2] row_mask:0xf bank_mask:0xf
	v_min_u32_dpp v28, v11, v4 quad_perm:[1,0,3,2] row_mask:0xf bank_mask:0xf
	v_max_u32_dpp v29, v11, v4 quad_perm:[1,0,3,2] row_mask:0xf bank_mask:0xf
	v_min_u32_dpp v30, v4, v11 quad_perm:[1,0,3,2] row_mask:0xf bank_mask:0xf
	v_max_u32_dpp v31, v4, v11 quad_perm:[1,0,3,2] row_mask:0xf bank_mask:0xf
	v_min_u32_dpp v32, v23, v2 quad_perm:[1,0,3,2] row_mask:0xf bank_mask:0xf
	v_max_u32_dpp v33, v23, v2 quad_perm:[1,0,3,2] row_mask:0xf bank_mask:0xf
	v_min_u32_dpp v34, v2, v23 quad_perm:[1,0,3,2] row_mask:0xf bank_mask:0xf
	v_max_u32_dpp v35, v2, v23 quad_perm:[1,0,3,2] row_mask:0xf bank_mask:0xf
	v_min_u32_dpp v36, v22, v19 quad_perm:[1,0,3,2] row_mask:0xf bank_mask:0xf
	v_max_u32_dpp v37, v22, v19 quad_perm:[1,0,3,2] row_mask:0xf bank_mask:0xf
	v_min_u32_dpp v38, v19, v22 quad_perm:[1,0,3,2] row_mask:0xf bank_mask:0xf
	v_max_u32_dpp v39, v19, v22 quad_perm:[1,0,3,2] row_mask:0xf bank_mask:0xf
	v_cndmask_b32_e64 v0, v25, v24, s[88:89]
	v_cndmask_b32_e64 v15, v27, v26, s[88:89]
	v_cndmask_b32_e64 v4, v29, v28, s[88:89]
	v_cndmask_b32_e64 v11, v31, v30, s[88:89]
	v_cndmask_b32_e64 v2, v33, v32, s[88:89]
	v_cndmask_b32_e64 v23, v35, v34, s[88:89]
	v_cndmask_b32_e64 v19, v37, v36, s[88:89]
	v_cndmask_b32_e64 v22, v39, v38, s[88:89]
	s_nop 1
	v_min_u32_dpp v24, v7, v20 quad_perm:[1,0,3,2] row_mask:0xf bank_mask:0xf
	v_max_u32_dpp v25, v7, v20 quad_perm:[1,0,3,2] row_mask:0xf bank_mask:0xf
	v_min_u32_dpp v26, v20, v7 quad_perm:[1,0,3,2] row_mask:0xf bank_mask:0xf
	v_max_u32_dpp v27, v20, v7 quad_perm:[1,0,3,2] row_mask:0xf bank_mask:0xf
	v_min_u32_dpp v28, v3, v5 quad_perm:[1,0,3,2] row_mask:0xf bank_mask:0xf
	v_max_u32_dpp v29, v3, v5 quad_perm:[1,0,3,2] row_mask:0xf bank_mask:0xf
	v_min_u32_dpp v30, v5, v3 quad_perm:[1,0,3,2] row_mask:0xf bank_mask:0xf
	v_max_u32_dpp v31, v5, v3 quad_perm:[1,0,3,2] row_mask:0xf bank_mask:0xf
	v_min_u32_dpp v32, v10, v12 quad_perm:[1,0,3,2] row_mask:0xf bank_mask:0xf
	v_max_u32_dpp v33, v10, v12 quad_perm:[1,0,3,2] row_mask:0xf bank_mask:0xf
	v_min_u32_dpp v34, v12, v10 quad_perm:[1,0,3,2] row_mask:0xf bank_mask:0xf
	v_max_u32_dpp v35, v12, v10 quad_perm:[1,0,3,2] row_mask:0xf bank_mask:0xf
	v_min_u32_dpp v36, v18, v13 quad_perm:[1,0,3,2] row_mask:0xf bank_mask:0xf
	v_max_u32_dpp v37, v18, v13 quad_perm:[1,0,3,2] row_mask:0xf bank_mask:0xf
	v_min_u32_dpp v38, v13, v18 quad_perm:[1,0,3,2] row_mask:0xf bank_mask:0xf
	v_max_u32_dpp v39, v13, v18 quad_perm:[1,0,3,2] row_mask:0xf bank_mask:0xf
	v_cndmask_b32_e64 v20, v25, v24, s[88:89]
	v_cndmask_b32_e64 v7, v27, v26, s[88:89]
	v_cndmask_b32_e64 v5, v29, v28, s[88:89]
	v_cndmask_b32_e64 v3, v31, v30, s[88:89]
	v_cndmask_b32_e64 v12, v33, v32, s[88:89]
	v_cndmask_b32_e64 v10, v35, v34, s[88:89]
	v_cndmask_b32_e64 v13, v37, v36, s[88:89]
	v_cndmask_b32_e64 v18, v39, v38, s[88:89]
	s_nop 1
	v_min_u32_e32 v16, v0, v18
; DEV void sort_lists(int lane, int& myi0, int& myi1, float& myg0, float& myg1) {
; #pragma unroll
;     for (int k = 2; k <= 128; k <<= 1) {
; #pragma unroll
;       for (int j = k >> 1; j >= 1; j >>= 1) {
;         if (j == 64) {
;           const bool sw_ = myi1 < myi0;
;           const int ti = sw_ ? myi1 : myi0, tj = sw_ ? myi0 : myi1; const float tg = sw_ ? myg1 : myg0, th = sw_ ? myg0 : myg1;
;           myi0 = ti; myi1 = tj; myg0 = tg; myg1 = th;
;         } else {
;           const bool lower = (lane & j) == 0;
;           {
;             const bool up = (k == 128) ? true : ((k == 64) ? true : ((lane & k) == 0));
;             const int oi = __shfl_xor(myi0, j); const float og = __shfl_xor(myg0, j);
;             const bool take = (lower == up) ? (oi < myi0) : (oi > myi0);
;             myi0 = take ? oi : myi0; myg0 = take ? og : myg0;
;           }
;           {
;             const bool up = (k == 128) ? true : ((k == 64) ? false : ((lane & k) == 0));
;             const int oi = __shfl_xor(myi1, j); const float og = __shfl_xor(myg1, j);
;             const bool take = (lower == up) ? (oi < myi1) : (oi > myi1);
;             myi1 = take ? oi : myi1; myg1 = take ? og : myg1;
;           }
;         }
;       }
;     }
; }
	v_min_u32_e32 v17, v4, v10
	v_min_u32_e32 v1, v2, v3
	v_min_u32_e32 v9, v19, v7
	v_min_u32_e32 v8, v20, v22
	v_min_u32_e32 v6, v5, v23
	v_min_u32_e32 v21, v12, v11
	v_min_u32_e32 v14, v13, v15
	v_max_u32_e32 v18, v0, v18
	v_max_u32_e32 v10, v4, v10
	v_max_u32_e32 v3, v2, v3
	v_max_u32_e32 v7, v19, v7
	v_max_u32_e32 v22, v20, v22
	v_max_u32_e32 v23, v5, v23
	v_max_u32_e32 v11, v12, v11
	v_max_u32_e32 v15, v13, v15
	v_min_u32_e32 v0, v16, v8
	v_min_u32_e32 v4, v17, v6
	v_min_u32_e32 v2, v1, v21
	v_min_u32_e32 v19, v9, v14
	v_min_u32_e32 v20, v18, v22
	v_min_u32_e32 v5, v10, v23
	v_min_u32_e32 v12, v3, v11
	v_min_u32_e32 v13, v7, v15
	v_max_u32_e32 v8, v16, v8
	v_max_u32_e32 v6, v17, v6
	v_max_u32_e32 v21, v1, v21
	v_max_u32_e32 v14, v9, v14
	v_max_u32_e32 v22, v18, v22
	v_max_u32_e32 v23, v10, v23
	v_max_u32_e32 v11, v3, v11
	v_max_u32_e32 v15, v7, v15
	v_min_u32_e32 v16, v0, v2
	v_min_u32_e32 v17, v4, v19
	v_min_u32_e32 v1, v8, v21
	v_min_u32_e32 v9, v6, v14
	v_min_u32_e32 v18, v20, v12
	v_min_u32_e32 v10, v5, v13
	v_min_u32_e32 v3, v22, v11
	v_min_u32_e32 v7, v23, v15
	v_max_u32_e32 v2, v0, v2
	v_max_u32_e32 v19, v4, v19
	v_max_u32_e32 v21, v8, v21
	v_max_u32_e32 v14, v6, v14
	v_max_u32_e32 v12, v20, v12
	v_max_u32_e32 v13, v5, v13
	v_max_u32_e32 v11, v22, v11
	v_max_u32_e32 v15, v23, v15
	v_min_u32_e32 v0, v16, v17
	v_min_u32_e32 v4, v2, v19
	v_min_u32_e32 v8, v1, v9
	v_min_u32_e32 v6, v21, v14
	v_min_u32_e32 v20, v18, v10
	v_min_u32_e32 v5, v12, v13
	v_min_u32_e32 v22, v3, v7
	v_min_u32_e32 v23, v11, v15
	v_max_u32_e32 v17, v16, v17
	v_max_u32_e32 v19, v2, v19
	v_max_u32_e32 v9, v1, v9
	v_max_u32_e32 v14, v21, v14
	v_max_u32_e32 v10, v18, v10
	v_max_u32_e32 v13, v12, v13
	v_max_u32_e32 v7, v3, v7
	v_max_u32_e32 v15, v11, v15
	s_mov_b32 s88, 0x33333333
	s_mov_b32 s89, 0x33333333
	s_nop 1
	v_min_u32_dpp v24, v15, v0 quad_perm:[3,2,1,0] row_mask:0xf bank_mask:0xf
	v_max_u32_dpp v25, v15, v0 quad_perm:[3,2,1,0] row_mask:0xf bank_mask:0xf
	v_min_u32_dpp v26, v0, v15 quad_perm:[3,2,1,0] row_mask:0xf bank_mask:0xf
	v_max_u32_dpp v27, v0, v15 quad_perm:[3,2,1,0] row_mask:0xf bank_mask:0xf
	v_min_u32_dpp v28, v23, v17 quad_perm:[3,2,1,0] row_mask:0xf bank_mask:0xf
	v_max_u32_dpp v29, v23, v17 quad_perm:[3,2,1,0] row_mask:0xf bank_mask:0xf
	v_min_u32_dpp v30, v17, v23 quad_perm:[3,2,1,0] row_mask:0xf bank_mask:0xf
	v_max_u32_dpp v31, v17, v23 quad_perm:[3,2,1,0] row_mask:0xf bank_mask:0xf
	v_min_u32_dpp v32, v7, v4 quad_perm:[3,2,1,0] row_mask:0xf bank_mask:0xf
	v_max_u32_dpp v33, v7, v4 quad_perm:[3,2,1,0] row_mask:0xf bank_mask:0xf
	v_min_u32_dpp v34, v4, v7 quad_perm:[3,2,1,0] row_mask:0xf bank_mask:0xf
	v_max_u32_dpp v35, v4, v7 quad_perm:[3,2,1,0] row_mask:0xf bank_mask:0xf
	v_min_u32_dpp v36, v22, v19 quad_perm:[3,2,1,0] row_mask:0xf bank_mask:0xf
	v_max_u32_dpp v37, v22, v19 quad_perm:[3,2,1,0] row_mask:0xf bank_mask:0xf
	v_min_u32_dpp v38, v19, v22 quad_perm:[3,2,1,0] row_mask:0xf bank_mask:0xf
	v_max_u32_dpp v39, v19, v22 quad_perm:[3,2,1,0] row_mask:0xf bank_mask:0xf
	v_cndmask_b32_e64 v0, v25, v24, s[88:89]
	v_cndmask_b32_e64 v15, v27, v26, s[88:89]
	v_cndmask_b32_e64 v17, v29, v28, s[88:89]
	v_cndmask_b32_e64 v23, v31, v30, s[88:89]
	v_cndmask_b32_e64 v4, v33, v32, s[88:89]
	v_cndmask_b32_e64 v7, v35, v34, s[88:89]
	v_cndmask_b32_e64 v19, v37, v36, s[88:89]
	v_cndmask_b32_e64 v22, v39, v38, s[88:89]
	s_nop 1
	v_min_u32_dpp v24, v13, v8 quad_perm:[3,2,1,0] row_mask:0xf bank_mask:0xf
	v_max_u32_dpp v25, v13, v8 quad_perm:[3,2,1,0] row_mask:0xf bank_mask:0xf
	v_min_u32_dpp v26, v8, v13 quad_perm:[3,2,1,0] row_mask:0xf bank_mask:0xf
	v_max_u32_dpp v27, v8, v13 quad_perm:[3,2,1,0] row_mask:0xf bank_mask:0xf
	v_min_u32_dpp v28, v5, v9 quad_perm:[3,2,1,0] row_mask:0xf bank_mask:0xf
	v_max_u32_dpp v29, v5, v9 quad_perm:[3,2,1,0] row_mask:0xf bank_mask:0xf
	v_min_u32_dpp v30, v9, v5 quad_perm:[3,2,1,0] row_mask:0xf bank_mask:0xf
	v_max_u32_dpp v31, v9, v5 quad_perm:[3,2,1,0] row_mask:0xf bank_mask:0xf
	v_min_u32_dpp v32, v10, v6 quad_perm:[3,2,1,0] row_mask:0xf bank_mask:0xf
	v_max_u32_dpp v33, v10, v6 quad_perm:[3,2,1,0] row_mask:0xf bank_mask:0xf
	v_min_u32_dpp v34, v6, v10 quad_perm:[3,2,1,0] row_mask:0xf bank_mask:0xf
	v_max_u32_dpp v35, v6, v10 quad_perm:[3,2,1,0] row_mask:0xf bank_mask:0xf
	v_min_u32_dpp v36, v20, v14 quad_perm:[3,2,1,0] row_mask:0xf bank_mask:0xf
	v_max_u32_dpp v37, v20, v14 quad_perm:[3,2,1,0] row_mask:0xf bank_mask:0xf
	v_min_u32_dpp v38, v14, v20 quad_perm:[3,2,1,0] row_mask:0xf bank_mask:0xf
	v_max_u32_dpp v39, v14, v20 quad_perm:[3,2,1,0] row_mask:0xf bank_mask:0xf
	v_cndmask_b32_e64 v8, v25, v24, s[88:89]
	v_cndmask_b32_e64 v13, v27, v26, s[88:89]
	v_cndmask_b32_e64 v9, v29, v28, s[88:89]
	v_cndmask_b32_e64 v5, v31, v30, s[88:89]
	v_cndmask_b32_e64 v6, v33, v32, s[88:89]
	v_cndmask_b32_e64 v10, v35, v34, s[88:89]
	v_cndmask_b32_e64 v14, v37, v36, s[88:89]
	v_cndmask_b32_e64 v20, v39, v38, s[88:89]
	s_nop 1
	s_mov_b32 s88, 0x55555555
	s_mov_b32 s89, 0x55555555
	s_nop 1
	v_min_u32_dpp v24, v0, v0 quad_perm:[1,0,3,2] row_mask:0xf bank_mask:0xf
	v_max_u32_dpp v25, v0, v0 quad_perm:[1,0,3,2] row_mask:0xf bank_mask:0xf
	v_min_u32_dpp v26, v17, v17 quad_perm:[1,0,3,2] row_mask:0xf bank_mask:0xf
	v_max_u32_dpp v27, v17, v17 quad_perm:[1,0,3,2] row_mask:0xf bank_mask:0xf
	v_min_u32_dpp v28, v4, v4 quad_perm:[1,0,3,2] row_mask:0xf bank_mask:0xf
	v_max_u32_dpp v29, v4, v4 quad_perm:[1,0,3,2] row_mask:0xf bank_mask:0xf
	v_min_u32_dpp v30, v19, v19 quad_perm:[1,0,3,2] row_mask:0xf bank_mask:0xf
	v_max_u32_dpp v31, v19, v19 quad_perm:[1,0,3,2] row_mask:0xf bank_mask:0xf
	v_min_u32_dpp v32, v8, v8 quad_perm:[1,0,3,2] row_mask:0xf bank_mask:0xf
; DEV void sort_lists(int lane, int& myi0, int& myi1, float& myg0, float& myg1) {
; #pragma unroll
;     for (int k = 2; k <= 128; k <<= 1) {
; #pragma unroll
;       for (int j = k >> 1; j >= 1; j >>= 1) {
;         if (j == 64) {
;           const bool sw_ = myi1 < myi0;
;           const int ti = sw_ ? myi1 : myi0, tj = sw_ ? myi0 : myi1; const float tg = sw_ ? myg1 : myg0, th = sw_ ? myg0 : myg1;
;           myi0 = ti; myi1 = tj; myg0 = tg; myg1 = th;
;         } else {
;           const bool lower = (lane & j) == 0;
;           {
;             const bool up = (k == 128) ? true : ((k == 64) ? true : ((lane & k) == 0));
;             const int oi = __shfl_xor(myi0, j); const float og = __shfl_xor(myg0, j);
;             const bool take = (lower == up) ? (oi < myi0) : (oi > myi0);
;             myi0 = take ? oi : myi0; myg0 = take ? og : myg0;
;           }
;           {
;             const bool up = (k == 128) ? true : ((k == 64) ? false : ((lane & k) == 0));
;             const int oi = __shfl_xor(myi1, j); const float og = __shfl_xor(myg1, j);
;             const bool take = (lower == up) ? (oi < myi1) : (oi > myi1);
;             myi1 = take ? oi : myi1; myg1 = take ? og : myg1;
;           }
;         }
;       }
;     }
; }
	v_max_u32_dpp v33, v8, v8 quad_perm:[1,0,3,2] row_mask:0xf bank_mask:0xf
	v_min_u32_dpp v34, v9, v9 quad_perm:[1,0,3,2] row_mask:0xf bank_mask:0xf
	v_max_u32_dpp v35, v9, v9 quad_perm:[1,0,3,2] row_mask:0xf bank_mask:0xf
	v_min_u32_dpp v36, v6, v6 quad_perm:[1,0,3,2] row_mask:0xf bank_mask:0xf
	v_max_u32_dpp v37, v6, v6 quad_perm:[1,0,3,2] row_mask:0xf bank_mask:0xf
	v_min_u32_dpp v38, v14, v14 quad_perm:[1,0,3,2] row_mask:0xf bank_mask:0xf
	v_max_u32_dpp v39, v14, v14 quad_perm:[1,0,3,2] row_mask:0xf bank_mask:0xf
	v_cndmask_b32_e64 v0, v25, v24, s[88:89]
	v_cndmask_b32_e64 v17, v27, v26, s[88:89]
	v_cndmask_b32_e64 v4, v29, v28, s[88:89]
	v_cndmask_b32_e64 v19, v31, v30, s[88:89]
	v_cndmask_b32_e64 v8, v33, v32, s[88:89]
	v_cndmask_b32_e64 v9, v35, v34, s[88:89]
	v_cndmask_b32_e64 v6, v37, v36, s[88:89]
	v_cndmask_b32_e64 v14, v39, v38, s[88:89]
	s_nop 1
	v_min_u32_dpp v24, v20, v20 quad_perm:[1,0,3,2] row_mask:0xf bank_mask:0xf
	v_max_u32_dpp v25, v20, v20 quad_perm:[1,0,3,2] row_mask:0xf bank_mask:0xf
	v_min_u32_dpp v26, v10, v10 quad_perm:[1,0,3,2] row_mask:0xf bank_mask:0xf
	v_max_u32_dpp v27, v10, v10 quad_perm:[1,0,3,2] row_mask:0xf bank_mask:0xf
	v_min_u32_dpp v28, v5, v5 quad_perm:[1,0,3,2] row_mask:0xf bank_mask:0xf
	v_max_u32_dpp v29, v5, v5 quad_perm:[1,0,3,2] row_mask:0xf bank_mask:0xf
	v_min_u32_dpp v30, v13, v13 quad_perm:[1,0,3,2] row_mask:0xf bank_mask:0xf
	v_max_u32_dpp v31, v13, v13 quad_perm:[1,0,3,2] row_mask:0xf bank_mask:0xf
	v_min_u32_dpp v32, v22, v22 quad_perm:[1,0,3,2] row_mask:0xf bank_mask:0xf
	v_max_u32_dpp v33, v22, v22 quad_perm:[1,0,3,2] row_mask:0xf bank_mask:0xf
	v_min_u32_dpp v34, v7, v7 quad_perm:[1,0,3,2] row_mask:0xf bank_mask:0xf
	v_max_u32_dpp v35, v7, v7 quad_perm:[1,0,3,2] row_mask:0xf bank_mask:0xf
	v_min_u32_dpp v36, v23, v23 quad_perm:[1,0,3,2] row_mask:0xf bank_mask:0xf
	v_max_u32_dpp v37, v23, v23 quad_perm:[1,0,3,2] row_mask:0xf bank_mask:0xf
	v_min_u32_dpp v38, v15, v15 quad_perm:[1,0,3,2] row_mask:0xf bank_mask:0xf
	v_max_u32_dpp v39, v15, v15 quad_perm:[1,0,3,2] row_mask:0xf bank_mask:0xf
	v_cndmask_b32_e64 v20, v25, v24, s[88:89]
	v_cndmask_b32_e64 v10, v27, v26, s[88:89]
	v_cndmask_b32_e64 v5, v29, v28, s[88:89]
	v_cndmask_b32_e64 v13, v31, v30, s[88:89]
	v_cndmask_b32_e64 v22, v33, v32, s[88:89]
	v_cndmask_b32_e64 v7, v35, v34, s[88:89]
	v_cndmask_b32_e64 v23, v37, v36, s[88:89]
	v_cndmask_b32_e64 v15, v39, v38, s[88:89]
	s_nop 1
	v_min_u32_e32 v16, v0, v20
	v_min_u32_e32 v2, v17, v10
	v_min_u32_e32 v1, v4, v5
	v_min_u32_e32 v21, v19, v13
	v_min_u32_e32 v18, v8, v22
	v_min_u32_e32 v12, v9, v7
	v_min_u32_e32 v3, v6, v23
	v_min_u32_e32 v11, v14, v15
	v_max_u32_e32 v20, v0, v20
	v_max_u32_e32 v10, v17, v10
	v_max_u32_e32 v5, v4, v5
	v_max_u32_e32 v13, v19, v13
	v_max_u32_e32 v22, v8, v22
	v_max_u32_e32 v7, v9, v7
	v_max_u32_e32 v23, v6, v23
	v_max_u32_e32 v15, v14, v15
	v_min_u32_e32 v0, v16, v18
	v_min_u32_e32 v17, v2, v12
	v_min_u32_e32 v4, v1, v3
	v_min_u32_e32 v19, v21, v11
	v_min_u32_e32 v8, v20, v22
	v_min_u32_e32 v9, v10, v7
	v_min_u32_e32 v6, v5, v23
	v_min_u32_e32 v14, v13, v15
	v_max_u32_e32 v18, v16, v18
	v_max_u32_e32 v12, v2, v12
	v_max_u32_e32 v3, v1, v3
	v_max_u32_e32 v11, v21, v11
	v_max_u32_e32 v22, v20, v22
	v_max_u32_e32 v7, v10, v7
	v_max_u32_e32 v23, v5, v23
	v_max_u32_e32 v15, v13, v15
	v_min_u32_e32 v16, v0, v4
	v_min_u32_e32 v2, v17, v19
	v_min_u32_e32 v1, v18, v3
	v_min_u32_e32 v21, v12, v11
	v_min_u32_e32 v20, v8, v6
	v_min_u32_e32 v10, v9, v14
	v_min_u32_e32 v5, v22, v23
	v_min_u32_e32 v13, v7, v15
	v_max_u32_e32 v4, v0, v4
	v_max_u32_e32 v19, v17, v19
	v_max_u32_e32 v3, v18, v3
	v_max_u32_e32 v11, v12, v11
	v_max_u32_e32 v6, v8, v6
	v_max_u32_e32 v14, v9, v14
	v_max_u32_e32 v23, v22, v23
	v_max_u32_e32 v15, v7, v15
	v_min_u32_e32 v0, v16, v2
	v_min_u32_e32 v17, v4, v19
	v_min_u32_e32 v18, v1, v21
	v_min_u32_e32 v12, v3, v11
	v_min_u32_e32 v8, v20, v10
	v_min_u32_e32 v9, v6, v14
	v_min_u32_e32 v22, v5, v13
	v_min_u32_e32 v7, v23, v15
	v_max_u32_e32 v2, v16, v2
	v_max_u32_e32 v19, v4, v19
	v_max_u32_e32 v21, v1, v21
	v_max_u32_e32 v11, v3, v11
	v_max_u32_e32 v10, v20, v10
	v_max_u32_e32 v14, v6, v14
	v_max_u32_e32 v13, v5, v13
	v_max_u32_e32 v15, v23, v15
	s_mov_b32 s88, 0xf0f0f0f
	s_mov_b32 s89, 0xf0f0f0f
	s_nop 1
	v_min_u32_dpp v24, v15, v0 row_half_mirror row_mask:0xf bank_mask:0xf
	v_max_u32_dpp v25, v15, v0 row_half_mirror row_mask:0xf bank_mask:0xf
	v_min_u32_dpp v26, v0, v15 row_half_mirror row_mask:0xf bank_mask:0xf
	v_max_u32_dpp v27, v0, v15 row_half_mirror row_mask:0xf bank_mask:0xf
	v_min_u32_dpp v28, v7, v2 row_half_mirror row_mask:0xf bank_mask:0xf
	v_max_u32_dpp v29, v7, v2 row_half_mirror row_mask:0xf bank_mask:0xf
	v_min_u32_dpp v30, v2, v7 row_half_mirror row_mask:0xf bank_mask:0xf
	v_max_u32_dpp v31, v2, v7 row_half_mirror row_mask:0xf bank_mask:0xf
	v_min_u32_dpp v32, v13, v17 row_half_mirror row_mask:0xf bank_mask:0xf
	v_max_u32_dpp v33, v13, v17 row_half_mirror row_mask:0xf bank_mask:0xf
	v_min_u32_dpp v34, v17, v13 row_half_mirror row_mask:0xf bank_mask:0xf
	v_max_u32_dpp v35, v17, v13 row_half_mirror row_mask:0xf bank_mask:0xf
	v_min_u32_dpp v36, v22, v19 row_half_mirror row_mask:0xf bank_mask:0xf
	v_max_u32_dpp v37, v22, v19 row_half_mirror row_mask:0xf bank_mask:0xf
	v_min_u32_dpp v38, v19, v22 row_half_mirror row_mask:0xf bank_mask:0xf
	v_max_u32_dpp v39, v19, v22 row_half_mirror row_mask:0xf bank_mask:0xf
	v_cndmask_b32_e64 v0, v25, v24, s[88:89]
	v_cndmask_b32_e64 v15, v27, v26, s[88:89]
	v_cndmask_b32_e64 v2, v29, v28, s[88:89]
	v_cndmask_b32_e64 v7, v31, v30, s[88:89]
	v_cndmask_b32_e64 v17, v33, v32, s[88:89]
; DEV void sort_lists(int lane, int& myi0, int& myi1, float& myg0, float& myg1) {
; #pragma unroll
;     for (int k = 2; k <= 128; k <<= 1) {
; #pragma unroll
;       for (int j = k >> 1; j >= 1; j >>= 1) {
;         if (j == 64) {
;           const bool sw_ = myi1 < myi0;
;           const int ti = sw_ ? myi1 : myi0, tj = sw_ ? myi0 : myi1; const float tg = sw_ ? myg1 : myg0, th = sw_ ? myg0 : myg1;
;           myi0 = ti; myi1 = tj; myg0 = tg; myg1 = th;
;         } else {
;           const bool lower = (lane & j) == 0;
;           {
;             const bool up = (k == 128) ? true : ((k == 64) ? true : ((lane & k) == 0));
;             const int oi = __shfl_xor(myi0, j); const float og = __shfl_xor(myg0, j);
;             const bool take = (lower == up) ? (oi < myi0) : (oi > myi0);
;             myi0 = take ? oi : myi0; myg0 = take ? og : myg0;
;           }
;           {
;             const bool up = (k == 128) ? true : ((k == 64) ? false : ((lane & k) == 0));
;             const int oi = __shfl_xor(myi1, j); const float og = __shfl_xor(myg1, j);
;             const bool take = (lower == up) ? (oi < myi1) : (oi > myi1);
;             myi1 = take ? oi : myi1; myg1 = take ? og : myg1;
;           }
;         }
;       }
;     }
; }
	v_cndmask_b32_e64 v13, v35, v34, s[88:89]
	v_cndmask_b32_e64 v19, v37, v36, s[88:89]
	v_cndmask_b32_e64 v22, v39, v38, s[88:89]
	s_nop 1
	v_min_u32_dpp v24, v14, v18 row_half_mirror row_mask:0xf bank_mask:0xf
	v_max_u32_dpp v25, v14, v18 row_half_mirror row_mask:0xf bank_mask:0xf
	v_min_u32_dpp v26, v18, v14 row_half_mirror row_mask:0xf bank_mask:0xf
	v_max_u32_dpp v27, v18, v14 row_half_mirror row_mask:0xf bank_mask:0xf
	v_min_u32_dpp v28, v9, v21 row_half_mirror row_mask:0xf bank_mask:0xf
	v_max_u32_dpp v29, v9, v21 row_half_mirror row_mask:0xf bank_mask:0xf
	v_min_u32_dpp v30, v21, v9 row_half_mirror row_mask:0xf bank_mask:0xf
	v_max_u32_dpp v31, v21, v9 row_half_mirror row_mask:0xf bank_mask:0xf
	v_min_u32_dpp v32, v10, v12 row_half_mirror row_mask:0xf bank_mask:0xf
	v_max_u32_dpp v33, v10, v12 row_half_mirror row_mask:0xf bank_mask:0xf
	v_min_u32_dpp v34, v12, v10 row_half_mirror row_mask:0xf bank_mask:0xf
	v_max_u32_dpp v35, v12, v10 row_half_mirror row_mask:0xf bank_mask:0xf
	v_min_u32_dpp v36, v8, v11 row_half_mirror row_mask:0xf bank_mask:0xf
	v_max_u32_dpp v37, v8, v11 row_half_mirror row_mask:0xf bank_mask:0xf
	v_min_u32_dpp v38, v11, v8 row_half_mirror row_mask:0xf bank_mask:0xf
	v_max_u32_dpp v39, v11, v8 row_half_mirror row_mask:0xf bank_mask:0xf
	v_cndmask_b32_e64 v18, v25, v24, s[88:89]
	v_cndmask_b32_e64 v14, v27, v26, s[88:89]
	v_cndmask_b32_e64 v21, v29, v28, s[88:89]
	v_cndmask_b32_e64 v9, v31, v30, s[88:89]
	v_cndmask_b32_e64 v12, v33, v32, s[88:89]
	v_cndmask_b32_e64 v10, v35, v34, s[88:89]
	v_cndmask_b32_e64 v11, v37, v36, s[88:89]
	v_cndmask_b32_e64 v8, v39, v38, s[88:89]
	s_nop 1
	s_mov_b32 s88, 0x33333333
	s_mov_b32 s89, 0x33333333
	s_nop 1
	v_min_u32_dpp v24, v0, v0 quad_perm:[2,3,0,1] row_mask:0xf bank_mask:0xf
	v_max_u32_dpp v25, v0, v0 quad_perm:[2,3,0,1] row_mask:0xf bank_mask:0xf
	v_min_u32_dpp v26, v2, v2 quad_perm:[2,3,0,1] row_mask:0xf bank_mask:0xf
	v_max_u32_dpp v27, v2, v2 quad_perm:[2,3,0,1] row_mask:0xf bank_mask:0xf
	v_min_u32_dpp v28, v17, v17 quad_perm:[2,3,0,1] row_mask:0xf bank_mask:0xf
	v_max_u32_dpp v29, v17, v17 quad_perm:[2,3,0,1] row_mask:0xf bank_mask:0xf
	v_min_u32_dpp v30, v19, v19 quad_perm:[2,3,0,1] row_mask:0xf bank_mask:0xf
	v_max_u32_dpp v31, v19, v19 quad_perm:[2,3,0,1] row_mask:0xf bank_mask:0xf
	v_min_u32_dpp v32, v18, v18 quad_perm:[2,3,0,1] row_mask:0xf bank_mask:0xf
	v_max_u32_dpp v33, v18, v18 quad_perm:[2,3,0,1] row_mask:0xf bank_mask:0xf
	v_min_u32_dpp v34, v21, v21 quad_perm:[2,3,0,1] row_mask:0xf bank_mask:0xf
	v_max_u32_dpp v35, v21, v21 quad_perm:[2,3,0,1] row_mask:0xf bank_mask:0xf
	v_min_u32_dpp v36, v12, v12 quad_perm:[2,3,0,1] row_mask:0xf bank_mask:0xf
	v_max_u32_dpp v37, v12, v12 quad_perm:[2,3,0,1] row_mask:0xf bank_mask:0xf
	v_min_u32_dpp v38, v11, v11 quad_perm:[2,3,0,1] row_mask:0xf bank_mask:0xf
	v_max_u32_dpp v39, v11, v11 quad_perm:[2,3,0,1] row_mask:0xf bank_mask:0xf
	v_cndmask_b32_e64 v0, v25, v24, s[88:89]
	v_cndmask_b32_e64 v2, v27, v26, s[88:89]
	v_cndmask_b32_e64 v17, v29, v28, s[88:89]
	v_cndmask_b32_e64 v19, v31, v30, s[88:89]
	v_cndmask_b32_e64 v18, v33, v32, s[88:89]
	v_cndmask_b32_e64 v21, v35, v34, s[88:89]
	v_cndmask_b32_e64 v12, v37, v36, s[88:89]
	v_cndmask_b32_e64 v11, v39, v38, s[88:89]
	s_nop 1
	v_min_u32_dpp v24, v8, v8 quad_perm:[2,3,0,1] row_mask:0xf bank_mask:0xf
	v_max_u32_dpp v25, v8, v8 quad_perm:[2,3,0,1] row_mask:0xf bank_mask:0xf
	v_min_u32_dpp v26, v10, v10 quad_perm:[2,3,0,1] row_mask:0xf bank_mask:0xf
	v_max_u32_dpp v27, v10, v10 quad_perm:[2,3,0,1] row_mask:0xf bank_mask:0xf
	v_min_u32_dpp v28, v9, v9 quad_perm:[2,3,0,1] row_mask:0xf bank_mask:0xf
	v_max_u32_dpp v29, v9, v9 quad_perm:[2,3,0,1] row_mask:0xf bank_mask:0xf
	v_min_u32_dpp v30, v14, v14 quad_perm:[2,3,0,1] row_mask:0xf bank_mask:0xf
	v_max_u32_dpp v31, v14, v14 quad_perm:[2,3,0,1] row_mask:0xf bank_mask:0xf
	v_min_u32_dpp v32, v22, v22 quad_perm:[2,3,0,1] row_mask:0xf bank_mask:0xf
	v_max_u32_dpp v33, v22, v22 quad_perm:[2,3,0,1] row_mask:0xf bank_mask:0xf
	v_min_u32_dpp v34, v13, v13 quad_perm:[2,3,0,1] row_mask:0xf bank_mask:0xf
	v_max_u32_dpp v35, v13, v13 quad_perm:[2,3,0,1] row_mask:0xf bank_mask:0xf
	v_min_u32_dpp v36, v7, v7 quad_perm:[2,3,0,1] row_mask:0xf bank_mask:0xf
	v_max_u32_dpp v37, v7, v7 quad_perm:[2,3,0,1] row_mask:0xf bank_mask:0xf
	v_min_u32_dpp v38, v15, v15 quad_perm:[2,3,0,1] row_mask:0xf bank_mask:0xf
	v_max_u32_dpp v39, v15, v15 quad_perm:[2,3,0,1] row_mask:0xf bank_mask:0xf
	v_cndmask_b32_e64 v8, v25, v24, s[88:89]
	v_cndmask_b32_e64 v10, v27, v26, s[88:89]
	v_cndmask_b32_e64 v9, v29, v28, s[88:89]
	v_cndmask_b32_e64 v14, v31, v30, s[88:89]
	v_cndmask_b32_e64 v22, v33, v32, s[88:89]
	v_cndmask_b32_e64 v13, v35, v34, s[88:89]
	v_cndmask_b32_e64 v7, v37, v36, s[88:89]
	v_cndmask_b32_e64 v15, v39, v38, s[88:89]
	s_nop 1
	s_mov_b32 s88, 0x55555555
	s_mov_b32 s89, 0x55555555
	s_nop 1
	v_min_u32_dpp v24, v0, v0 quad_perm:[1,0,3,2] row_mask:0xf bank_mask:0xf
	v_max_u32_dpp v25, v0, v0 quad_perm:[1,0,3,2] row_mask:0xf bank_mask:0xf
	v_min_u32_dpp v26, v2, v2 quad_perm:[1,0,3,2] row_mask:0xf bank_mask:0xf
	v_max_u32_dpp v27, v2, v2 quad_perm:[1,0,3,2] row_mask:0xf bank_mask:0xf
	v_min_u32_dpp v28, v17, v17 quad_perm:[1,0,3,2] row_mask:0xf bank_mask:0xf
	v_max_u32_dpp v29, v17, v17 quad_perm:[1,0,3,2] row_mask:0xf bank_mask:0xf
	v_min_u32_dpp v30, v19, v19 quad_perm:[1,0,3,2] row_mask:0xf bank_mask:0xf
	v_max_u32_dpp v31, v19, v19 quad_perm:[1,0,3,2] row_mask:0xf bank_mask:0xf
	v_min_u32_dpp v32, v18, v18 quad_perm:[1,0,3,2] row_mask:0xf bank_mask:0xf
	v_max_u32_dpp v33, v18, v18 quad_perm:[1,0,3,2] row_mask:0xf bank_mask:0xf
; DEV int tid_l() { int t = threadIdx.x; asm volatile("" : "+v"(t)); return t; }
; DEV void sort_lists(int lane, int& myi0, int& myi1, float& myg0, float& myg1) {
; #pragma unroll
;     for (int k = 2; k <= 128; k <<= 1) {
; #pragma unroll
;       for (int j = k >> 1; j >= 1; j >>= 1) {
;         if (j == 64) {
;           const bool sw_ = myi1 < myi0;
;           const int ti = sw_ ? myi1 : myi0, tj = sw_ ? myi0 : myi1; const float tg = sw_ ? myg1 : myg0, th = sw_ ? myg0 : myg1;
;           myi0 = ti; myi1 = tj; myg0 = tg; myg1 = th;
;         } else {
;           const bool lower = (lane & j) == 0;
;           {
;             const bool up = (k == 128) ? true : ((k == 64) ? true : ((lane & k) == 0));
;             const int oi = __shfl_xor(myi0, j); const float og = __shfl_xor(myg0, j);
;             const bool take = (lower == up) ? (oi < myi0) : (oi > myi0);
;             myi0 = take ? oi : myi0; myg0 = take ? og : myg0;
;           }
;           {
;             const bool up = (k == 128) ? true : ((k == 64) ? false : ((lane & k) == 0));
;             const int oi = __shfl_xor(myi1, j); const float og = __shfl_xor(myg1, j);
;             const bool take = (lower == up) ? (oi < myi1) : (oi > myi1);
;             myi1 = take ? oi : myi1; myg1 = take ? og : myg1;
;           }
;         }
;       }
;     }
; }
; DEV void peer_gather(const Params& P, int l, int m0, const int* idxs, const float* gs) {
;   const int tid = tid_l(), lane = tid & 63, wid = tid >> 6;
;   const unsigned char* U = P.ws + WS_TAB + (size_t)l * 32 * MB;
;   const unsigned char* V = U + 16 * MB;
;   bf16_t* hn = (bf16_t*)(P.ws + WS_HN);
;   const float* gp = P.norm_ple + l * DM;
;   const int row = lane >> 4, rmap = ((row & 1) << 1) | (row >> 1);
;   u32x4 nxa = *(const u32x4*)(hn + (size_t)(m0 + wid * 16) * DM + lane * 16), nxb = *(const u32x4*)(hn + (size_t)(m0 + wid * 16) * DM + lane * 16 + 8);
;   int ni0 = idxs[(wid * 16) * 128 + lane], ni1 = idxs[(wid * 16) * 128 + 64 + lane];
;   float ng0 = gs[(wid * 16) * 128 + lane], ng1 = gs[(wid * 16) * 128 + 64 + lane];
;   sort_lists(lane, ni0, ni1, ng0, ng1);
	v_min_u32_dpp v34, v21, v21 quad_perm:[1,0,3,2] row_mask:0xf bank_mask:0xf
	v_max_u32_dpp v35, v21, v21 quad_perm:[1,0,3,2] row_mask:0xf bank_mask:0xf
	v_min_u32_dpp v36, v12, v12 quad_perm:[1,0,3,2] row_mask:0xf bank_mask:0xf
	v_max_u32_dpp v37, v12, v12 quad_perm:[1,0,3,2] row_mask:0xf bank_mask:0xf
	v_min_u32_dpp v38, v11, v11 quad_perm:[1,0,3,2] row_mask:0xf bank_mask:0xf
	v_max_u32_dpp v39, v11, v11 quad_perm:[1,0,3,2] row_mask:0xf bank_mask:0xf
	v_cndmask_b32_e64 v0, v25, v24, s[88:89]
	v_cndmask_b32_e64 v2, v27, v26, s[88:89]
	v_cndmask_b32_e64 v17, v29, v28, s[88:89]
	v_cndmask_b32_e64 v19, v31, v30, s[88:89]
	v_cndmask_b32_e64 v18, v33, v32, s[88:89]
	v_cndmask_b32_e64 v21, v35, v34, s[88:89]
	v_cndmask_b32_e64 v12, v37, v36, s[88:89]
	v_cndmask_b32_e64 v11, v39, v38, s[88:89]
	s_nop 1
	v_min_u32_dpp v24, v8, v8 quad_perm:[1,0,3,2] row_mask:0xf bank_mask:0xf
	v_max_u32_dpp v25, v8, v8 quad_perm:[1,0,3,2] row_mask:0xf bank_mask:0xf
	v_min_u32_dpp v26, v10, v10 quad_perm:[1,0,3,2] row_mask:0xf bank_mask:0xf
	v_max_u32_dpp v27, v10, v10 quad_perm:[1,0,3,2] row_mask:0xf bank_mask:0xf
	v_min_u32_dpp v28, v9, v9 quad_perm:[1,0,3,2] row_mask:0xf bank_mask:0xf
	v_max_u32_dpp v29, v9, v9 quad_perm:[1,0,3,2] row_mask:0xf bank_mask:0xf
	v_min_u32_dpp v30, v14, v14 quad_perm:[1,0,3,2] row_mask:0xf bank_mask:0xf
	v_max_u32_dpp v31, v14, v14 quad_perm:[1,0,3,2] row_mask:0xf bank_mask:0xf
	v_min_u32_dpp v32, v22, v22 quad_perm:[1,0,3,2] row_mask:0xf bank_mask:0xf
	v_max_u32_dpp v33, v22, v22 quad_perm:[1,0,3,2] row_mask:0xf bank_mask:0xf
	v_min_u32_dpp v34, v13, v13 quad_perm:[1,0,3,2] row_mask:0xf bank_mask:0xf
	v_max_u32_dpp v35, v13, v13 quad_perm:[1,0,3,2] row_mask:0xf bank_mask:0xf
	v_min_u32_dpp v36, v7, v7 quad_perm:[1,0,3,2] row_mask:0xf bank_mask:0xf
	v_max_u32_dpp v37, v7, v7 quad_perm:[1,0,3,2] row_mask:0xf bank_mask:0xf
	v_min_u32_dpp v38, v15, v15 quad_perm:[1,0,3,2] row_mask:0xf bank_mask:0xf
	v_max_u32_dpp v39, v15, v15 quad_perm:[1,0,3,2] row_mask:0xf bank_mask:0xf
	v_cndmask_b32_e64 v8, v25, v24, s[88:89]
	v_cndmask_b32_e64 v10, v27, v26, s[88:89]
	v_cndmask_b32_e64 v9, v29, v28, s[88:89]
	v_cndmask_b32_e64 v14, v31, v30, s[88:89]
	v_cndmask_b32_e64 v22, v33, v32, s[88:89]
	v_cndmask_b32_e64 v13, v35, v34, s[88:89]
	v_cndmask_b32_e64 v7, v37, v36, s[88:89]
	v_cndmask_b32_e64 v15, v39, v38, s[88:89]
	s_nop 1
	v_min_u32_e32 v16, v0, v8
	v_min_u32_e32 v4, v2, v10
	v_min_u32_e32 v1, v17, v9
	v_min_u32_e32 v3, v19, v14
	v_min_u32_e32 v20, v18, v22
	v_min_u32_e32 v6, v21, v13
	v_min_u32_e32 v5, v12, v7
	v_min_u32_e32 v23, v11, v15
	v_max_u32_e32 v8, v0, v8
	v_max_u32_e32 v10, v2, v10
	v_max_u32_e32 v9, v17, v9
	v_max_u32_e32 v14, v19, v14
	v_max_u32_e32 v22, v18, v22
	v_max_u32_e32 v13, v21, v13
	v_max_u32_e32 v7, v12, v7
	v_max_u32_e32 v15, v11, v15
	v_min_u32_e32 v0, v16, v20
	v_min_u32_e32 v2, v4, v6
	v_min_u32_e32 v17, v1, v5
	v_min_u32_e32 v19, v3, v23
	v_min_u32_e32 v18, v8, v22
	v_min_u32_e32 v21, v10, v13
	v_min_u32_e32 v12, v9, v7
	v_min_u32_e32 v11, v14, v15
	v_max_u32_e32 v20, v16, v20
	v_max_u32_e32 v6, v4, v6
	v_max_u32_e32 v5, v1, v5
	v_max_u32_e32 v23, v3, v23
	v_max_u32_e32 v22, v8, v22
	v_max_u32_e32 v13, v10, v13
	v_max_u32_e32 v7, v9, v7
	v_max_u32_e32 v15, v14, v15
	v_min_u32_e32 v16, v0, v17
	v_min_u32_e32 v4, v2, v19
	v_min_u32_e32 v1, v20, v5
	v_min_u32_e32 v3, v6, v23
	v_min_u32_e32 v8, v18, v12
	v_min_u32_e32 v10, v21, v11
	v_min_u32_e32 v9, v22, v7
	v_min_u32_e32 v14, v13, v15
	v_max_u32_e32 v17, v0, v17
	v_max_u32_e32 v19, v2, v19
	v_max_u32_e32 v5, v20, v5
	v_max_u32_e32 v23, v6, v23
	v_max_u32_e32 v12, v18, v12
	v_max_u32_e32 v11, v21, v11
	v_max_u32_e32 v7, v22, v7
	v_max_u32_e32 v15, v13, v15
	v_min_u32_e32 v0, v16, v4
	v_min_u32_e32 v2, v17, v19
	v_min_u32_e32 v20, v1, v3
	v_min_u32_e32 v6, v5, v23
	v_min_u32_e32 v18, v8, v10
	v_min_u32_e32 v21, v12, v11
	v_min_u32_e32 v22, v9, v14
	v_min_u32_e32 v13, v7, v15
	v_max_u32_e32 v4, v16, v4
	v_max_u32_e32 v19, v17, v19
	v_max_u32_e32 v3, v1, v3
	v_max_u32_e32 v23, v5, v23
	v_max_u32_e32 v10, v8, v10
	v_max_u32_e32 v11, v12, v11
	v_max_u32_e32 v14, v9, v14
	v_max_u32_e32 v15, v7, v15
	ds_write_b32 v41, v0 offset:0
	ds_write_b32 v41, v4 offset:64
	ds_write_b32 v41, v2 offset:128
	ds_write_b32 v41, v19 offset:192
	ds_write_b32 v41, v20 offset:256
	ds_write_b32 v41, v3 offset:320
	ds_write_b32 v41, v6 offset:384
	ds_write_b32 v41, v23 offset:448
	ds_write_b32 v41, v18 offset:4
	ds_write_b32 v41, v10 offset:68
	ds_write_b32 v41, v21 offset:132
	ds_write_b32 v41, v11 offset:196
	ds_write_b32 v41, v22 offset:260
	ds_write_b32 v41, v14 offset:324
	ds_write_b32 v41, v13 offset:388
	ds_write_b32 v41, v15 offset:452
	global_load_dwordx4 v[0:3], v40, s[82:83] offset:0
	global_load_dwordx4 v[4:7], v40, s[82:83] offset:16
	global_load_dwordx4 v[8:11], v40, s[82:83] offset:32
	global_load_dwordx4 v[12:15], v40, s[82:83] offset:48
	s_waitcnt vmcnt(0)
; DEV void sort_lists(int lane, int& myi0, int& myi1, float& myg0, float& myg1) {
; #pragma unroll
;     for (int k = 2; k <= 128; k <<= 1) {
; #pragma unroll
;       for (int j = k >> 1; j >= 1; j >>= 1) {
;         if (j == 64) {
;           const bool sw_ = myi1 < myi0;
;           const int ti = sw_ ? myi1 : myi0, tj = sw_ ? myi0 : myi1; const float tg = sw_ ? myg1 : myg0, th = sw_ ? myg0 : myg1;
;           myi0 = ti; myi1 = tj; myg0 = tg; myg1 = th;
;         } else {
;           const bool lower = (lane & j) == 0;
;           {
;             const bool up = (k == 128) ? true : ((k == 64) ? true : ((lane & k) == 0));
;             const int oi = __shfl_xor(myi0, j); const float og = __shfl_xor(myg0, j);
;             const bool take = (lower == up) ? (oi < myi0) : (oi > myi0);
;             myi0 = take ? oi : myi0; myg0 = take ? og : myg0;
;           }
;           {
;             const bool up = (k == 128) ? true : ((k == 64) ? false : ((lane & k) == 0));
;             const int oi = __shfl_xor(myi1, j); const float og = __shfl_xor(myg1, j);
;             const bool take = (lower == up) ? (oi < myi1) : (oi > myi1);
;             myi1 = take ? oi : myi1; myg1 = take ? og : myg1;
;           }
;         }
;       }
;     }
; }
	v_lshl_or_b32 v0, v0, 7, v235
	v_lshl_or_b32 v1, v1, 7, v235
	v_lshl_or_b32 v2, v2, 7, v235
	v_lshl_or_b32 v3, v3, 7, v235
	v_lshl_or_b32 v4, v4, 7, v235
	v_lshl_or_b32 v5, v5, 7, v235
	v_lshl_or_b32 v6, v6, 7, v235
	v_lshl_or_b32 v7, v7, 7, v235
	v_lshl_or_b32 v8, v8, 7, v235
	v_lshl_or_b32 v9, v9, 7, v235
	v_lshl_or_b32 v10, v10, 7, v235
	v_lshl_or_b32 v11, v11, 7, v235
	v_lshl_or_b32 v12, v12, 7, v235
	v_lshl_or_b32 v13, v13, 7, v235
	v_lshl_or_b32 v14, v14, 7, v235
	v_lshl_or_b32 v15, v15, 7, v235
	v_or_b32_e32 v1, 1, v1
	v_or_b32_e32 v2, 2, v2
	v_or_b32_e32 v3, 3, v3
	v_or_b32_e32 v4, 4, v4
	v_or_b32_e32 v5, 5, v5
	v_or_b32_e32 v6, 6, v6
	v_or_b32_e32 v7, 7, v7
	v_or_b32_e32 v8, 8, v8
	v_or_b32_e32 v9, 9, v9
	v_or_b32_e32 v10, 10, v10
	v_or_b32_e32 v11, 11, v11
	v_or_b32_e32 v12, 12, v12
	v_or_b32_e32 v13, 13, v13
	v_or_b32_e32 v14, 14, v14
	v_or_b32_e32 v15, 15, v15
	v_min_u32_e32 v16, v0, v1
	v_min_u32_e32 v17, v2, v3
	v_min_u32_e32 v18, v4, v5
	v_min_u32_e32 v19, v6, v7
	v_min_u32_e32 v20, v8, v9
	v_min_u32_e32 v21, v10, v11
	v_min_u32_e32 v22, v12, v13
	v_min_u32_e32 v23, v14, v15
	v_max_u32_e32 v1, v0, v1
	v_max_u32_e32 v3, v2, v3
	v_max_u32_e32 v5, v4, v5
	v_max_u32_e32 v7, v6, v7
	v_max_u32_e32 v9, v8, v9
	v_max_u32_e32 v11, v10, v11
	v_max_u32_e32 v13, v12, v13
	v_max_u32_e32 v15, v14, v15
	v_min_u32_e32 v0, v16, v3
	v_min_u32_e32 v2, v1, v17
	v_min_u32_e32 v4, v18, v7
	v_min_u32_e32 v6, v5, v19
	v_min_u32_e32 v8, v20, v11
	v_min_u32_e32 v10, v9, v21
	v_min_u32_e32 v12, v22, v15
	v_min_u32_e32 v14, v13, v23
	v_max_u32_e32 v3, v16, v3
	v_max_u32_e32 v17, v1, v17
	v_max_u32_e32 v7, v18, v7
	v_max_u32_e32 v19, v5, v19
	v_max_u32_e32 v11, v20, v11
	v_max_u32_e32 v21, v9, v21
	v_max_u32_e32 v15, v22, v15
	v_max_u32_e32 v23, v13, v23
	v_min_u32_e32 v16, v0, v2
	v_min_u32_e32 v1, v17, v3
	v_min_u32_e32 v18, v4, v6
	v_min_u32_e32 v5, v19, v7
	v_min_u32_e32 v20, v8, v10
	v_min_u32_e32 v9, v21, v11
	v_min_u32_e32 v22, v12, v14
	v_min_u32_e32 v13, v23, v15
	v_max_u32_e32 v2, v0, v2
	v_max_u32_e32 v3, v17, v3
	v_max_u32_e32 v6, v4, v6
	v_max_u32_e32 v7, v19, v7
	v_max_u32_e32 v10, v8, v10
	v_max_u32_e32 v11, v21, v11
	v_max_u32_e32 v14, v12, v14
	v_max_u32_e32 v15, v23, v15
	v_min_u32_e32 v0, v16, v7
	v_min_u32_e32 v17, v2, v5
	v_min_u32_e32 v4, v1, v6
	v_min_u32_e32 v19, v3, v18
	v_min_u32_e32 v8, v20, v15
	v_min_u32_e32 v21, v10, v13
	v_min_u32_e32 v12, v9, v14
	v_min_u32_e32 v23, v11, v22
	v_max_u32_e32 v7, v16, v7
	v_max_u32_e32 v5, v2, v5
	v_max_u32_e32 v6, v1, v6
	v_max_u32_e32 v18, v3, v18
	v_max_u32_e32 v15, v20, v15
	v_max_u32_e32 v13, v10, v13
	v_max_u32_e32 v14, v9, v14
	v_max_u32_e32 v22, v11, v22
	v_min_u32_e32 v16, v0, v4
	v_min_u32_e32 v2, v17, v19
	v_min_u32_e32 v1, v18, v5
	v_min_u32_e32 v3, v6, v7
	v_min_u32_e32 v20, v8, v12
	v_min_u32_e32 v10, v21, v23
	v_min_u32_e32 v9, v22, v13
	v_min_u32_e32 v11, v14, v15
	v_max_u32_e32 v4, v0, v4
	v_max_u32_e32 v19, v17, v19
	v_max_u32_e32 v5, v18, v5
	v_max_u32_e32 v7, v6, v7
	v_max_u32_e32 v12, v8, v12
	v_max_u32_e32 v23, v21, v23
	v_max_u32_e32 v13, v22, v13
	v_max_u32_e32 v15, v14, v15
	v_min_u32_e32 v0, v16, v2
	v_min_u32_e32 v17, v4, v19
	v_min_u32_e32 v18, v1, v3
	v_min_u32_e32 v6, v5, v7
	v_min_u32_e32 v8, v20, v10
	v_min_u32_e32 v21, v12, v23
	v_min_u32_e32 v22, v9, v11
	v_min_u32_e32 v14, v13, v15
	v_max_u32_e32 v2, v16, v2
	v_max_u32_e32 v19, v4, v19
	v_max_u32_e32 v3, v1, v3
	v_max_u32_e32 v7, v5, v7
	v_max_u32_e32 v10, v20, v10
	v_max_u32_e32 v23, v12, v23
	v_max_u32_e32 v11, v9, v11
	v_max_u32_e32 v15, v13, v15
	v_min_u32_e32 v16, v0, v15
	v_min_u32_e32 v4, v2, v14
	v_min_u32_e32 v1, v17, v11
	v_min_u32_e32 v5, v19, v22
	v_min_u32_e32 v20, v18, v23
	v_min_u32_e32 v12, v3, v21
	v_min_u32_e32 v9, v6, v10
	v_min_u32_e32 v13, v7, v8
	v_max_u32_e32 v15, v0, v15
	v_max_u32_e32 v14, v2, v14
	v_max_u32_e32 v11, v17, v11
	v_max_u32_e32 v22, v19, v22
	v_max_u32_e32 v23, v18, v23
	v_max_u32_e32 v21, v3, v21
	v_max_u32_e32 v10, v6, v10
	v_max_u32_e32 v8, v7, v8
	v_min_u32_e32 v0, v16, v20
	v_min_u32_e32 v2, v4, v12
	v_min_u32_e32 v17, v1, v9
	v_min_u32_e32 v19, v5, v13
	v_min_u32_e32 v18, v8, v22
	v_min_u32_e32 v3, v10, v11
	v_min_u32_e32 v6, v21, v14
	v_min_u32_e32 v7, v23, v15
	v_max_u32_e32 v20, v16, v20
	v_max_u32_e32 v12, v4, v12
	v_max_u32_e32 v9, v1, v9
	v_max_u32_e32 v13, v5, v13
	v_max_u32_e32 v22, v8, v22
	v_max_u32_e32 v11, v10, v11
	v_max_u32_e32 v14, v21, v14
	v_max_u32_e32 v15, v23, v15
	v_min_u32_e32 v16, v0, v17
	v_min_u32_e32 v4, v2, v19
	v_min_u32_e32 v1, v20, v9
	v_min_u32_e32 v5, v12, v13
	v_min_u32_e32 v8, v18, v6
	v_min_u32_e32 v10, v3, v7
	v_min_u32_e32 v21, v22, v14
	v_min_u32_e32 v23, v11, v15
	v_max_u32_e32 v17, v0, v17
	v_max_u32_e32 v19, v2, v19
	v_max_u32_e32 v9, v20, v9
	v_max_u32_e32 v13, v12, v13
	v_max_u32_e32 v6, v18, v6
	v_max_u32_e32 v7, v3, v7
	v_max_u32_e32 v14, v22, v14
	v_max_u32_e32 v15, v11, v15
	v_min_u32_e32 v0, v16, v4
	v_min_u32_e32 v2, v17, v19
	v_min_u32_e32 v20, v1, v5
	v_min_u32_e32 v12, v9, v13
	v_min_u32_e32 v18, v8, v10
	v_min_u32_e32 v3, v6, v7
	v_min_u32_e32 v22, v21, v23
	v_min_u32_e32 v11, v14, v15
	v_max_u32_e32 v4, v16, v4
	v_max_u32_e32 v19, v17, v19
	v_max_u32_e32 v5, v1, v5
	v_max_u32_e32 v13, v9, v13
	v_max_u32_e32 v10, v8, v10
	v_max_u32_e32 v7, v6, v7
	v_max_u32_e32 v23, v21, v23
	v_max_u32_e32 v15, v14, v15
	s_mov_b32 s88, 0x55555555
	s_mov_b32 s89, 0x55555555
	s_nop 1
	v_min_u32_dpp v24, v15, v0 quad_perm:[1,0,3,2] row_mask:0xf bank_mask:0xf
	v_max_u32_dpp v25, v15, v0 quad_perm:[1,0,3,2] row_mask:0xf bank_mask:0xf
	v_min_u32_dpp v26, v0, v15 quad_perm:[1,0,3,2] row_mask:0xf bank_mask:0xf
; DEV void sort_lists(int lane, int& myi0, int& myi1, float& myg0, float& myg1) {
; #pragma unroll
;     for (int k = 2; k <= 128; k <<= 1) {
; #pragma unroll
;       for (int j = k >> 1; j >= 1; j >>= 1) {
;         if (j == 64) {
;           const bool sw_ = myi1 < myi0;
;           const int ti = sw_ ? myi1 : myi0, tj = sw_ ? myi0 : myi1; const float tg = sw_ ? myg1 : myg0, th = sw_ ? myg0 : myg1;
;           myi0 = ti; myi1 = tj; myg0 = tg; myg1 = th;
;         } else {
;           const bool lower = (lane & j) == 0;
;           {
;             const bool up = (k == 128) ? true : ((k == 64) ? true : ((lane & k) == 0));
;             const int oi = __shfl_xor(myi0, j); const float og = __shfl_xor(myg0, j);
;             const bool take = (lower == up) ? (oi < myi0) : (oi > myi0);
;             myi0 = take ? oi : myi0; myg0 = take ? og : myg0;
;           }
;           {
;             const bool up = (k == 128) ? true : ((k == 64) ? false : ((lane & k) == 0));
;             const int oi = __shfl_xor(myi1, j); const float og = __shfl_xor(myg1, j);
;             const bool take = (lower == up) ? (oi < myi1) : (oi > myi1);
;             myi1 = take ? oi : myi1; myg1 = take ? og : myg1;
;           }
;         }
;       }
;     }
; }
	v_max_u32_dpp v27, v0, v15 quad_perm:[1,0,3,2] row_mask:0xf bank_mask:0xf
	v_min_u32_dpp v28, v11, v4 quad_perm:[1,0,3,2] row_mask:0xf bank_mask:0xf
	v_max_u32_dpp v29, v11, v4 quad_perm:[1,0,3,2] row_mask:0xf bank_mask:0xf
	v_min_u32_dpp v30, v4, v11 quad_perm:[1,0,3,2] row_mask:0xf bank_mask:0xf
	v_max_u32_dpp v31, v4, v11 quad_perm:[1,0,3,2] row_mask:0xf bank_mask:0xf
	v_min_u32_dpp v32, v23, v2 quad_perm:[1,0,3,2] row_mask:0xf bank_mask:0xf
	v_max_u32_dpp v33, v23, v2 quad_perm:[1,0,3,2] row_mask:0xf bank_mask:0xf
	v_min_u32_dpp v34, v2, v23 quad_perm:[1,0,3,2] row_mask:0xf bank_mask:0xf
	v_max_u32_dpp v35, v2, v23 quad_perm:[1,0,3,2] row_mask:0xf bank_mask:0xf
	v_min_u32_dpp v36, v22, v19 quad_perm:[1,0,3,2] row_mask:0xf bank_mask:0xf
	v_max_u32_dpp v37, v22, v19 quad_perm:[1,0,3,2] row_mask:0xf bank_mask:0xf
	v_min_u32_dpp v38, v19, v22 quad_perm:[1,0,3,2] row_mask:0xf bank_mask:0xf
	v_max_u32_dpp v39, v19, v22 quad_perm:[1,0,3,2] row_mask:0xf bank_mask:0xf
	v_cndmask_b32_e64 v0, v25, v24, s[88:89]
	v_cndmask_b32_e64 v15, v27, v26, s[88:89]
	v_cndmask_b32_e64 v4, v29, v28, s[88:89]
	v_cndmask_b32_e64 v11, v31, v30, s[88:89]
	v_cndmask_b32_e64 v2, v33, v32, s[88:89]
	v_cndmask_b32_e64 v23, v35, v34, s[88:89]
	v_cndmask_b32_e64 v19, v37, v36, s[88:89]
	v_cndmask_b32_e64 v22, v39, v38, s[88:89]
	s_nop 1
	v_min_u32_dpp v24, v7, v20 quad_perm:[1,0,3,2] row_mask:0xf bank_mask:0xf
	v_max_u32_dpp v25, v7, v20 quad_perm:[1,0,3,2] row_mask:0xf bank_mask:0xf
	v_min_u32_dpp v26, v20, v7 quad_perm:[1,0,3,2] row_mask:0xf bank_mask:0xf
	v_max_u32_dpp v27, v20, v7 quad_perm:[1,0,3,2] row_mask:0xf bank_mask:0xf
	v_min_u32_dpp v28, v3, v5 quad_perm:[1,0,3,2] row_mask:0xf bank_mask:0xf
	v_max_u32_dpp v29, v3, v5 quad_perm:[1,0,3,2] row_mask:0xf bank_mask:0xf
	v_min_u32_dpp v30, v5, v3 quad_perm:[1,0,3,2] row_mask:0xf bank_mask:0xf
	v_max_u32_dpp v31, v5, v3 quad_perm:[1,0,3,2] row_mask:0xf bank_mask:0xf
	v_min_u32_dpp v32, v10, v12 quad_perm:[1,0,3,2] row_mask:0xf bank_mask:0xf
	v_max_u32_dpp v33, v10, v12 quad_perm:[1,0,3,2] row_mask:0xf bank_mask:0xf
	v_min_u32_dpp v34, v12, v10 quad_perm:[1,0,3,2] row_mask:0xf bank_mask:0xf
	v_max_u32_dpp v35, v12, v10 quad_perm:[1,0,3,2] row_mask:0xf bank_mask:0xf
	v_min_u32_dpp v36, v18, v13 quad_perm:[1,0,3,2] row_mask:0xf bank_mask:0xf
	v_max_u32_dpp v37, v18, v13 quad_perm:[1,0,3,2] row_mask:0xf bank_mask:0xf
	v_min_u32_dpp v38, v13, v18 quad_perm:[1,0,3,2] row_mask:0xf bank_mask:0xf
	v_max_u32_dpp v39, v13, v18 quad_perm:[1,0,3,2] row_mask:0xf bank_mask:0xf
	v_cndmask_b32_e64 v20, v25, v24, s[88:89]
	v_cndmask_b32_e64 v7, v27, v26, s[88:89]
	v_cndmask_b32_e64 v5, v29, v28, s[88:89]
	v_cndmask_b32_e64 v3, v31, v30, s[88:89]
	v_cndmask_b32_e64 v12, v33, v32, s[88:89]
	v_cndmask_b32_e64 v10, v35, v34, s[88:89]
	v_cndmask_b32_e64 v13, v37, v36, s[88:89]
	v_cndmask_b32_e64 v18, v39, v38, s[88:89]
	s_nop 1
	v_min_u32_e32 v16, v0, v18
	v_min_u32_e32 v17, v4, v10
	v_min_u32_e32 v1, v2, v3
	v_min_u32_e32 v9, v19, v7
	v_min_u32_e32 v8, v20, v22
	v_min_u32_e32 v6, v5, v23
	v_min_u32_e32 v21, v12, v11
	v_min_u32_e32 v14, v13, v15
	v_max_u32_e32 v18, v0, v18
	v_max_u32_e32 v10, v4, v10
	v_max_u32_e32 v3, v2, v3
	v_max_u32_e32 v7, v19, v7
	v_max_u32_e32 v22, v20, v22
	v_max_u32_e32 v23, v5, v23
	v_max_u32_e32 v11, v12, v11
	v_max_u32_e32 v15, v13, v15
	v_min_u32_e32 v0, v16, v8
	v_min_u32_e32 v4, v17, v6
	v_min_u32_e32 v2, v1, v21
	v_min_u32_e32 v19, v9, v14
	v_min_u32_e32 v20, v18, v22
	v_min_u32_e32 v5, v10, v23
	v_min_u32_e32 v12, v3, v11
	v_min_u32_e32 v13, v7, v15
	v_max_u32_e32 v8, v16, v8
	v_max_u32_e32 v6, v17, v6
	v_max_u32_e32 v21, v1, v21
	v_max_u32_e32 v14, v9, v14
	v_max_u32_e32 v22, v18, v22
	v_max_u32_e32 v23, v10, v23
	v_max_u32_e32 v11, v3, v11
	v_max_u32_e32 v15, v7, v15
	v_min_u32_e32 v16, v0, v2
	v_min_u32_e32 v17, v4, v19
	v_min_u32_e32 v1, v8, v21
	v_min_u32_e32 v9, v6, v14
	v_min_u32_e32 v18, v20, v12
	v_min_u32_e32 v10, v5, v13
	v_min_u32_e32 v3, v22, v11
	v_min_u32_e32 v7, v23, v15
	v_max_u32_e32 v2, v0, v2
	v_max_u32_e32 v19, v4, v19
	v_max_u32_e32 v21, v8, v21
	v_max_u32_e32 v14, v6, v14
	v_max_u32_e32 v12, v20, v12
	v_max_u32_e32 v13, v5, v13
	v_max_u32_e32 v11, v22, v11
	v_max_u32_e32 v15, v23, v15
	v_min_u32_e32 v0, v16, v17
	v_min_u32_e32 v4, v2, v19
	v_min_u32_e32 v8, v1, v9
	v_min_u32_e32 v6, v21, v14
	v_min_u32_e32 v20, v18, v10
	v_min_u32_e32 v5, v12, v13
	v_min_u32_e32 v22, v3, v7
	v_min_u32_e32 v23, v11, v15
	v_max_u32_e32 v17, v16, v17
	v_max_u32_e32 v19, v2, v19
	v_max_u32_e32 v9, v1, v9
	v_max_u32_e32 v14, v21, v14
	v_max_u32_e32 v10, v18, v10
	v_max_u32_e32 v13, v12, v13
	v_max_u32_e32 v7, v3, v7
	v_max_u32_e32 v15, v11, v15
	s_mov_b32 s88, 0x33333333
	s_mov_b32 s89, 0x33333333
	s_nop 1
	v_min_u32_dpp v24, v15, v0 quad_perm:[3,2,1,0] row_mask:0xf bank_mask:0xf
	v_max_u32_dpp v25, v15, v0 quad_perm:[3,2,1,0] row_mask:0xf bank_mask:0xf
	v_min_u32_dpp v26, v0, v15 quad_perm:[3,2,1,0] row_mask:0xf bank_mask:0xf
	v_max_u32_dpp v27, v0, v15 quad_perm:[3,2,1,0] row_mask:0xf bank_mask:0xf
	v_min_u32_dpp v28, v23, v17 quad_perm:[3,2,1,0] row_mask:0xf bank_mask:0xf
	v_max_u32_dpp v29, v23, v17 quad_perm:[3,2,1,0] row_mask:0xf bank_mask:0xf
	v_min_u32_dpp v30, v17, v23 quad_perm:[3,2,1,0] row_mask:0xf bank_mask:0xf
	v_max_u32_dpp v31, v17, v23 quad_perm:[3,2,1,0] row_mask:0xf bank_mask:0xf
	v_min_u32_dpp v32, v7, v4 quad_perm:[3,2,1,0] row_mask:0xf bank_mask:0xf
	v_max_u32_dpp v33, v7, v4 quad_perm:[3,2,1,0] row_mask:0xf bank_mask:0xf
	v_min_u32_dpp v34, v4, v7 quad_perm:[3,2,1,0] row_mask:0xf bank_mask:0xf
	v_max_u32_dpp v35, v4, v7 quad_perm:[3,2,1,0] row_mask:0xf bank_mask:0xf
; DEV void sort_lists(int lane, int& myi0, int& myi1, float& myg0, float& myg1) {
; #pragma unroll
;     for (int k = 2; k <= 128; k <<= 1) {
; #pragma unroll
;       for (int j = k >> 1; j >= 1; j >>= 1) {
;         if (j == 64) {
;           const bool sw_ = myi1 < myi0;
;           const int ti = sw_ ? myi1 : myi0, tj = sw_ ? myi0 : myi1; const float tg = sw_ ? myg1 : myg0, th = sw_ ? myg0 : myg1;
;           myi0 = ti; myi1 = tj; myg0 = tg; myg1 = th;
;         } else {
;           const bool lower = (lane & j) == 0;
;           {
;             const bool up = (k == 128) ? true : ((k == 64) ? true : ((lane & k) == 0));
;             const int oi = __shfl_xor(myi0, j); const float og = __shfl_xor(myg0, j);
;             const bool take = (lower == up) ? (oi < myi0) : (oi > myi0);
;             myi0 = take ? oi : myi0; myg0 = take ? og : myg0;
;           }
;           {
;             const bool up = (k == 128) ? true : ((k == 64) ? false : ((lane & k) == 0));
;             const int oi = __shfl_xor(myi1, j); const float og = __shfl_xor(myg1, j);
;             const bool take = (lower == up) ? (oi < myi1) : (oi > myi1);
;             myi1 = take ? oi : myi1; myg1 = take ? og : myg1;
;           }
;         }
;       }
;     }
; }
	v_min_u32_dpp v36, v22, v19 quad_perm:[3,2,1,0] row_mask:0xf bank_mask:0xf
	v_max_u32_dpp v37, v22, v19 quad_perm:[3,2,1,0] row_mask:0xf bank_mask:0xf
	v_min_u32_dpp v38, v19, v22 quad_perm:[3,2,1,0] row_mask:0xf bank_mask:0xf
	v_max_u32_dpp v39, v19, v22 quad_perm:[3,2,1,0] row_mask:0xf bank_mask:0xf
	v_cndmask_b32_e64 v0, v25, v24, s[88:89]
	v_cndmask_b32_e64 v15, v27, v26, s[88:89]
	v_cndmask_b32_e64 v17, v29, v28, s[88:89]
	v_cndmask_b32_e64 v23, v31, v30, s[88:89]
	v_cndmask_b32_e64 v4, v33, v32, s[88:89]
	v_cndmask_b32_e64 v7, v35, v34, s[88:89]
	v_cndmask_b32_e64 v19, v37, v36, s[88:89]
	v_cndmask_b32_e64 v22, v39, v38, s[88:89]
	s_nop 1
	v_min_u32_dpp v24, v13, v8 quad_perm:[3,2,1,0] row_mask:0xf bank_mask:0xf
	v_max_u32_dpp v25, v13, v8 quad_perm:[3,2,1,0] row_mask:0xf bank_mask:0xf
	v_min_u32_dpp v26, v8, v13 quad_perm:[3,2,1,0] row_mask:0xf bank_mask:0xf
	v_max_u32_dpp v27, v8, v13 quad_perm:[3,2,1,0] row_mask:0xf bank_mask:0xf
	v_min_u32_dpp v28, v5, v9 quad_perm:[3,2,1,0] row_mask:0xf bank_mask:0xf
	v_max_u32_dpp v29, v5, v9 quad_perm:[3,2,1,0] row_mask:0xf bank_mask:0xf
	v_min_u32_dpp v30, v9, v5 quad_perm:[3,2,1,0] row_mask:0xf bank_mask:0xf
	v_max_u32_dpp v31, v9, v5 quad_perm:[3,2,1,0] row_mask:0xf bank_mask:0xf
	v_min_u32_dpp v32, v10, v6 quad_perm:[3,2,1,0] row_mask:0xf bank_mask:0xf
	v_max_u32_dpp v33, v10, v6 quad_perm:[3,2,1,0] row_mask:0xf bank_mask:0xf
	v_min_u32_dpp v34, v6, v10 quad_perm:[3,2,1,0] row_mask:0xf bank_mask:0xf
	v_max_u32_dpp v35, v6, v10 quad_perm:[3,2,1,0] row_mask:0xf bank_mask:0xf
	v_min_u32_dpp v36, v20, v14 quad_perm:[3,2,1,0] row_mask:0xf bank_mask:0xf
	v_max_u32_dpp v37, v20, v14 quad_perm:[3,2,1,0] row_mask:0xf bank_mask:0xf
	v_min_u32_dpp v38, v14, v20 quad_perm:[3,2,1,0] row_mask:0xf bank_mask:0xf
	v_max_u32_dpp v39, v14, v20 quad_perm:[3,2,1,0] row_mask:0xf bank_mask:0xf
	v_cndmask_b32_e64 v8, v25, v24, s[88:89]
	v_cndmask_b32_e64 v13, v27, v26, s[88:89]
	v_cndmask_b32_e64 v9, v29, v28, s[88:89]
	v_cndmask_b32_e64 v5, v31, v30, s[88:89]
	v_cndmask_b32_e64 v6, v33, v32, s[88:89]
	v_cndmask_b32_e64 v10, v35, v34, s[88:89]
	v_cndmask_b32_e64 v14, v37, v36, s[88:89]
	v_cndmask_b32_e64 v20, v39, v38, s[88:89]
	s_nop 1
	s_mov_b32 s88, 0x55555555
	s_mov_b32 s89, 0x55555555
	s_nop 1
	v_min_u32_dpp v24, v0, v0 quad_perm:[1,0,3,2] row_mask:0xf bank_mask:0xf
	v_max_u32_dpp v25, v0, v0 quad_perm:[1,0,3,2] row_mask:0xf bank_mask:0xf
	v_min_u32_dpp v26, v17, v17 quad_perm:[1,0,3,2] row_mask:0xf bank_mask:0xf
	v_max_u32_dpp v27, v17, v17 quad_perm:[1,0,3,2] row_mask:0xf bank_mask:0xf
	v_min_u32_dpp v28, v4, v4 quad_perm:[1,0,3,2] row_mask:0xf bank_mask:0xf
	v_max_u32_dpp v29, v4, v4 quad_perm:[1,0,3,2] row_mask:0xf bank_mask:0xf
	v_min_u32_dpp v30, v19, v19 quad_perm:[1,0,3,2] row_mask:0xf bank_mask:0xf
	v_max_u32_dpp v31, v19, v19 quad_perm:[1,0,3,2] row_mask:0xf bank_mask:0xf
	v_min_u32_dpp v32, v8, v8 quad_perm:[1,0,3,2] row_mask:0xf bank_mask:0xf
	v_max_u32_dpp v33, v8, v8 quad_perm:[1,0,3,2] row_mask:0xf bank_mask:0xf
	v_min_u32_dpp v34, v9, v9 quad_perm:[1,0,3,2] row_mask:0xf bank_mask:0xf
	v_max_u32_dpp v35, v9, v9 quad_perm:[1,0,3,2] row_mask:0xf bank_mask:0xf
	v_min_u32_dpp v36, v6, v6 quad_perm:[1,0,3,2] row_mask:0xf bank_mask:0xf
	v_max_u32_dpp v37, v6, v6 quad_perm:[1,0,3,2] row_mask:0xf bank_mask:0xf
	v_min_u32_dpp v38, v14, v14 quad_perm:[1,0,3,2] row_mask:0xf bank_mask:0xf
	v_max_u32_dpp v39, v14, v14 quad_perm:[1,0,3,2] row_mask:0xf bank_mask:0xf
	v_cndmask_b32_e64 v0, v25, v24, s[88:89]
	v_cndmask_b32_e64 v17, v27, v26, s[88:89]
	v_cndmask_b32_e64 v4, v29, v28, s[88:89]
	v_cndmask_b32_e64 v19, v31, v30, s[88:89]
	v_cndmask_b32_e64 v8, v33, v32, s[88:89]
	v_cndmask_b32_e64 v9, v35, v34, s[88:89]
	v_cndmask_b32_e64 v6, v37, v36, s[88:89]
	v_cndmask_b32_e64 v14, v39, v38, s[88:89]
	s_nop 1
	v_min_u32_dpp v24, v20, v20 quad_perm:[1,0,3,2] row_mask:0xf bank_mask:0xf
	v_max_u32_dpp v25, v20, v20 quad_perm:[1,0,3,2] row_mask:0xf bank_mask:0xf
	v_min_u32_dpp v26, v10, v10 quad_perm:[1,0,3,2] row_mask:0xf bank_mask:0xf
	v_max_u32_dpp v27, v10, v10 quad_perm:[1,0,3,2] row_mask:0xf bank_mask:0xf
	v_min_u32_dpp v28, v5, v5 quad_perm:[1,0,3,2] row_mask:0xf bank_mask:0xf
	v_max_u32_dpp v29, v5, v5 quad_perm:[1,0,3,2] row_mask:0xf bank_mask:0xf
	v_min_u32_dpp v30, v13, v13 quad_perm:[1,0,3,2] row_mask:0xf bank_mask:0xf
	v_max_u32_dpp v31, v13, v13 quad_perm:[1,0,3,2] row_mask:0xf bank_mask:0xf
	v_min_u32_dpp v32, v22, v22 quad_perm:[1,0,3,2] row_mask:0xf bank_mask:0xf
	v_max_u32_dpp v33, v22, v22 quad_perm:[1,0,3,2] row_mask:0xf bank_mask:0xf
	v_min_u32_dpp v34, v7, v7 quad_perm:[1,0,3,2] row_mask:0xf bank_mask:0xf
	v_max_u32_dpp v35, v7, v7 quad_perm:[1,0,3,2] row_mask:0xf bank_mask:0xf
	v_min_u32_dpp v36, v23, v23 quad_perm:[1,0,3,2] row_mask:0xf bank_mask:0xf
	v_max_u32_dpp v37, v23, v23 quad_perm:[1,0,3,2] row_mask:0xf bank_mask:0xf
	v_min_u32_dpp v38, v15, v15 quad_perm:[1,0,3,2] row_mask:0xf bank_mask:0xf
	v_max_u32_dpp v39, v15, v15 quad_perm:[1,0,3,2] row_mask:0xf bank_mask:0xf
	v_cndmask_b32_e64 v20, v25, v24, s[88:89]
	v_cndmask_b32_e64 v10, v27, v26, s[88:89]
	v_cndmask_b32_e64 v5, v29, v28, s[88:89]
	v_cndmask_b32_e64 v13, v31, v30, s[88:89]
	v_cndmask_b32_e64 v22, v33, v32, s[88:89]
	v_cndmask_b32_e64 v7, v35, v34, s[88:89]
	v_cndmask_b32_e64 v23, v37, v36, s[88:89]
	v_cndmask_b32_e64 v15, v39, v38, s[88:89]
	s_nop 1
	v_min_u32_e32 v16, v0, v20
	v_min_u32_e32 v2, v17, v10
	v_min_u32_e32 v1, v4, v5
	v_min_u32_e32 v21, v19, v13
	v_min_u32_e32 v18, v8, v22
	v_min_u32_e32 v12, v9, v7
	v_min_u32_e32 v3, v6, v23
	v_min_u32_e32 v11, v14, v15
	v_max_u32_e32 v20, v0, v20
	v_max_u32_e32 v10, v17, v10
; DEV void sort_lists(int lane, int& myi0, int& myi1, float& myg0, float& myg1) {
; #pragma unroll
;     for (int k = 2; k <= 128; k <<= 1) {
; #pragma unroll
;       for (int j = k >> 1; j >= 1; j >>= 1) {
;         if (j == 64) {
;           const bool sw_ = myi1 < myi0;
;           const int ti = sw_ ? myi1 : myi0, tj = sw_ ? myi0 : myi1; const float tg = sw_ ? myg1 : myg0, th = sw_ ? myg0 : myg1;
;           myi0 = ti; myi1 = tj; myg0 = tg; myg1 = th;
;         } else {
;           const bool lower = (lane & j) == 0;
;           {
;             const bool up = (k == 128) ? true : ((k == 64) ? true : ((lane & k) == 0));
;             const int oi = __shfl_xor(myi0, j); const float og = __shfl_xor(myg0, j);
;             const bool take = (lower == up) ? (oi < myi0) : (oi > myi0);
;             myi0 = take ? oi : myi0; myg0 = take ? og : myg0;
;           }
;           {
;             const bool up = (k == 128) ? true : ((k == 64) ? false : ((lane & k) == 0));
;             const int oi = __shfl_xor(myi1, j); const float og = __shfl_xor(myg1, j);
;             const bool take = (lower == up) ? (oi < myi1) : (oi > myi1);
;             myi1 = take ? oi : myi1; myg1 = take ? og : myg1;
;           }
;         }
;       }
;     }
; }
	v_max_u32_e32 v5, v4, v5
	v_max_u32_e32 v13, v19, v13
	v_max_u32_e32 v22, v8, v22
	v_max_u32_e32 v7, v9, v7
	v_max_u32_e32 v23, v6, v23
	v_max_u32_e32 v15, v14, v15
	v_min_u32_e32 v0, v16, v18
	v_min_u32_e32 v17, v2, v12
	v_min_u32_e32 v4, v1, v3
	v_min_u32_e32 v19, v21, v11
	v_min_u32_e32 v8, v20, v22
	v_min_u32_e32 v9, v10, v7
	v_min_u32_e32 v6, v5, v23
	v_min_u32_e32 v14, v13, v15
	v_max_u32_e32 v18, v16, v18
	v_max_u32_e32 v12, v2, v12
	v_max_u32_e32 v3, v1, v3
	v_max_u32_e32 v11, v21, v11
	v_max_u32_e32 v22, v20, v22
	v_max_u32_e32 v7, v10, v7
	v_max_u32_e32 v23, v5, v23
	v_max_u32_e32 v15, v13, v15
	v_min_u32_e32 v16, v0, v4
	v_min_u32_e32 v2, v17, v19
	v_min_u32_e32 v1, v18, v3
	v_min_u32_e32 v21, v12, v11
	v_min_u32_e32 v20, v8, v6
	v_min_u32_e32 v10, v9, v14
	v_min_u32_e32 v5, v22, v23
	v_min_u32_e32 v13, v7, v15
	v_max_u32_e32 v4, v0, v4
	v_max_u32_e32 v19, v17, v19
	v_max_u32_e32 v3, v18, v3
	v_max_u32_e32 v11, v12, v11
	v_max_u32_e32 v6, v8, v6
	v_max_u32_e32 v14, v9, v14
	v_max_u32_e32 v23, v22, v23
	v_max_u32_e32 v15, v7, v15
	v_min_u32_e32 v0, v16, v2
	v_min_u32_e32 v17, v4, v19
	v_min_u32_e32 v18, v1, v21
	v_min_u32_e32 v12, v3, v11
	v_min_u32_e32 v8, v20, v10
	v_min_u32_e32 v9, v6, v14
	v_min_u32_e32 v22, v5, v13
	v_min_u32_e32 v7, v23, v15
	v_max_u32_e32 v2, v16, v2
	v_max_u32_e32 v19, v4, v19
	v_max_u32_e32 v21, v1, v21
	v_max_u32_e32 v11, v3, v11
	v_max_u32_e32 v10, v20, v10
	v_max_u32_e32 v14, v6, v14
	v_max_u32_e32 v13, v5, v13
	v_max_u32_e32 v15, v23, v15
	s_mov_b32 s88, 0xf0f0f0f
	s_mov_b32 s89, 0xf0f0f0f
	s_nop 1
	v_min_u32_dpp v24, v15, v0 row_half_mirror row_mask:0xf bank_mask:0xf
	v_max_u32_dpp v25, v15, v0 row_half_mirror row_mask:0xf bank_mask:0xf
	v_min_u32_dpp v26, v0, v15 row_half_mirror row_mask:0xf bank_mask:0xf
	v_max_u32_dpp v27, v0, v15 row_half_mirror row_mask:0xf bank_mask:0xf
	v_min_u32_dpp v28, v7, v2 row_half_mirror row_mask:0xf bank_mask:0xf
	v_max_u32_dpp v29, v7, v2 row_half_mirror row_mask:0xf bank_mask:0xf
	v_min_u32_dpp v30, v2, v7 row_half_mirror row_mask:0xf bank_mask:0xf
	v_max_u32_dpp v31, v2, v7 row_half_mirror row_mask:0xf bank_mask:0xf
	v_min_u32_dpp v32, v13, v17 row_half_mirror row_mask:0xf bank_mask:0xf
	v_max_u32_dpp v33, v13, v17 row_half_mirror row_mask:0xf bank_mask:0xf
	v_min_u32_dpp v34, v17, v13 row_half_mirror row_mask:0xf bank_mask:0xf
	v_max_u32_dpp v35, v17, v13 row_half_mirror row_mask:0xf bank_mask:0xf
	v_min_u32_dpp v36, v22, v19 row_half_mirror row_mask:0xf bank_mask:0xf
	v_max_u32_dpp v37, v22, v19 row_half_mirror row_mask:0xf bank_mask:0xf
	v_min_u32_dpp v38, v19, v22 row_half_mirror row_mask:0xf bank_mask:0xf
	v_max_u32_dpp v39, v19, v22 row_half_mirror row_mask:0xf bank_mask:0xf
	v_cndmask_b32_e64 v0, v25, v24, s[88:89]
	v_cndmask_b32_e64 v15, v27, v26, s[88:89]
	v_cndmask_b32_e64 v2, v29, v28, s[88:89]
	v_cndmask_b32_e64 v7, v31, v30, s[88:89]
	v_cndmask_b32_e64 v17, v33, v32, s[88:89]
	v_cndmask_b32_e64 v13, v35, v34, s[88:89]
	v_cndmask_b32_e64 v19, v37, v36, s[88:89]
	v_cndmask_b32_e64 v22, v39, v38, s[88:89]
	s_nop 1
	v_min_u32_dpp v24, v14, v18 row_half_mirror row_mask:0xf bank_mask:0xf
	v_max_u32_dpp v25, v14, v18 row_half_mirror row_mask:0xf bank_mask:0xf
	v_min_u32_dpp v26, v18, v14 row_half_mirror row_mask:0xf bank_mask:0xf
	v_max_u32_dpp v27, v18, v14 row_half_mirror row_mask:0xf bank_mask:0xf
	v_min_u32_dpp v28, v9, v21 row_half_mirror row_mask:0xf bank_mask:0xf
	v_max_u32_dpp v29, v9, v21 row_half_mirror row_mask:0xf bank_mask:0xf
	v_min_u32_dpp v30, v21, v9 row_half_mirror row_mask:0xf bank_mask:0xf
	v_max_u32_dpp v31, v21, v9 row_half_mirror row_mask:0xf bank_mask:0xf
	v_min_u32_dpp v32, v10, v12 row_half_mirror row_mask:0xf bank_mask:0xf
	v_max_u32_dpp v33, v10, v12 row_half_mirror row_mask:0xf bank_mask:0xf
	v_min_u32_dpp v34, v12, v10 row_half_mirror row_mask:0xf bank_mask:0xf
	v_max_u32_dpp v35, v12, v10 row_half_mirror row_mask:0xf bank_mask:0xf
	v_min_u32_dpp v36, v8, v11 row_half_mirror row_mask:0xf bank_mask:0xf
	v_max_u32_dpp v37, v8, v11 row_half_mirror row_mask:0xf bank_mask:0xf
	v_min_u32_dpp v38, v11, v8 row_half_mirror row_mask:0xf bank_mask:0xf
	v_max_u32_dpp v39, v11, v8 row_half_mirror row_mask:0xf bank_mask:0xf
	v_cndmask_b32_e64 v18, v25, v24, s[88:89]
	v_cndmask_b32_e64 v14, v27, v26, s[88:89]
	v_cndmask_b32_e64 v21, v29, v28, s[88:89]
	v_cndmask_b32_e64 v9, v31, v30, s[88:89]
	v_cndmask_b32_e64 v12, v33, v32, s[88:89]
	v_cndmask_b32_e64 v10, v35, v34, s[88:89]
	v_cndmask_b32_e64 v11, v37, v36, s[88:89]
	v_cndmask_b32_e64 v8, v39, v38, s[88:89]
	s_nop 1
	s_mov_b32 s88, 0x33333333
	s_mov_b32 s89, 0x33333333
	s_nop 1
	v_min_u32_dpp v24, v0, v0 quad_perm:[2,3,0,1] row_mask:0xf bank_mask:0xf
	v_max_u32_dpp v25, v0, v0 quad_perm:[2,3,0,1] row_mask:0xf bank_mask:0xf
	v_min_u32_dpp v26, v2, v2 quad_perm:[2,3,0,1] row_mask:0xf bank_mask:0xf
	v_max_u32_dpp v27, v2, v2 quad_perm:[2,3,0,1] row_mask:0xf bank_mask:0xf
	v_min_u32_dpp v28, v17, v17 quad_perm:[2,3,0,1] row_mask:0xf bank_mask:0xf
	v_max_u32_dpp v29, v17, v17 quad_perm:[2,3,0,1] row_mask:0xf bank_mask:0xf
	v_min_u32_dpp v30, v19, v19 quad_perm:[2,3,0,1] row_mask:0xf bank_mask:0xf
	v_max_u32_dpp v31, v19, v19 quad_perm:[2,3,0,1] row_mask:0xf bank_mask:0xf
	v_min_u32_dpp v32, v18, v18 quad_perm:[2,3,0,1] row_mask:0xf bank_mask:0xf
	v_max_u32_dpp v33, v18, v18 quad_perm:[2,3,0,1] row_mask:0xf bank_mask:0xf
	v_min_u32_dpp v34, v21, v21 quad_perm:[2,3,0,1] row_mask:0xf bank_mask:0xf
	v_max_u32_dpp v35, v21, v21 quad_perm:[2,3,0,1] row_mask:0xf bank_mask:0xf
	v_min_u32_dpp v36, v12, v12 quad_perm:[2,3,0,1] row_mask:0xf bank_mask:0xf
	v_max_u32_dpp v37, v12, v12 quad_perm:[2,3,0,1] row_mask:0xf bank_mask:0xf
; DEV void sort_lists(int lane, int& myi0, int& myi1, float& myg0, float& myg1) {
; #pragma unroll
;     for (int k = 2; k <= 128; k <<= 1) {
; #pragma unroll
;       for (int j = k >> 1; j >= 1; j >>= 1) {
;         if (j == 64) {
;           const bool sw_ = myi1 < myi0;
;           const int ti = sw_ ? myi1 : myi0, tj = sw_ ? myi0 : myi1; const float tg = sw_ ? myg1 : myg0, th = sw_ ? myg0 : myg1;
;           myi0 = ti; myi1 = tj; myg0 = tg; myg1 = th;
;         } else {
;           const bool lower = (lane & j) == 0;
;           {
;             const bool up = (k == 128) ? true : ((k == 64) ? true : ((lane & k) == 0));
;             const int oi = __shfl_xor(myi0, j); const float og = __shfl_xor(myg0, j);
;             const bool take = (lower == up) ? (oi < myi0) : (oi > myi0);
;             myi0 = take ? oi : myi0; myg0 = take ? og : myg0;
;           }
;           {
;             const bool up = (k == 128) ? true : ((k == 64) ? false : ((lane & k) == 0));
;             const int oi = __shfl_xor(myi1, j); const float og = __shfl_xor(myg1, j);
;             const bool take = (lower == up) ? (oi < myi1) : (oi > myi1);
;             myi1 = take ? oi : myi1; myg1 = take ? og : myg1;
;           }
;         }
;       }
;     }
; }
	v_min_u32_dpp v38, v11, v11 quad_perm:[2,3,0,1] row_mask:0xf bank_mask:0xf
	v_max_u32_dpp v39, v11, v11 quad_perm:[2,3,0,1] row_mask:0xf bank_mask:0xf
	v_cndmask_b32_e64 v0, v25, v24, s[88:89]
	v_cndmask_b32_e64 v2, v27, v26, s[88:89]
	v_cndmask_b32_e64 v17, v29, v28, s[88:89]
	v_cndmask_b32_e64 v19, v31, v30, s[88:89]
	v_cndmask_b32_e64 v18, v33, v32, s[88:89]
	v_cndmask_b32_e64 v21, v35, v34, s[88:89]
	v_cndmask_b32_e64 v12, v37, v36, s[88:89]
	v_cndmask_b32_e64 v11, v39, v38, s[88:89]
	s_nop 1
	v_min_u32_dpp v24, v8, v8 quad_perm:[2,3,0,1] row_mask:0xf bank_mask:0xf
	v_max_u32_dpp v25, v8, v8 quad_perm:[2,3,0,1] row_mask:0xf bank_mask:0xf
	v_min_u32_dpp v26, v10, v10 quad_perm:[2,3,0,1] row_mask:0xf bank_mask:0xf
	v_max_u32_dpp v27, v10, v10 quad_perm:[2,3,0,1] row_mask:0xf bank_mask:0xf
	v_min_u32_dpp v28, v9, v9 quad_perm:[2,3,0,1] row_mask:0xf bank_mask:0xf
	v_max_u32_dpp v29, v9, v9 quad_perm:[2,3,0,1] row_mask:0xf bank_mask:0xf
	v_min_u32_dpp v30, v14, v14 quad_perm:[2,3,0,1] row_mask:0xf bank_mask:0xf
	v_max_u32_dpp v31, v14, v14 quad_perm:[2,3,0,1] row_mask:0xf bank_mask:0xf
	v_min_u32_dpp v32, v22, v22 quad_perm:[2,3,0,1] row_mask:0xf bank_mask:0xf
	v_max_u32_dpp v33, v22, v22 quad_perm:[2,3,0,1] row_mask:0xf bank_mask:0xf
	v_min_u32_dpp v34, v13, v13 quad_perm:[2,3,0,1] row_mask:0xf bank_mask:0xf
	v_max_u32_dpp v35, v13, v13 quad_perm:[2,3,0,1] row_mask:0xf bank_mask:0xf
	v_min_u32_dpp v36, v7, v7 quad_perm:[2,3,0,1] row_mask:0xf bank_mask:0xf
	v_max_u32_dpp v37, v7, v7 quad_perm:[2,3,0,1] row_mask:0xf bank_mask:0xf
	v_min_u32_dpp v38, v15, v15 quad_perm:[2,3,0,1] row_mask:0xf bank_mask:0xf
	v_max_u32_dpp v39, v15, v15 quad_perm:[2,3,0,1] row_mask:0xf bank_mask:0xf
	v_cndmask_b32_e64 v8, v25, v24, s[88:89]
	v_cndmask_b32_e64 v10, v27, v26, s[88:89]
	v_cndmask_b32_e64 v9, v29, v28, s[88:89]
	v_cndmask_b32_e64 v14, v31, v30, s[88:89]
	v_cndmask_b32_e64 v22, v33, v32, s[88:89]
	v_cndmask_b32_e64 v13, v35, v34, s[88:89]
	v_cndmask_b32_e64 v7, v37, v36, s[88:89]
	v_cndmask_b32_e64 v15, v39, v38, s[88:89]
	s_nop 1
	s_mov_b32 s88, 0x55555555
	s_mov_b32 s89, 0x55555555
	s_nop 1
	v_min_u32_dpp v24, v0, v0 quad_perm:[1,0,3,2] row_mask:0xf bank_mask:0xf
	v_max_u32_dpp v25, v0, v0 quad_perm:[1,0,3,2] row_mask:0xf bank_mask:0xf
	v_min_u32_dpp v26, v2, v2 quad_perm:[1,0,3,2] row_mask:0xf bank_mask:0xf
	v_max_u32_dpp v27, v2, v2 quad_perm:[1,0,3,2] row_mask:0xf bank_mask:0xf
	v_min_u32_dpp v28, v17, v17 quad_perm:[1,0,3,2] row_mask:0xf bank_mask:0xf
	v_max_u32_dpp v29, v17, v17 quad_perm:[1,0,3,2] row_mask:0xf bank_mask:0xf
	v_min_u32_dpp v30, v19, v19 quad_perm:[1,0,3,2] row_mask:0xf bank_mask:0xf
	v_max_u32_dpp v31, v19, v19 quad_perm:[1,0,3,2] row_mask:0xf bank_mask:0xf
	v_min_u32_dpp v32, v18, v18 quad_perm:[1,0,3,2] row_mask:0xf bank_mask:0xf
	v_max_u32_dpp v33, v18, v18 quad_perm:[1,0,3,2] row_mask:0xf bank_mask:0xf
	v_min_u32_dpp v34, v21, v21 quad_perm:[1,0,3,2] row_mask:0xf bank_mask:0xf
	v_max_u32_dpp v35, v21, v21 quad_perm:[1,0,3,2] row_mask:0xf bank_mask:0xf
	v_min_u32_dpp v36, v12, v12 quad_perm:[1,0,3,2] row_mask:0xf bank_mask:0xf
	v_max_u32_dpp v37, v12, v12 quad_perm:[1,0,3,2] row_mask:0xf bank_mask:0xf
	v_min_u32_dpp v38, v11, v11 quad_perm:[1,0,3,2] row_mask:0xf bank_mask:0xf
	v_max_u32_dpp v39, v11, v11 quad_perm:[1,0,3,2] row_mask:0xf bank_mask:0xf
	v_cndmask_b32_e64 v0, v25, v24, s[88:89]
	v_cndmask_b32_e64 v2, v27, v26, s[88:89]
	v_cndmask_b32_e64 v17, v29, v28, s[88:89]
	v_cndmask_b32_e64 v19, v31, v30, s[88:89]
	v_cndmask_b32_e64 v18, v33, v32, s[88:89]
	v_cndmask_b32_e64 v21, v35, v34, s[88:89]
	v_cndmask_b32_e64 v12, v37, v36, s[88:89]
	v_cndmask_b32_e64 v11, v39, v38, s[88:89]
	s_nop 1
	v_min_u32_dpp v24, v8, v8 quad_perm:[1,0,3,2] row_mask:0xf bank_mask:0xf
	v_max_u32_dpp v25, v8, v8 quad_perm:[1,0,3,2] row_mask:0xf bank_mask:0xf
	v_min_u32_dpp v26, v10, v10 quad_perm:[1,0,3,2] row_mask:0xf bank_mask:0xf
	v_max_u32_dpp v27, v10, v10 quad_perm:[1,0,3,2] row_mask:0xf bank_mask:0xf
	v_min_u32_dpp v28, v9, v9 quad_perm:[1,0,3,2] row_mask:0xf bank_mask:0xf
	v_max_u32_dpp v29, v9, v9 quad_perm:[1,0,3,2] row_mask:0xf bank_mask:0xf
	v_min_u32_dpp v30, v14, v14 quad_perm:[1,0,3,2] row_mask:0xf bank_mask:0xf
	v_max_u32_dpp v31, v14, v14 quad_perm:[1,0,3,2] row_mask:0xf bank_mask:0xf
	v_min_u32_dpp v32, v22, v22 quad_perm:[1,0,3,2] row_mask:0xf bank_mask:0xf
	v_max_u32_dpp v33, v22, v22 quad_perm:[1,0,3,2] row_mask:0xf bank_mask:0xf
	v_min_u32_dpp v34, v13, v13 quad_perm:[1,0,3,2] row_mask:0xf bank_mask:0xf
	v_max_u32_dpp v35, v13, v13 quad_perm:[1,0,3,2] row_mask:0xf bank_mask:0xf
	v_min_u32_dpp v36, v7, v7 quad_perm:[1,0,3,2] row_mask:0xf bank_mask:0xf
	v_max_u32_dpp v37, v7, v7 quad_perm:[1,0,3,2] row_mask:0xf bank_mask:0xf
	v_min_u32_dpp v38, v15, v15 quad_perm:[1,0,3,2] row_mask:0xf bank_mask:0xf
	v_max_u32_dpp v39, v15, v15 quad_perm:[1,0,3,2] row_mask:0xf bank_mask:0xf
	v_cndmask_b32_e64 v8, v25, v24, s[88:89]
	v_cndmask_b32_e64 v10, v27, v26, s[88:89]
	v_cndmask_b32_e64 v9, v29, v28, s[88:89]
	v_cndmask_b32_e64 v14, v31, v30, s[88:89]
; #define PG_ISSUE(BUF, TAB, e0_) do { const int isrc_ = ((e0_) < 64) ? myi0 : myi1; \
;       _Pragma("unroll") for (int e = 0; e < 8; ++e) { const int idx_ = __builtin_amdgcn_readlane(isrc_, ((e0_) + e) & 63); \
;         BUF[e] = *(const u32x4*)((TAB) + (size_t)idx_ * 1024 + lane * 16); } } while (0)
; DEV void sort_lists(int lane, int& myi0, int& myi1, float& myg0, float& myg1) {
; #pragma unroll
;     for (int k = 2; k <= 128; k <<= 1) {
; #pragma unroll
;       for (int j = k >> 1; j >= 1; j >>= 1) {
;         if (j == 64) {
;           const bool sw_ = myi1 < myi0;
;           const int ti = sw_ ? myi1 : myi0, tj = sw_ ? myi0 : myi1; const float tg = sw_ ? myg1 : myg0, th = sw_ ? myg0 : myg1;
;           myi0 = ti; myi1 = tj; myg0 = tg; myg1 = th;
;         } else {
;           const bool lower = (lane & j) == 0;
;           {
;             const bool up = (k == 128) ? true : ((k == 64) ? true : ((lane & k) == 0));
;             const int oi = __shfl_xor(myi0, j); const float og = __shfl_xor(myg0, j);
;             const bool take = (lower == up) ? (oi < myi0) : (oi > myi0);
;             myi0 = take ? oi : myi0; myg0 = take ? og : myg0;
;           }
;           {
;             const bool up = (k == 128) ? true : ((k == 64) ? false : ((lane & k) == 0));
;             const int oi = __shfl_xor(myi1, j); const float og = __shfl_xor(myg1, j);
;             const bool take = (lower == up) ? (oi < myi1) : (oi > myi1);
;             myi1 = take ? oi : myi1; myg1 = take ? og : myg1;
;           }
;         }
;       }
;     }
; }
; DEV void peer_gather(const Params& P, int l, int m0, const int* idxs, const float* gs) {
;     ...
;     PG_ISSUE(b0, U, 0);
; #pragma nounroll
;     for (int e0 = 0; e0 < 128; e0 += 16) {
;       PG_ISSUE(b1, U, e0 + 8);
	v_cndmask_b32_e64 v22, v33, v32, s[88:89]
	v_cndmask_b32_e64 v13, v35, v34, s[88:89]
	v_cndmask_b32_e64 v7, v37, v36, s[88:89]
	v_cndmask_b32_e64 v15, v39, v38, s[88:89]
	s_nop 1
	v_min_u32_e32 v16, v0, v8
	v_min_u32_e32 v4, v2, v10
	v_min_u32_e32 v1, v17, v9
	v_min_u32_e32 v3, v19, v14
	v_min_u32_e32 v20, v18, v22
	v_min_u32_e32 v6, v21, v13
	v_min_u32_e32 v5, v12, v7
	v_min_u32_e32 v23, v11, v15
	v_max_u32_e32 v8, v0, v8
	v_max_u32_e32 v10, v2, v10
	v_max_u32_e32 v9, v17, v9
	v_max_u32_e32 v14, v19, v14
	v_max_u32_e32 v22, v18, v22
	v_max_u32_e32 v13, v21, v13
	v_max_u32_e32 v7, v12, v7
	v_max_u32_e32 v15, v11, v15
	v_min_u32_e32 v0, v16, v20
	v_min_u32_e32 v2, v4, v6
	v_min_u32_e32 v17, v1, v5
	v_min_u32_e32 v19, v3, v23
	v_min_u32_e32 v18, v8, v22
	v_min_u32_e32 v21, v10, v13
	v_min_u32_e32 v12, v9, v7
	v_min_u32_e32 v11, v14, v15
	v_max_u32_e32 v20, v16, v20
	v_max_u32_e32 v6, v4, v6
	v_max_u32_e32 v5, v1, v5
	v_max_u32_e32 v23, v3, v23
	v_max_u32_e32 v22, v8, v22
	v_max_u32_e32 v13, v10, v13
	v_max_u32_e32 v7, v9, v7
	v_max_u32_e32 v15, v14, v15
	v_min_u32_e32 v16, v0, v17
	v_min_u32_e32 v4, v2, v19
	v_min_u32_e32 v1, v20, v5
	v_min_u32_e32 v3, v6, v23
	v_min_u32_e32 v8, v18, v12
	v_min_u32_e32 v10, v21, v11
	v_min_u32_e32 v9, v22, v7
	v_min_u32_e32 v14, v13, v15
	v_max_u32_e32 v17, v0, v17
	v_max_u32_e32 v19, v2, v19
	v_max_u32_e32 v5, v20, v5
	v_max_u32_e32 v23, v6, v23
	v_max_u32_e32 v12, v18, v12
	v_max_u32_e32 v11, v21, v11
	v_max_u32_e32 v7, v22, v7
	v_max_u32_e32 v15, v13, v15
	v_min_u32_e32 v0, v16, v4
	v_min_u32_e32 v2, v17, v19
	v_min_u32_e32 v20, v1, v3
	v_min_u32_e32 v6, v5, v23
	v_min_u32_e32 v18, v8, v10
	v_min_u32_e32 v21, v12, v11
	v_min_u32_e32 v22, v9, v14
	v_min_u32_e32 v13, v7, v15
	v_max_u32_e32 v4, v16, v4
	v_max_u32_e32 v19, v17, v19
	v_max_u32_e32 v3, v1, v3
	v_max_u32_e32 v23, v5, v23
	v_max_u32_e32 v10, v8, v10
	v_max_u32_e32 v11, v12, v11
	v_max_u32_e32 v14, v9, v14
	v_max_u32_e32 v15, v7, v15
	ds_write_b32 v41, v0 offset:4096
	ds_write_b32 v41, v4 offset:4160
	ds_write_b32 v41, v2 offset:4224
	ds_write_b32 v41, v19 offset:4288
	ds_write_b32 v41, v20 offset:4352
	ds_write_b32 v41, v3 offset:4416
	ds_write_b32 v41, v6 offset:4480
	ds_write_b32 v41, v23 offset:4544
	ds_write_b32 v41, v18 offset:4100
	ds_write_b32 v41, v10 offset:4164
	ds_write_b32 v41, v21 offset:4228
	ds_write_b32 v41, v11 offset:4292
	ds_write_b32 v41, v22 offset:4356
	ds_write_b32 v41, v14 offset:4420
	ds_write_b32 v41, v13 offset:4484
	ds_write_b32 v41, v15 offset:4548
	s_waitcnt lgkmcnt(0)
	v_readfirstlane_b32 s82, v122
	v_readfirstlane_b32 s83, v123
	s_nop 4
	v_readfirstlane_b32 s80, v126
	v_readfirstlane_b32 s81, v127
	s_nop 4
	s_mov_b32 s2, 0xffffff80
	s_mov_b32 s86, 0xcccccccc
	s_mov_b32 s87, 0xcccccccc
	s_mov_b32 s88, 0xaaaaaaaa
	s_mov_b32 s89, 0xaaaaaaaa
	s_mov_b32 s90, 0xf0f0f0f0
	s_mov_b32 s91, 0xf0f0f0f0
	s_lshl_b32 vcc_lo, s3, 11
	s_add_u32 s82, s82, vcc_lo
	s_addc_u32 s83, s83, 0
	v_lshl_add_u32 v246, v237, 4, s101
	v_lshrrev_b32_e32 v247, 2, v235
	v_add_u32_e32 v247, v247, v246
	v_add_u32_e32 v247, 0x10000, v247
	s_mov_b32 s100, 0
	s_mov_b32 s98, 0
	s_mov_b32 s99, 0
	s_lshl3_add_u32 vcc_lo, s98, s99
	v_lshl_add_u32 v119, vcc_lo, 8, v236
	global_load_dwordx4 v[80:83], v119, s[82:83]
	global_load_dwordx4 v[84:87], v119, s[82:83] offset:16
	v_lshl_add_u32 v116, s98, 9, v246
	ds_read_b128 v[112:115], v116
	ds_read_b128 v[138:141], v116 offset:16
	ds_read_b128 v[250:253], v116 offset:32
	ds_read_b128 v[242:245], v116 offset:48
	v_lshl_or_b32 v240, s99, 21, v235
	s_waitcnt lgkmcnt(0)
	v_and_or_b32 v112, v112, s2, v240
	v_and_or_b32 v113, v113, s2, v240
	global_load_dwordx4 v[0:3], v112, s[80:81]
	global_load_dwordx4 v[4:7], v113, s[80:81]
	v_and_or_b32 v114, v114, s2, v240
	v_and_or_b32 v115, v115, s2, v240
	global_load_dwordx4 v[8:11], v114, s[80:81]
	global_load_dwordx4 v[12:15], v115, s[80:81]
	v_and_or_b32 v138, v138, s2, v240
	v_and_or_b32 v139, v139, s2, v240
	global_load_dwordx4 v[16:19], v138, s[80:81]
	global_load_dwordx4 v[20:23], v139, s[80:81]
	v_and_or_b32 v140, v140, s2, v240
	v_and_or_b32 v141, v141, s2, v240
	global_load_dwordx4 v[24:27], v140, s[80:81]
	global_load_dwordx4 v[28:31], v141, s[80:81]
	v_and_or_b32 v250, v250, s2, v240
	v_and_or_b32 v251, v251, s2, v240
	global_load_dwordx4 v[32:35], v250, s[80:81]
	global_load_dwordx4 v[36:39], v251, s[80:81]
	v_and_or_b32 v252, v252, s2, v240
	v_and_or_b32 v253, v253, s2, v240
	global_load_dwordx4 v[40:43], v252, s[80:81]
	global_load_dwordx4 v[44:47], v253, s[80:81]
	v_and_or_b32 v242, v242, s2, v240
	v_and_or_b32 v243, v243, s2, v240
	global_load_dwordx4 v[48:51], v242, s[80:81]
	global_load_dwordx4 v[52:55], v243, s[80:81]
	v_and_or_b32 v244, v244, s2, v240
	v_and_or_b32 v245, v245, s2, v240
	global_load_dwordx4 v[56:59], v244, s[80:81]
	global_load_dwordx4 v[60:63], v245, s[80:81]
	s_mov_b32 s92, 1
	v_lshl_add_u32 v116, s92, 9, v246
	ds_read_b128 v[112:115], v116
	ds_read_b128 v[138:141], v116 offset:16
	ds_read_b128 v[250:253], v116 offset:32
	ds_read_b128 v[242:245], v116 offset:48
